# NORM0 / POST row passes with three x rows prefetched ahead (4 register buffers)
# baseline (speedup 1.0000x reference)
; DI int TIDX() { int t = threadIdx.x; asm volatile("" : "+v"(t)); return t; }
; DI int BIDX() { int b = blockIdx.x; asm volatile("" : "+s"(b)); return b; }
; DI void rows_norm_mod(const P& p, const float* xlat, const float* xctx, int l, const float* gain, int sh_idx, int sc_idx,
;                       h16* dst, int nrows) {
;   const int lane = TIDX() & 63;
;   const int gw = BIDX() * 4 + (TIDX() >> 6), nw = gridDim.x * 4;
;   const float* mod = (const float*)(p.ws + OFF_MOD);
;   for (int row = gw; row < nrows; row += nw) {
;     const float* xr = row < TL ? xlat + (size_t)row * 1024 : xctx + (size_t)(row - TL) * 1024;
;     const int mrow = row < TL ? (row >> 12) : 8;
;     const float* mr = mod + ((size_t)l * 9 + mrow) * 6144;
;     f32x4 v[4];
;     float ss = 0.f;
; #pragma unroll
;     for (int i = 0; i < 4; ++i) {
;       v[i] = *(const f32x4*)(xr + lane * 4 + 256 * i);
;       ss += v[i].x * v[i].x + v[i].y * v[i].y + v[i].z * v[i].z + v[i].w * v[i].w;
;     }
;     ss = wave_sum(ss);
;     const float rstd = rsqrtf(ss * (1.f / 1024.f) + EPS);
; #pragma unroll
;     for (int i = 0; i < 4; ++i) {
;       const int c = lane * 4 + 256 * i;
;       f32x4 g = *(const f32x4*)(gain + c), sc = *(const f32x4*)(mr + sc_idx * 1024 + c), sh = *(const f32x4*)(mr + sh_idx * 1024 + c);
;       h16x4 o;
;       o.x = (h16)(v[i].x * rstd * g.x * (1.f + sc.x) + sh.x);
;       o.y = (h16)(v[i].y * rstd * g.y * (1.f + sc.y) + sh.y);
;       o.z = (h16)(v[i].z * rstd * g.z * (1.f + sc.z) + sh.z);
;       o.w = (h16)(v[i].w * rstd * g.w * (1.f + sc.w) + sh.w);
;       *(h16x4*)(dst + (size_t)row * 1024 + c) = o;
;     }
;   }
; }
.LBB0_158:
	s_mul_i32 s41, s78, 0x36000
	s_add_u32 s56, s6, s41
	s_addc_u32 s57, s7, 0
	s_add_u32 s58, s48, 0x17cec000
	s_addc_u32 s59, s49, 0
	s_lshl_b32 s41, s78, 12
	s_add_u32 s60, s24, s41
	s_addc_u32 s61, s25, 0
	v_lshrrev_b32_e32 v128, 1, v0
	global_load_dwordx4 v[80:83], v0, s[60:61]
	global_load_dwordx4 v[84:87], v0, s[60:61] offset:1024
	global_load_dwordx4 v[88:91], v0, s[60:61] offset:2048
	global_load_dwordx4 v[92:95], v0, s[60:61] offset:3072
	v_readfirstlane_b32 s40, v22
	s_nop 3
	s_sub_u32 s42, s40, 0x8000
	s_cmp_lt_u32 s40, 0x8000
	s_cselect_b32 s42, s40, s42
	s_cselect_b32 s44, s82, s80
	s_cselect_b32 s45, s83, s81
	s_lshl_b32 s42, s42, 12
	s_add_u32 s44, s44, s42
	s_addc_u32 s45, s45, 0
	global_load_dwordx4 v[2:5], v0, s[44:45]
	global_load_dwordx4 v[6:9], v0, s[44:45] offset:1024
	global_load_dwordx4 v[10:13], v0, s[44:45] offset:2048
	global_load_dwordx4 v[14:17], v0, s[44:45] offset:3072
	s_mov_b32 s43, s40
	s_add_i32 s43, s43, s4
	s_cmp_lt_i32 s43, s36
	s_cbranch_scc0 .Lrnp_pre0
	s_sub_u32 s42, s43, 0x8000
	s_cmp_lt_u32 s43, 0x8000
	s_cselect_b32 s42, s43, s42
	s_cselect_b32 s44, s82, s80
	s_cselect_b32 s45, s83, s81
	s_lshl_b32 s42, s42, 12
	s_add_u32 s44, s44, s42
	s_addc_u32 s45, s45, 0
	global_load_dwordx4 v[32:35], v0, s[44:45]
	global_load_dwordx4 v[36:39], v0, s[44:45] offset:1024
	global_load_dwordx4 v[40:43], v0, s[44:45] offset:2048
	global_load_dwordx4 v[44:47], v0, s[44:45] offset:3072
	s_add_i32 s43, s43, s4
	s_cmp_lt_i32 s43, s36
	s_cbranch_scc0 .Lrnp_pre0
	s_sub_u32 s42, s43, 0x8000
	s_cmp_lt_u32 s43, 0x8000
	s_cselect_b32 s42, s43, s42
	s_cselect_b32 s44, s82, s80
	s_cselect_b32 s45, s83, s81
	s_lshl_b32 s42, s42, 12
	s_add_u32 s44, s44, s42
	s_addc_u32 s45, s45, 0
	global_load_dwordx4 v[162:165], v0, s[44:45]
	global_load_dwordx4 v[166:169], v0, s[44:45] offset:1024
	global_load_dwordx4 v[170:173], v0, s[44:45] offset:2048
	global_load_dwordx4 v[174:177], v0, s[44:45] offset:3072
.Lrnp_pre0:
	s_lshr_b32 s41, s40, 12
	s_cmp_lt_u32 s40, 0x8000
	s_cselect_b32 s41, s41, 8
	s_mul_i32 s41, s41, 0x6000
	s_add_u32 s50, s56, s41
	s_addc_u32 s51, s57, 0
	s_add_u32 s52, s50, 0x1000
	s_addc_u32 s53, s51, 0
	s_lshl_b32 s41, s40, 11
	s_add_u32 s54, s58, s41
	s_addc_u32 s55, s59, 0
	global_load_dwordx4 v[96:99], v0, s[52:53]
	global_load_dwordx4 v[100:103], v0, s[52:53] offset:1024
	global_load_dwordx4 v[104:107], v0, s[52:53] offset:2048
	global_load_dwordx4 v[108:111], v0, s[52:53] offset:3072
	global_load_dwordx4 v[178:181], v0, s[50:51]
	global_load_dwordx4 v[182:185], v0, s[50:51] offset:1024
	global_load_dwordx4 v[186:189], v0, s[50:51] offset:2048
	global_load_dwordx4 v[190:193], v0, s[50:51] offset:3072
	s_add_i32 s46, s40, s4
	s_add_i32 s46, s46, s4
	s_add_i32 s46, s46, s4
	s_cmp_lt_i32 s46, s36
	s_cbranch_scc0 .Lrnp_tail0
	s_sub_u32 s42, s46, 0x8000
	s_cmp_lt_u32 s46, 0x8000
	s_cselect_b32 s42, s46, s42
	s_cselect_b32 s44, s82, s80
	s_cselect_b32 s45, s83, s81
	s_lshl_b32 s42, s42, 12
	s_add_u32 s44, s44, s42
	s_addc_u32 s45, s45, 0
	global_load_dwordx4 v[204:207], v0, s[44:45]
	global_load_dwordx4 v[208:211], v0, s[44:45] offset:1024
	global_load_dwordx4 v[212:215], v0, s[44:45] offset:2048
	global_load_dwordx4 v[216:219], v0, s[44:45] offset:3072
	s_waitcnt vmcnt(20)
	v_mul_f32_e32 v112, v3, v3
	v_mul_f32_e32 v113, v7, v7
	v_mul_f32_e32 v114, v11, v11
	v_mul_f32_e32 v115, v15, v15
	v_fmac_f32_e32 v112, v2, v2
	v_fmac_f32_e32 v113, v6, v6
	v_fmac_f32_e32 v114, v10, v10
	v_fmac_f32_e32 v115, v14, v14
	v_fmac_f32_e32 v112, v4, v4
	v_fmac_f32_e32 v113, v8, v8
	v_fmac_f32_e32 v114, v12, v12
	v_fmac_f32_e32 v115, v16, v16
	v_fmac_f32_e32 v112, v5, v5
	v_fmac_f32_e32 v113, v9, v9
	v_fmac_f32_e32 v114, v13, v13
	v_fmac_f32_e32 v115, v17, v17
	v_add_f32_e32 v112, v112, v113
	v_add_f32_e32 v112, v112, v114
	v_add_f32_e32 v112, v112, v115
	s_nop 1
	v_add_f32_dpp v112, v112, v112 quad_perm:[1,0,3,2] row_mask:0xf bank_mask:0xf bound_ctrl:1
	s_nop 1
	v_add_f32_dpp v112, v112, v112 quad_perm:[2,3,0,1] row_mask:0xf bank_mask:0xf bound_ctrl:1
	s_nop 1
	v_add_f32_dpp v112, v112, v112 row_half_mirror row_mask:0xf bank_mask:0xf bound_ctrl:1
	s_nop 1
	v_add_f32_dpp v112, v112, v112 row_mirror row_mask:0xf bank_mask:0xf bound_ctrl:1
	s_nop 1
	ds_swizzle_b32 v113, v112 offset:swizzle(SWAP,16)
	s_waitcnt lgkmcnt(0)
	v_add_f32_e32 v112, v112, v113
	v_mov_b32_e32 v113, v112
	s_nop 1
	v_permlane32_swap_b32_e32 v112, v113
	v_add_f32_e32 v112, v112, v113
	v_fmamk_f32 v112, v112, 0x3a800000, v224
	v_rsq_f32_e32 v112, v112
	s_waitcnt vmcnt(4)
	v_mul_f32_e32 v2, v2, v112
	v_mul_f32_e32 v3, v3, v112
	v_mul_f32_e32 v4, v4, v112
	v_mul_f32_e32 v5, v5, v112
	v_mul_f32_e32 v6, v6, v112
	v_mul_f32_e32 v7, v7, v112
	v_mul_f32_e32 v8, v8, v112
	v_mul_f32_e32 v9, v9, v112
	v_mul_f32_e32 v10, v10, v112
	v_mul_f32_e32 v11, v11, v112
	v_mul_f32_e32 v12, v12, v112
	v_mul_f32_e32 v13, v13, v112
	v_mul_f32_e32 v14, v14, v112
	v_mul_f32_e32 v15, v15, v112
	v_mul_f32_e32 v16, v16, v112
	v_mul_f32_e32 v17, v17, v112
	v_mul_f32_e32 v2, v80, v2
	v_mul_f32_e32 v3, v81, v3
	v_mul_f32_e32 v4, v82, v4
	v_mul_f32_e32 v5, v83, v5
	v_mul_f32_e32 v6, v84, v6
	v_mul_f32_e32 v7, v85, v7
	v_mul_f32_e32 v8, v86, v8
	v_mul_f32_e32 v9, v87, v9
	v_mul_f32_e32 v10, v88, v10
	v_mul_f32_e32 v11, v89, v11
	v_mul_f32_e32 v12, v90, v12
	v_mul_f32_e32 v13, v91, v13
	v_mul_f32_e32 v14, v92, v14
	v_mul_f32_e32 v15, v93, v15
	v_mul_f32_e32 v16, v94, v16
	v_mul_f32_e32 v17, v95, v17
	v_add_f32_e32 v96, 1.0, v96
	v_add_f32_e32 v97, 1.0, v97
	v_add_f32_e32 v98, 1.0, v98
	v_add_f32_e32 v99, 1.0, v99
	v_add_f32_e32 v100, 1.0, v100
	v_add_f32_e32 v101, 1.0, v101
	v_add_f32_e32 v102, 1.0, v102
	v_add_f32_e32 v103, 1.0, v103
	v_add_f32_e32 v104, 1.0, v104
	v_add_f32_e32 v105, 1.0, v105
	v_add_f32_e32 v106, 1.0, v106
	v_add_f32_e32 v107, 1.0, v107
	v_add_f32_e32 v108, 1.0, v108
	v_add_f32_e32 v109, 1.0, v109
	v_add_f32_e32 v110, 1.0, v110
	v_add_f32_e32 v111, 1.0, v111
	v_fma_f32 v2, v96, v2, v178
	v_fma_f32 v3, v97, v3, v179
	v_fma_f32 v4, v98, v4, v180
	v_fma_f32 v5, v99, v5, v181
	v_fma_f32 v6, v100, v6, v182
	v_fma_f32 v7, v101, v7, v183
	v_fma_f32 v8, v102, v8, v184
	v_fma_f32 v9, v103, v9, v185
	v_fma_f32 v10, v104, v10, v186
	v_fma_f32 v11, v105, v11, v187
	v_fma_f32 v12, v106, v12, v188
	v_fma_f32 v13, v107, v13, v189
	v_fma_f32 v14, v108, v14, v190
	v_fma_f32 v15, v109, v15, v191
	v_fma_f32 v16, v110, v16, v192
	v_fma_f32 v17, v111, v17, v193
	v_cvt_pk_f16_f32 v114, v2, v3
	v_cvt_pk_f16_f32 v115, v4, v5
	v_cvt_pk_f16_f32 v116, v6, v7
	v_cvt_pk_f16_f32 v117, v8, v9
	v_cvt_pk_f16_f32 v118, v10, v11
	v_cvt_pk_f16_f32 v119, v12, v13
	v_cvt_pk_f16_f32 v120, v14, v15
	v_cvt_pk_f16_f32 v121, v16, v17
	global_store_dwordx2 v128, v[114:115], s[54:55]
	global_store_dwordx2 v128, v[116:117], s[54:55] offset:512
	global_store_dwordx2 v128, v[118:119], s[54:55] offset:1024
	global_store_dwordx2 v128, v[120:121], s[54:55] offset:1536
	s_add_i32 s40, s40, s4
; DI void rows_norm_mod(const P& p, const float* xlat, const float* xctx, int l, const float* gain, int sh_idx, int sc_idx,
;                       h16* dst, int nrows) {
;     ...
;   for (int row = gw; row < nrows; row += nw) {
;     const float* xr = row < TL ? xlat + (size_t)row * 1024 : xctx + (size_t)(row - TL) * 1024;
;     const int mrow = row < TL ? (row >> 12) : 8;
;     const float* mr = mod + ((size_t)l * 9 + mrow) * 6144;
;     f32x4 v[4];
;     float ss = 0.f;
; #pragma unroll
;     for (int i = 0; i < 4; ++i) {
;       v[i] = *(const f32x4*)(xr + lane * 4 + 256 * i);
;       ss += v[i].x * v[i].x + v[i].y * v[i].y + v[i].z * v[i].z + v[i].w * v[i].w;
;     }
;     ss = wave_sum(ss);
;     const float rstd = rsqrtf(ss * (1.f / 1024.f) + EPS);
; #pragma unroll
;     for (int i = 0; i < 4; ++i) {
;       const int c = lane * 4 + 256 * i;
;       f32x4 g = *(const f32x4*)(gain + c), sc = *(const f32x4*)(mr + sc_idx * 1024 + c), sh = *(const f32x4*)(mr + sh_idx * 1024 + c);
;       h16x4 o;
;       o.x = (h16)(v[i].x * rstd * g.x * (1.f + sc.x) + sh.x);
;       o.y = (h16)(v[i].y * rstd * g.y * (1.f + sc.y) + sh.y);
;       o.z = (h16)(v[i].z * rstd * g.z * (1.f + sc.z) + sh.z);
;       o.w = (h16)(v[i].w * rstd * g.w * (1.f + sc.w) + sh.w);
;       *(h16x4*)(dst + (size_t)row * 1024 + c) = o;
;     }
;   }
.Lrnp_pre1:
	s_lshr_b32 s41, s40, 12
	s_cmp_lt_u32 s40, 0x8000
	s_cselect_b32 s41, s41, 8
	s_mul_i32 s41, s41, 0x6000
	s_add_u32 s50, s56, s41
	s_addc_u32 s51, s57, 0
	s_add_u32 s52, s50, 0x1000
	s_addc_u32 s53, s51, 0
	s_lshl_b32 s41, s40, 11
	s_add_u32 s54, s58, s41
	s_addc_u32 s55, s59, 0
	global_load_dwordx4 v[96:99], v0, s[52:53]
	global_load_dwordx4 v[100:103], v0, s[52:53] offset:1024
	global_load_dwordx4 v[104:107], v0, s[52:53] offset:2048
	global_load_dwordx4 v[108:111], v0, s[52:53] offset:3072
	global_load_dwordx4 v[178:181], v0, s[50:51]
	global_load_dwordx4 v[182:185], v0, s[50:51] offset:1024
	global_load_dwordx4 v[186:189], v0, s[50:51] offset:2048
	global_load_dwordx4 v[190:193], v0, s[50:51] offset:3072
	s_add_i32 s46, s40, s4
	s_add_i32 s46, s46, s4
	s_add_i32 s46, s46, s4
	s_cmp_lt_i32 s46, s36
	s_cbranch_scc0 .Lrnp_tail1
	s_sub_u32 s42, s46, 0x8000
	s_cmp_lt_u32 s46, 0x8000
	s_cselect_b32 s42, s46, s42
	s_cselect_b32 s44, s82, s80
	s_cselect_b32 s45, s83, s81
	s_lshl_b32 s42, s42, 12
	s_add_u32 s44, s44, s42
	s_addc_u32 s45, s45, 0
	global_load_dwordx4 v[2:5], v0, s[44:45]
	global_load_dwordx4 v[6:9], v0, s[44:45] offset:1024
	global_load_dwordx4 v[10:13], v0, s[44:45] offset:2048
	global_load_dwordx4 v[14:17], v0, s[44:45] offset:3072
	s_waitcnt vmcnt(20)
	v_mul_f32_e32 v112, v33, v33
	v_mul_f32_e32 v113, v37, v37
	v_mul_f32_e32 v114, v41, v41
	v_mul_f32_e32 v115, v45, v45
	v_fmac_f32_e32 v112, v32, v32
	v_fmac_f32_e32 v113, v36, v36
	v_fmac_f32_e32 v114, v40, v40
	v_fmac_f32_e32 v115, v44, v44
	v_fmac_f32_e32 v112, v34, v34
	v_fmac_f32_e32 v113, v38, v38
	v_fmac_f32_e32 v114, v42, v42
	v_fmac_f32_e32 v115, v46, v46
	v_fmac_f32_e32 v112, v35, v35
	v_fmac_f32_e32 v113, v39, v39
	v_fmac_f32_e32 v114, v43, v43
	v_fmac_f32_e32 v115, v47, v47
	v_add_f32_e32 v112, v112, v113
	v_add_f32_e32 v112, v112, v114
	v_add_f32_e32 v112, v112, v115
	s_nop 1
	v_add_f32_dpp v112, v112, v112 quad_perm:[1,0,3,2] row_mask:0xf bank_mask:0xf bound_ctrl:1
	s_nop 1
	v_add_f32_dpp v112, v112, v112 quad_perm:[2,3,0,1] row_mask:0xf bank_mask:0xf bound_ctrl:1
	s_nop 1
	v_add_f32_dpp v112, v112, v112 row_half_mirror row_mask:0xf bank_mask:0xf bound_ctrl:1
	s_nop 1
	v_add_f32_dpp v112, v112, v112 row_mirror row_mask:0xf bank_mask:0xf bound_ctrl:1
	s_nop 1
	ds_swizzle_b32 v113, v112 offset:swizzle(SWAP,16)
	s_waitcnt lgkmcnt(0)
	v_add_f32_e32 v112, v112, v113
	v_mov_b32_e32 v113, v112
	s_nop 1
	v_permlane32_swap_b32_e32 v112, v113
	v_add_f32_e32 v112, v112, v113
	v_fmamk_f32 v112, v112, 0x3a800000, v224
	v_rsq_f32_e32 v112, v112
	s_waitcnt vmcnt(4)
	v_mul_f32_e32 v32, v32, v112
	v_mul_f32_e32 v33, v33, v112
	v_mul_f32_e32 v34, v34, v112
	v_mul_f32_e32 v35, v35, v112
	v_mul_f32_e32 v36, v36, v112
	v_mul_f32_e32 v37, v37, v112
	v_mul_f32_e32 v38, v38, v112
	v_mul_f32_e32 v39, v39, v112
	v_mul_f32_e32 v40, v40, v112
	v_mul_f32_e32 v41, v41, v112
	v_mul_f32_e32 v42, v42, v112
	v_mul_f32_e32 v43, v43, v112
	v_mul_f32_e32 v44, v44, v112
	v_mul_f32_e32 v45, v45, v112
	v_mul_f32_e32 v46, v46, v112
	v_mul_f32_e32 v47, v47, v112
	v_mul_f32_e32 v32, v80, v32
	v_mul_f32_e32 v33, v81, v33
	v_mul_f32_e32 v34, v82, v34
	v_mul_f32_e32 v35, v83, v35
	v_mul_f32_e32 v36, v84, v36
	v_mul_f32_e32 v37, v85, v37
	v_mul_f32_e32 v38, v86, v38
	v_mul_f32_e32 v39, v87, v39
	v_mul_f32_e32 v40, v88, v40
	v_mul_f32_e32 v41, v89, v41
	v_mul_f32_e32 v42, v90, v42
	v_mul_f32_e32 v43, v91, v43
	v_mul_f32_e32 v44, v92, v44
	v_mul_f32_e32 v45, v93, v45
	v_mul_f32_e32 v46, v94, v46
	v_mul_f32_e32 v47, v95, v47
	v_add_f32_e32 v96, 1.0, v96
	v_add_f32_e32 v97, 1.0, v97
	v_add_f32_e32 v98, 1.0, v98
	v_add_f32_e32 v99, 1.0, v99
	v_add_f32_e32 v100, 1.0, v100
	v_add_f32_e32 v101, 1.0, v101
	v_add_f32_e32 v102, 1.0, v102
	v_add_f32_e32 v103, 1.0, v103
	v_add_f32_e32 v104, 1.0, v104
	v_add_f32_e32 v105, 1.0, v105
	v_add_f32_e32 v106, 1.0, v106
	v_add_f32_e32 v107, 1.0, v107
	v_add_f32_e32 v108, 1.0, v108
	v_add_f32_e32 v109, 1.0, v109
	v_add_f32_e32 v110, 1.0, v110
	v_add_f32_e32 v111, 1.0, v111
	v_fma_f32 v32, v96, v32, v178
	v_fma_f32 v33, v97, v33, v179
	v_fma_f32 v34, v98, v34, v180
	v_fma_f32 v35, v99, v35, v181
	v_fma_f32 v36, v100, v36, v182
	v_fma_f32 v37, v101, v37, v183
	v_fma_f32 v38, v102, v38, v184
	v_fma_f32 v39, v103, v39, v185
	v_fma_f32 v40, v104, v40, v186
	v_fma_f32 v41, v105, v41, v187
	v_fma_f32 v42, v106, v42, v188
	v_fma_f32 v43, v107, v43, v189
	v_fma_f32 v44, v108, v44, v190
	v_fma_f32 v45, v109, v45, v191
	v_fma_f32 v46, v110, v46, v192
	v_fma_f32 v47, v111, v47, v193
	v_cvt_pk_f16_f32 v114, v32, v33
	v_cvt_pk_f16_f32 v115, v34, v35
	v_cvt_pk_f16_f32 v116, v36, v37
	v_cvt_pk_f16_f32 v117, v38, v39
	v_cvt_pk_f16_f32 v118, v40, v41
	v_cvt_pk_f16_f32 v119, v42, v43
	v_cvt_pk_f16_f32 v120, v44, v45
	v_cvt_pk_f16_f32 v121, v46, v47
	global_store_dwordx2 v128, v[114:115], s[54:55]
	global_store_dwordx2 v128, v[116:117], s[54:55] offset:512
	global_store_dwordx2 v128, v[118:119], s[54:55] offset:1024
	global_store_dwordx2 v128, v[120:121], s[54:55] offset:1536
	s_add_i32 s40, s40, s4
; DI void rows_norm_mod(const P& p, const float* xlat, const float* xctx, int l, const float* gain, int sh_idx, int sc_idx,
;                       h16* dst, int nrows) {
;     ...
;   for (int row = gw; row < nrows; row += nw) {
;     const float* xr = row < TL ? xlat + (size_t)row * 1024 : xctx + (size_t)(row - TL) * 1024;
;     const int mrow = row < TL ? (row >> 12) : 8;
;     const float* mr = mod + ((size_t)l * 9 + mrow) * 6144;
;     f32x4 v[4];
;     float ss = 0.f;
; #pragma unroll
;     for (int i = 0; i < 4; ++i) {
;       v[i] = *(const f32x4*)(xr + lane * 4 + 256 * i);
;       ss += v[i].x * v[i].x + v[i].y * v[i].y + v[i].z * v[i].z + v[i].w * v[i].w;
;     }
;     ss = wave_sum(ss);
;     const float rstd = rsqrtf(ss * (1.f / 1024.f) + EPS);
; #pragma unroll
;     for (int i = 0; i < 4; ++i) {
;       const int c = lane * 4 + 256 * i;
;       f32x4 g = *(const f32x4*)(gain + c), sc = *(const f32x4*)(mr + sc_idx * 1024 + c), sh = *(const f32x4*)(mr + sh_idx * 1024 + c);
;       h16x4 o;
;       o.x = (h16)(v[i].x * rstd * g.x * (1.f + sc.x) + sh.x);
;       o.y = (h16)(v[i].y * rstd * g.y * (1.f + sc.y) + sh.y);
;       o.z = (h16)(v[i].z * rstd * g.z * (1.f + sc.z) + sh.z);
;       o.w = (h16)(v[i].w * rstd * g.w * (1.f + sc.w) + sh.w);
;       *(h16x4*)(dst + (size_t)row * 1024 + c) = o;
;     }
;   }
.Lrnp_pre2:
	s_lshr_b32 s41, s40, 12
	s_cmp_lt_u32 s40, 0x8000
	s_cselect_b32 s41, s41, 8
	s_mul_i32 s41, s41, 0x6000
	s_add_u32 s50, s56, s41
	s_addc_u32 s51, s57, 0
	s_add_u32 s52, s50, 0x1000
	s_addc_u32 s53, s51, 0
	s_lshl_b32 s41, s40, 11
	s_add_u32 s54, s58, s41
	s_addc_u32 s55, s59, 0
	global_load_dwordx4 v[96:99], v0, s[52:53]
	global_load_dwordx4 v[100:103], v0, s[52:53] offset:1024
	global_load_dwordx4 v[104:107], v0, s[52:53] offset:2048
	global_load_dwordx4 v[108:111], v0, s[52:53] offset:3072
	global_load_dwordx4 v[178:181], v0, s[50:51]
	global_load_dwordx4 v[182:185], v0, s[50:51] offset:1024
	global_load_dwordx4 v[186:189], v0, s[50:51] offset:2048
	global_load_dwordx4 v[190:193], v0, s[50:51] offset:3072
	s_add_i32 s46, s40, s4
	s_add_i32 s46, s46, s4
	s_add_i32 s46, s46, s4
	s_cmp_lt_i32 s46, s36
	s_cbranch_scc0 .Lrnp_tail2
	s_sub_u32 s42, s46, 0x8000
	s_cmp_lt_u32 s46, 0x8000
	s_cselect_b32 s42, s46, s42
	s_cselect_b32 s44, s82, s80
	s_cselect_b32 s45, s83, s81
	s_lshl_b32 s42, s42, 12
	s_add_u32 s44, s44, s42
	s_addc_u32 s45, s45, 0
	global_load_dwordx4 v[32:35], v0, s[44:45]
	global_load_dwordx4 v[36:39], v0, s[44:45] offset:1024
	global_load_dwordx4 v[40:43], v0, s[44:45] offset:2048
	global_load_dwordx4 v[44:47], v0, s[44:45] offset:3072
	s_waitcnt vmcnt(20)
	v_mul_f32_e32 v112, v163, v163
	v_mul_f32_e32 v113, v167, v167
	v_mul_f32_e32 v114, v171, v171
	v_mul_f32_e32 v115, v175, v175
	v_fmac_f32_e32 v112, v162, v162
	v_fmac_f32_e32 v113, v166, v166
	v_fmac_f32_e32 v114, v170, v170
	v_fmac_f32_e32 v115, v174, v174
	v_fmac_f32_e32 v112, v164, v164
	v_fmac_f32_e32 v113, v168, v168
	v_fmac_f32_e32 v114, v172, v172
	v_fmac_f32_e32 v115, v176, v176
	v_fmac_f32_e32 v112, v165, v165
	v_fmac_f32_e32 v113, v169, v169
	v_fmac_f32_e32 v114, v173, v173
	v_fmac_f32_e32 v115, v177, v177
	v_add_f32_e32 v112, v112, v113
	v_add_f32_e32 v112, v112, v114
	v_add_f32_e32 v112, v112, v115
	s_nop 1
	v_add_f32_dpp v112, v112, v112 quad_perm:[1,0,3,2] row_mask:0xf bank_mask:0xf bound_ctrl:1
	s_nop 1
	v_add_f32_dpp v112, v112, v112 quad_perm:[2,3,0,1] row_mask:0xf bank_mask:0xf bound_ctrl:1
	s_nop 1
	v_add_f32_dpp v112, v112, v112 row_half_mirror row_mask:0xf bank_mask:0xf bound_ctrl:1
	s_nop 1
	v_add_f32_dpp v112, v112, v112 row_mirror row_mask:0xf bank_mask:0xf bound_ctrl:1
	s_nop 1
	ds_swizzle_b32 v113, v112 offset:swizzle(SWAP,16)
	s_waitcnt lgkmcnt(0)
	v_add_f32_e32 v112, v112, v113
	v_mov_b32_e32 v113, v112
	s_nop 1
	v_permlane32_swap_b32_e32 v112, v113
	v_add_f32_e32 v112, v112, v113
	v_fmamk_f32 v112, v112, 0x3a800000, v224
	v_rsq_f32_e32 v112, v112
	s_waitcnt vmcnt(4)
	v_mul_f32_e32 v162, v162, v112
	v_mul_f32_e32 v163, v163, v112
	v_mul_f32_e32 v164, v164, v112
	v_mul_f32_e32 v165, v165, v112
	v_mul_f32_e32 v166, v166, v112
	v_mul_f32_e32 v167, v167, v112
	v_mul_f32_e32 v168, v168, v112
	v_mul_f32_e32 v169, v169, v112
	v_mul_f32_e32 v170, v170, v112
	v_mul_f32_e32 v171, v171, v112
	v_mul_f32_e32 v172, v172, v112
	v_mul_f32_e32 v173, v173, v112
	v_mul_f32_e32 v174, v174, v112
	v_mul_f32_e32 v175, v175, v112
	v_mul_f32_e32 v176, v176, v112
	v_mul_f32_e32 v177, v177, v112
	v_mul_f32_e32 v162, v80, v162
	v_mul_f32_e32 v163, v81, v163
	v_mul_f32_e32 v164, v82, v164
	v_mul_f32_e32 v165, v83, v165
	v_mul_f32_e32 v166, v84, v166
	v_mul_f32_e32 v167, v85, v167
	v_mul_f32_e32 v168, v86, v168
	v_mul_f32_e32 v169, v87, v169
	v_mul_f32_e32 v170, v88, v170
	v_mul_f32_e32 v171, v89, v171
	v_mul_f32_e32 v172, v90, v172
	v_mul_f32_e32 v173, v91, v173
	v_mul_f32_e32 v174, v92, v174
	v_mul_f32_e32 v175, v93, v175
	v_mul_f32_e32 v176, v94, v176
	v_mul_f32_e32 v177, v95, v177
	v_add_f32_e32 v96, 1.0, v96
	v_add_f32_e32 v97, 1.0, v97
	v_add_f32_e32 v98, 1.0, v98
	v_add_f32_e32 v99, 1.0, v99
	v_add_f32_e32 v100, 1.0, v100
	v_add_f32_e32 v101, 1.0, v101
	v_add_f32_e32 v102, 1.0, v102
	v_add_f32_e32 v103, 1.0, v103
	v_add_f32_e32 v104, 1.0, v104
	v_add_f32_e32 v105, 1.0, v105
	v_add_f32_e32 v106, 1.0, v106
	v_add_f32_e32 v107, 1.0, v107
	v_add_f32_e32 v108, 1.0, v108
	v_add_f32_e32 v109, 1.0, v109
	v_add_f32_e32 v110, 1.0, v110
	v_add_f32_e32 v111, 1.0, v111
	v_fma_f32 v162, v96, v162, v178
	v_fma_f32 v163, v97, v163, v179
	v_fma_f32 v164, v98, v164, v180
	v_fma_f32 v165, v99, v165, v181
	v_fma_f32 v166, v100, v166, v182
	v_fma_f32 v167, v101, v167, v183
	v_fma_f32 v168, v102, v168, v184
	v_fma_f32 v169, v103, v169, v185
	v_fma_f32 v170, v104, v170, v186
	v_fma_f32 v171, v105, v171, v187
	v_fma_f32 v172, v106, v172, v188
	v_fma_f32 v173, v107, v173, v189
	v_fma_f32 v174, v108, v174, v190
	v_fma_f32 v175, v109, v175, v191
	v_fma_f32 v176, v110, v176, v192
	v_fma_f32 v177, v111, v177, v193
	v_cvt_pk_f16_f32 v114, v162, v163
	v_cvt_pk_f16_f32 v115, v164, v165
	v_cvt_pk_f16_f32 v116, v166, v167
	v_cvt_pk_f16_f32 v117, v168, v169
	v_cvt_pk_f16_f32 v118, v170, v171
	v_cvt_pk_f16_f32 v119, v172, v173
	v_cvt_pk_f16_f32 v120, v174, v175
	v_cvt_pk_f16_f32 v121, v176, v177
	global_store_dwordx2 v128, v[114:115], s[54:55]
	global_store_dwordx2 v128, v[116:117], s[54:55] offset:512
	global_store_dwordx2 v128, v[118:119], s[54:55] offset:1024
	global_store_dwordx2 v128, v[120:121], s[54:55] offset:1536
	s_add_i32 s40, s40, s4
; DI void rows_norm_mod(const P& p, const float* xlat, const float* xctx, int l, const float* gain, int sh_idx, int sc_idx,
;                       h16* dst, int nrows) {
;     ...
;   for (int row = gw; row < nrows; row += nw) {
;     const float* xr = row < TL ? xlat + (size_t)row * 1024 : xctx + (size_t)(row - TL) * 1024;
;     const int mrow = row < TL ? (row >> 12) : 8;
;     const float* mr = mod + ((size_t)l * 9 + mrow) * 6144;
;     f32x4 v[4];
;     float ss = 0.f;
; #pragma unroll
;     for (int i = 0; i < 4; ++i) {
;       v[i] = *(const f32x4*)(xr + lane * 4 + 256 * i);
;       ss += v[i].x * v[i].x + v[i].y * v[i].y + v[i].z * v[i].z + v[i].w * v[i].w;
;     }
;     ss = wave_sum(ss);
;     const float rstd = rsqrtf(ss * (1.f / 1024.f) + EPS);
; #pragma unroll
;     for (int i = 0; i < 4; ++i) {
;       const int c = lane * 4 + 256 * i;
;       f32x4 g = *(const f32x4*)(gain + c), sc = *(const f32x4*)(mr + sc_idx * 1024 + c), sh = *(const f32x4*)(mr + sh_idx * 1024 + c);
;       h16x4 o;
;       o.x = (h16)(v[i].x * rstd * g.x * (1.f + sc.x) + sh.x);
;       o.y = (h16)(v[i].y * rstd * g.y * (1.f + sc.y) + sh.y);
;       o.z = (h16)(v[i].z * rstd * g.z * (1.f + sc.z) + sh.z);
;       o.w = (h16)(v[i].w * rstd * g.w * (1.f + sc.w) + sh.w);
;       *(h16x4*)(dst + (size_t)row * 1024 + c) = o;
;     }
;   }
.Lrnp_l3:
	s_lshr_b32 s41, s40, 12
	s_cmp_lt_u32 s40, 0x8000
	s_cselect_b32 s41, s41, 8
	s_mul_i32 s41, s41, 0x6000
	s_add_u32 s50, s56, s41
	s_addc_u32 s51, s57, 0
	s_add_u32 s52, s50, 0x1000
	s_addc_u32 s53, s51, 0
	s_lshl_b32 s41, s40, 11
	s_add_u32 s54, s58, s41
	s_addc_u32 s55, s59, 0
	global_load_dwordx4 v[96:99], v0, s[52:53]
	global_load_dwordx4 v[100:103], v0, s[52:53] offset:1024
	global_load_dwordx4 v[104:107], v0, s[52:53] offset:2048
	global_load_dwordx4 v[108:111], v0, s[52:53] offset:3072
	global_load_dwordx4 v[178:181], v0, s[50:51]
	global_load_dwordx4 v[182:185], v0, s[50:51] offset:1024
	global_load_dwordx4 v[186:189], v0, s[50:51] offset:2048
	global_load_dwordx4 v[190:193], v0, s[50:51] offset:3072
	s_add_i32 s46, s40, s4
	s_add_i32 s46, s46, s4
	s_add_i32 s46, s46, s4
	s_cmp_lt_i32 s46, s36
	s_cbranch_scc0 .Lrnp_tail3
	s_sub_u32 s42, s46, 0x8000
	s_cmp_lt_u32 s46, 0x8000
	s_cselect_b32 s42, s46, s42
	s_cselect_b32 s44, s82, s80
	s_cselect_b32 s45, s83, s81
	s_lshl_b32 s42, s42, 12
	s_add_u32 s44, s44, s42
	s_addc_u32 s45, s45, 0
	global_load_dwordx4 v[162:165], v0, s[44:45]
	global_load_dwordx4 v[166:169], v0, s[44:45] offset:1024
	global_load_dwordx4 v[170:173], v0, s[44:45] offset:2048
	global_load_dwordx4 v[174:177], v0, s[44:45] offset:3072
	s_waitcnt vmcnt(48)
	v_mul_f32_e32 v112, v205, v205
	v_mul_f32_e32 v113, v209, v209
	v_mul_f32_e32 v114, v213, v213
	v_mul_f32_e32 v115, v217, v217
	v_fmac_f32_e32 v112, v204, v204
	v_fmac_f32_e32 v113, v208, v208
	v_fmac_f32_e32 v114, v212, v212
	v_fmac_f32_e32 v115, v216, v216
	v_fmac_f32_e32 v112, v206, v206
	v_fmac_f32_e32 v113, v210, v210
	v_fmac_f32_e32 v114, v214, v214
	v_fmac_f32_e32 v115, v218, v218
	v_fmac_f32_e32 v112, v207, v207
	v_fmac_f32_e32 v113, v211, v211
	v_fmac_f32_e32 v114, v215, v215
	v_fmac_f32_e32 v115, v219, v219
	v_add_f32_e32 v112, v112, v113
	v_add_f32_e32 v112, v112, v114
	v_add_f32_e32 v112, v112, v115
	s_nop 1
	v_add_f32_dpp v112, v112, v112 quad_perm:[1,0,3,2] row_mask:0xf bank_mask:0xf bound_ctrl:1
	s_nop 1
	v_add_f32_dpp v112, v112, v112 quad_perm:[2,3,0,1] row_mask:0xf bank_mask:0xf bound_ctrl:1
	s_nop 1
	v_add_f32_dpp v112, v112, v112 row_half_mirror row_mask:0xf bank_mask:0xf bound_ctrl:1
	s_nop 1
	v_add_f32_dpp v112, v112, v112 row_mirror row_mask:0xf bank_mask:0xf bound_ctrl:1
	s_nop 1
	ds_swizzle_b32 v113, v112 offset:swizzle(SWAP,16)
	s_waitcnt lgkmcnt(0)
	v_add_f32_e32 v112, v112, v113
	v_mov_b32_e32 v113, v112
	s_nop 1
	v_permlane32_swap_b32_e32 v112, v113
	v_add_f32_e32 v112, v112, v113
	v_fmamk_f32 v112, v112, 0x3a800000, v224
	v_rsq_f32_e32 v112, v112
	s_waitcnt vmcnt(4)
	v_mul_f32_e32 v204, v204, v112
	v_mul_f32_e32 v205, v205, v112
	v_mul_f32_e32 v206, v206, v112
	v_mul_f32_e32 v207, v207, v112
	v_mul_f32_e32 v208, v208, v112
	v_mul_f32_e32 v209, v209, v112
	v_mul_f32_e32 v210, v210, v112
	v_mul_f32_e32 v211, v211, v112
	v_mul_f32_e32 v212, v212, v112
	v_mul_f32_e32 v213, v213, v112
	v_mul_f32_e32 v214, v214, v112
	v_mul_f32_e32 v215, v215, v112
	v_mul_f32_e32 v216, v216, v112
	v_mul_f32_e32 v217, v217, v112
	v_mul_f32_e32 v218, v218, v112
	v_mul_f32_e32 v219, v219, v112
	v_mul_f32_e32 v204, v80, v204
	v_mul_f32_e32 v205, v81, v205
	v_mul_f32_e32 v206, v82, v206
	v_mul_f32_e32 v207, v83, v207
	v_mul_f32_e32 v208, v84, v208
	v_mul_f32_e32 v209, v85, v209
	v_mul_f32_e32 v210, v86, v210
	v_mul_f32_e32 v211, v87, v211
	v_mul_f32_e32 v212, v88, v212
	v_mul_f32_e32 v213, v89, v213
	v_mul_f32_e32 v214, v90, v214
	v_mul_f32_e32 v215, v91, v215
	v_mul_f32_e32 v216, v92, v216
	v_mul_f32_e32 v217, v93, v217
	v_mul_f32_e32 v218, v94, v218
	v_mul_f32_e32 v219, v95, v219
	v_add_f32_e32 v96, 1.0, v96
	v_add_f32_e32 v97, 1.0, v97
	v_add_f32_e32 v98, 1.0, v98
	v_add_f32_e32 v99, 1.0, v99
	v_add_f32_e32 v100, 1.0, v100
	v_add_f32_e32 v101, 1.0, v101
	v_add_f32_e32 v102, 1.0, v102
	v_add_f32_e32 v103, 1.0, v103
	v_add_f32_e32 v104, 1.0, v104
	v_add_f32_e32 v105, 1.0, v105
	v_add_f32_e32 v106, 1.0, v106
	v_add_f32_e32 v107, 1.0, v107
	v_add_f32_e32 v108, 1.0, v108
	v_add_f32_e32 v109, 1.0, v109
	v_add_f32_e32 v110, 1.0, v110
	v_add_f32_e32 v111, 1.0, v111
	v_fma_f32 v204, v96, v204, v178
	v_fma_f32 v205, v97, v205, v179
	v_fma_f32 v206, v98, v206, v180
	v_fma_f32 v207, v99, v207, v181
	v_fma_f32 v208, v100, v208, v182
	v_fma_f32 v209, v101, v209, v183
	v_fma_f32 v210, v102, v210, v184
	v_fma_f32 v211, v103, v211, v185
	v_fma_f32 v212, v104, v212, v186
	v_fma_f32 v213, v105, v213, v187
	v_fma_f32 v214, v106, v214, v188
	v_fma_f32 v215, v107, v215, v189
	v_fma_f32 v216, v108, v216, v190
	v_fma_f32 v217, v109, v217, v191
	v_fma_f32 v218, v110, v218, v192
	v_fma_f32 v219, v111, v219, v193
	v_cvt_pk_f16_f32 v114, v204, v205
	v_cvt_pk_f16_f32 v115, v206, v207
	v_cvt_pk_f16_f32 v116, v208, v209
	v_cvt_pk_f16_f32 v117, v210, v211
	v_cvt_pk_f16_f32 v118, v212, v213
	v_cvt_pk_f16_f32 v119, v214, v215
	v_cvt_pk_f16_f32 v120, v216, v217
	v_cvt_pk_f16_f32 v121, v218, v219
	global_store_dwordx2 v128, v[114:115], s[54:55]
	global_store_dwordx2 v128, v[116:117], s[54:55] offset:512
	global_store_dwordx2 v128, v[118:119], s[54:55] offset:1024
	global_store_dwordx2 v128, v[120:121], s[54:55] offset:1536
	s_add_i32 s40, s40, s4
; DI void rows_norm_mod(const P& p, const float* xlat, const float* xctx, int l, const float* gain, int sh_idx, int sc_idx,
;                       h16* dst, int nrows) {
;     ...
;   for (int row = gw; row < nrows; row += nw) {
;     const float* xr = row < TL ? xlat + (size_t)row * 1024 : xctx + (size_t)(row - TL) * 1024;
;     const int mrow = row < TL ? (row >> 12) : 8;
;     const float* mr = mod + ((size_t)l * 9 + mrow) * 6144;
;     f32x4 v[4];
;     float ss = 0.f;
; #pragma unroll
;     for (int i = 0; i < 4; ++i) {
;       v[i] = *(const f32x4*)(xr + lane * 4 + 256 * i);
;       ss += v[i].x * v[i].x + v[i].y * v[i].y + v[i].z * v[i].z + v[i].w * v[i].w;
;     }
;     ss = wave_sum(ss);
;     const float rstd = rsqrtf(ss * (1.f / 1024.f) + EPS);
; #pragma unroll
;     for (int i = 0; i < 4; ++i) {
;       const int c = lane * 4 + 256 * i;
;       f32x4 g = *(const f32x4*)(gain + c), sc = *(const f32x4*)(mr + sc_idx * 1024 + c), sh = *(const f32x4*)(mr + sh_idx * 1024 + c);
;       h16x4 o;
;       o.x = (h16)(v[i].x * rstd * g.x * (1.f + sc.x) + sh.x);
;       o.y = (h16)(v[i].y * rstd * g.y * (1.f + sc.y) + sh.y);
;       o.z = (h16)(v[i].z * rstd * g.z * (1.f + sc.z) + sh.z);
;       o.w = (h16)(v[i].w * rstd * g.w * (1.f + sc.w) + sh.w);
;       *(h16x4*)(dst + (size_t)row * 1024 + c) = o;
;     }
;   }
.Lrnp_l0:
	s_lshr_b32 s41, s40, 12
	s_cmp_lt_u32 s40, 0x8000
	s_cselect_b32 s41, s41, 8
	s_mul_i32 s41, s41, 0x6000
	s_add_u32 s50, s56, s41
	s_addc_u32 s51, s57, 0
	s_add_u32 s52, s50, 0x1000
	s_addc_u32 s53, s51, 0
	s_lshl_b32 s41, s40, 11
	s_add_u32 s54, s58, s41
	s_addc_u32 s55, s59, 0
	global_load_dwordx4 v[96:99], v0, s[52:53]
	global_load_dwordx4 v[100:103], v0, s[52:53] offset:1024
	global_load_dwordx4 v[104:107], v0, s[52:53] offset:2048
	global_load_dwordx4 v[108:111], v0, s[52:53] offset:3072
	global_load_dwordx4 v[178:181], v0, s[50:51]
	global_load_dwordx4 v[182:185], v0, s[50:51] offset:1024
	global_load_dwordx4 v[186:189], v0, s[50:51] offset:2048
	global_load_dwordx4 v[190:193], v0, s[50:51] offset:3072
	s_add_i32 s46, s40, s4
	s_add_i32 s46, s46, s4
	s_add_i32 s46, s46, s4
	s_cmp_lt_i32 s46, s36
	s_cbranch_scc0 .Lrnp_tail0
	s_sub_u32 s42, s46, 0x8000
	s_cmp_lt_u32 s46, 0x8000
	s_cselect_b32 s42, s46, s42
	s_cselect_b32 s44, s82, s80
	s_cselect_b32 s45, s83, s81
	s_lshl_b32 s42, s42, 12
	s_add_u32 s44, s44, s42
	s_addc_u32 s45, s45, 0
	global_load_dwordx4 v[204:207], v0, s[44:45]
	global_load_dwordx4 v[208:211], v0, s[44:45] offset:1024
	global_load_dwordx4 v[212:215], v0, s[44:45] offset:2048
	global_load_dwordx4 v[216:219], v0, s[44:45] offset:3072
	s_waitcnt vmcnt(48)
	v_mul_f32_e32 v112, v3, v3
	v_mul_f32_e32 v113, v7, v7
	v_mul_f32_e32 v114, v11, v11
	v_mul_f32_e32 v115, v15, v15
	v_fmac_f32_e32 v112, v2, v2
	v_fmac_f32_e32 v113, v6, v6
	v_fmac_f32_e32 v114, v10, v10
	v_fmac_f32_e32 v115, v14, v14
	v_fmac_f32_e32 v112, v4, v4
	v_fmac_f32_e32 v113, v8, v8
	v_fmac_f32_e32 v114, v12, v12
	v_fmac_f32_e32 v115, v16, v16
	v_fmac_f32_e32 v112, v5, v5
	v_fmac_f32_e32 v113, v9, v9
	v_fmac_f32_e32 v114, v13, v13
	v_fmac_f32_e32 v115, v17, v17
	v_add_f32_e32 v112, v112, v113
	v_add_f32_e32 v112, v112, v114
	v_add_f32_e32 v112, v112, v115
	s_nop 1
	v_add_f32_dpp v112, v112, v112 quad_perm:[1,0,3,2] row_mask:0xf bank_mask:0xf bound_ctrl:1
	s_nop 1
	v_add_f32_dpp v112, v112, v112 quad_perm:[2,3,0,1] row_mask:0xf bank_mask:0xf bound_ctrl:1
	s_nop 1
	v_add_f32_dpp v112, v112, v112 row_half_mirror row_mask:0xf bank_mask:0xf bound_ctrl:1
	s_nop 1
	v_add_f32_dpp v112, v112, v112 row_mirror row_mask:0xf bank_mask:0xf bound_ctrl:1
	s_nop 1
	ds_swizzle_b32 v113, v112 offset:swizzle(SWAP,16)
	s_waitcnt lgkmcnt(0)
	v_add_f32_e32 v112, v112, v113
	v_mov_b32_e32 v113, v112
	s_nop 1
	v_permlane32_swap_b32_e32 v112, v113
	v_add_f32_e32 v112, v112, v113
	v_fmamk_f32 v112, v112, 0x3a800000, v224
	v_rsq_f32_e32 v112, v112
	s_waitcnt vmcnt(4)
	v_mul_f32_e32 v2, v2, v112
	v_mul_f32_e32 v3, v3, v112
	v_mul_f32_e32 v4, v4, v112
	v_mul_f32_e32 v5, v5, v112
	v_mul_f32_e32 v6, v6, v112
	v_mul_f32_e32 v7, v7, v112
	v_mul_f32_e32 v8, v8, v112
	v_mul_f32_e32 v9, v9, v112
	v_mul_f32_e32 v10, v10, v112
	v_mul_f32_e32 v11, v11, v112
	v_mul_f32_e32 v12, v12, v112
	v_mul_f32_e32 v13, v13, v112
	v_mul_f32_e32 v14, v14, v112
	v_mul_f32_e32 v15, v15, v112
	v_mul_f32_e32 v16, v16, v112
	v_mul_f32_e32 v17, v17, v112
	v_mul_f32_e32 v2, v80, v2
	v_mul_f32_e32 v3, v81, v3
	v_mul_f32_e32 v4, v82, v4
	v_mul_f32_e32 v5, v83, v5
	v_mul_f32_e32 v6, v84, v6
	v_mul_f32_e32 v7, v85, v7
	v_mul_f32_e32 v8, v86, v8
	v_mul_f32_e32 v9, v87, v9
	v_mul_f32_e32 v10, v88, v10
	v_mul_f32_e32 v11, v89, v11
	v_mul_f32_e32 v12, v90, v12
	v_mul_f32_e32 v13, v91, v13
	v_mul_f32_e32 v14, v92, v14
	v_mul_f32_e32 v15, v93, v15
	v_mul_f32_e32 v16, v94, v16
	v_mul_f32_e32 v17, v95, v17
	v_add_f32_e32 v96, 1.0, v96
	v_add_f32_e32 v97, 1.0, v97
	v_add_f32_e32 v98, 1.0, v98
	v_add_f32_e32 v99, 1.0, v99
	v_add_f32_e32 v100, 1.0, v100
	v_add_f32_e32 v101, 1.0, v101
	v_add_f32_e32 v102, 1.0, v102
	v_add_f32_e32 v103, 1.0, v103
	v_add_f32_e32 v104, 1.0, v104
	v_add_f32_e32 v105, 1.0, v105
	v_add_f32_e32 v106, 1.0, v106
	v_add_f32_e32 v107, 1.0, v107
	v_add_f32_e32 v108, 1.0, v108
	v_add_f32_e32 v109, 1.0, v109
	v_add_f32_e32 v110, 1.0, v110
	v_add_f32_e32 v111, 1.0, v111
	v_fma_f32 v2, v96, v2, v178
	v_fma_f32 v3, v97, v3, v179
	v_fma_f32 v4, v98, v4, v180
	v_fma_f32 v5, v99, v5, v181
	v_fma_f32 v6, v100, v6, v182
	v_fma_f32 v7, v101, v7, v183
	v_fma_f32 v8, v102, v8, v184
	v_fma_f32 v9, v103, v9, v185
	v_fma_f32 v10, v104, v10, v186
	v_fma_f32 v11, v105, v11, v187
	v_fma_f32 v12, v106, v12, v188
	v_fma_f32 v13, v107, v13, v189
	v_fma_f32 v14, v108, v14, v190
	v_fma_f32 v15, v109, v15, v191
	v_fma_f32 v16, v110, v16, v192
	v_fma_f32 v17, v111, v17, v193
	v_cvt_pk_f16_f32 v114, v2, v3
	v_cvt_pk_f16_f32 v115, v4, v5
	v_cvt_pk_f16_f32 v116, v6, v7
	v_cvt_pk_f16_f32 v117, v8, v9
	v_cvt_pk_f16_f32 v118, v10, v11
	v_cvt_pk_f16_f32 v119, v12, v13
	v_cvt_pk_f16_f32 v120, v14, v15
	v_cvt_pk_f16_f32 v121, v16, v17
	global_store_dwordx2 v128, v[114:115], s[54:55]
	global_store_dwordx2 v128, v[116:117], s[54:55] offset:512
	global_store_dwordx2 v128, v[118:119], s[54:55] offset:1024
	global_store_dwordx2 v128, v[120:121], s[54:55] offset:1536
	s_add_i32 s40, s40, s4
; DI void rows_norm_mod(const P& p, const float* xlat, const float* xctx, int l, const float* gain, int sh_idx, int sc_idx,
;                       h16* dst, int nrows) {
;     ...
;   for (int row = gw; row < nrows; row += nw) {
;     const float* xr = row < TL ? xlat + (size_t)row * 1024 : xctx + (size_t)(row - TL) * 1024;
;     const int mrow = row < TL ? (row >> 12) : 8;
;     const float* mr = mod + ((size_t)l * 9 + mrow) * 6144;
;     f32x4 v[4];
;     float ss = 0.f;
; #pragma unroll
;     for (int i = 0; i < 4; ++i) {
;       v[i] = *(const f32x4*)(xr + lane * 4 + 256 * i);
;       ss += v[i].x * v[i].x + v[i].y * v[i].y + v[i].z * v[i].z + v[i].w * v[i].w;
;     }
;     ss = wave_sum(ss);
;     const float rstd = rsqrtf(ss * (1.f / 1024.f) + EPS);
; #pragma unroll
;     for (int i = 0; i < 4; ++i) {
;       const int c = lane * 4 + 256 * i;
;       f32x4 g = *(const f32x4*)(gain + c), sc = *(const f32x4*)(mr + sc_idx * 1024 + c), sh = *(const f32x4*)(mr + sh_idx * 1024 + c);
;       h16x4 o;
;       o.x = (h16)(v[i].x * rstd * g.x * (1.f + sc.x) + sh.x);
;       o.y = (h16)(v[i].y * rstd * g.y * (1.f + sc.y) + sh.y);
;       o.z = (h16)(v[i].z * rstd * g.z * (1.f + sc.z) + sh.z);
;       o.w = (h16)(v[i].w * rstd * g.w * (1.f + sc.w) + sh.w);
;       *(h16x4*)(dst + (size_t)row * 1024 + c) = o;
;     }
;   }
.Lrnp_l1:
	s_lshr_b32 s41, s40, 12
	s_cmp_lt_u32 s40, 0x8000
	s_cselect_b32 s41, s41, 8
	s_mul_i32 s41, s41, 0x6000
	s_add_u32 s50, s56, s41
	s_addc_u32 s51, s57, 0
	s_add_u32 s52, s50, 0x1000
	s_addc_u32 s53, s51, 0
	s_lshl_b32 s41, s40, 11
	s_add_u32 s54, s58, s41
	s_addc_u32 s55, s59, 0
	global_load_dwordx4 v[96:99], v0, s[52:53]
	global_load_dwordx4 v[100:103], v0, s[52:53] offset:1024
	global_load_dwordx4 v[104:107], v0, s[52:53] offset:2048
	global_load_dwordx4 v[108:111], v0, s[52:53] offset:3072
	global_load_dwordx4 v[178:181], v0, s[50:51]
	global_load_dwordx4 v[182:185], v0, s[50:51] offset:1024
	global_load_dwordx4 v[186:189], v0, s[50:51] offset:2048
	global_load_dwordx4 v[190:193], v0, s[50:51] offset:3072
	s_add_i32 s46, s40, s4
	s_add_i32 s46, s46, s4
	s_add_i32 s46, s46, s4
	s_cmp_lt_i32 s46, s36
	s_cbranch_scc0 .Lrnp_tail1
	s_sub_u32 s42, s46, 0x8000
	s_cmp_lt_u32 s46, 0x8000
	s_cselect_b32 s42, s46, s42
	s_cselect_b32 s44, s82, s80
	s_cselect_b32 s45, s83, s81
	s_lshl_b32 s42, s42, 12
	s_add_u32 s44, s44, s42
	s_addc_u32 s45, s45, 0
	global_load_dwordx4 v[2:5], v0, s[44:45]
	global_load_dwordx4 v[6:9], v0, s[44:45] offset:1024
	global_load_dwordx4 v[10:13], v0, s[44:45] offset:2048
	global_load_dwordx4 v[14:17], v0, s[44:45] offset:3072
	s_waitcnt vmcnt(48)
	v_mul_f32_e32 v112, v33, v33
	v_mul_f32_e32 v113, v37, v37
	v_mul_f32_e32 v114, v41, v41
	v_mul_f32_e32 v115, v45, v45
	v_fmac_f32_e32 v112, v32, v32
	v_fmac_f32_e32 v113, v36, v36
	v_fmac_f32_e32 v114, v40, v40
	v_fmac_f32_e32 v115, v44, v44
	v_fmac_f32_e32 v112, v34, v34
	v_fmac_f32_e32 v113, v38, v38
	v_fmac_f32_e32 v114, v42, v42
	v_fmac_f32_e32 v115, v46, v46
	v_fmac_f32_e32 v112, v35, v35
	v_fmac_f32_e32 v113, v39, v39
	v_fmac_f32_e32 v114, v43, v43
	v_fmac_f32_e32 v115, v47, v47
	v_add_f32_e32 v112, v112, v113
	v_add_f32_e32 v112, v112, v114
	v_add_f32_e32 v112, v112, v115
	s_nop 1
	v_add_f32_dpp v112, v112, v112 quad_perm:[1,0,3,2] row_mask:0xf bank_mask:0xf bound_ctrl:1
	s_nop 1
	v_add_f32_dpp v112, v112, v112 quad_perm:[2,3,0,1] row_mask:0xf bank_mask:0xf bound_ctrl:1
	s_nop 1
	v_add_f32_dpp v112, v112, v112 row_half_mirror row_mask:0xf bank_mask:0xf bound_ctrl:1
	s_nop 1
	v_add_f32_dpp v112, v112, v112 row_mirror row_mask:0xf bank_mask:0xf bound_ctrl:1
	s_nop 1
	ds_swizzle_b32 v113, v112 offset:swizzle(SWAP,16)
	s_waitcnt lgkmcnt(0)
	v_add_f32_e32 v112, v112, v113
	v_mov_b32_e32 v113, v112
	s_nop 1
	v_permlane32_swap_b32_e32 v112, v113
	v_add_f32_e32 v112, v112, v113
	v_fmamk_f32 v112, v112, 0x3a800000, v224
	v_rsq_f32_e32 v112, v112
	s_waitcnt vmcnt(4)
	v_mul_f32_e32 v32, v32, v112
	v_mul_f32_e32 v33, v33, v112
	v_mul_f32_e32 v34, v34, v112
	v_mul_f32_e32 v35, v35, v112
	v_mul_f32_e32 v36, v36, v112
	v_mul_f32_e32 v37, v37, v112
	v_mul_f32_e32 v38, v38, v112
	v_mul_f32_e32 v39, v39, v112
	v_mul_f32_e32 v40, v40, v112
	v_mul_f32_e32 v41, v41, v112
	v_mul_f32_e32 v42, v42, v112
	v_mul_f32_e32 v43, v43, v112
	v_mul_f32_e32 v44, v44, v112
	v_mul_f32_e32 v45, v45, v112
	v_mul_f32_e32 v46, v46, v112
	v_mul_f32_e32 v47, v47, v112
	v_mul_f32_e32 v32, v80, v32
	v_mul_f32_e32 v33, v81, v33
	v_mul_f32_e32 v34, v82, v34
	v_mul_f32_e32 v35, v83, v35
	v_mul_f32_e32 v36, v84, v36
	v_mul_f32_e32 v37, v85, v37
	v_mul_f32_e32 v38, v86, v38
	v_mul_f32_e32 v39, v87, v39
	v_mul_f32_e32 v40, v88, v40
	v_mul_f32_e32 v41, v89, v41
	v_mul_f32_e32 v42, v90, v42
	v_mul_f32_e32 v43, v91, v43
	v_mul_f32_e32 v44, v92, v44
	v_mul_f32_e32 v45, v93, v45
	v_mul_f32_e32 v46, v94, v46
	v_mul_f32_e32 v47, v95, v47
	v_add_f32_e32 v96, 1.0, v96
	v_add_f32_e32 v97, 1.0, v97
	v_add_f32_e32 v98, 1.0, v98
	v_add_f32_e32 v99, 1.0, v99
	v_add_f32_e32 v100, 1.0, v100
	v_add_f32_e32 v101, 1.0, v101
	v_add_f32_e32 v102, 1.0, v102
	v_add_f32_e32 v103, 1.0, v103
	v_add_f32_e32 v104, 1.0, v104
	v_add_f32_e32 v105, 1.0, v105
	v_add_f32_e32 v106, 1.0, v106
	v_add_f32_e32 v107, 1.0, v107
	v_add_f32_e32 v108, 1.0, v108
	v_add_f32_e32 v109, 1.0, v109
	v_add_f32_e32 v110, 1.0, v110
	v_add_f32_e32 v111, 1.0, v111
	v_fma_f32 v32, v96, v32, v178
	v_fma_f32 v33, v97, v33, v179
	v_fma_f32 v34, v98, v34, v180
	v_fma_f32 v35, v99, v35, v181
	v_fma_f32 v36, v100, v36, v182
	v_fma_f32 v37, v101, v37, v183
	v_fma_f32 v38, v102, v38, v184
	v_fma_f32 v39, v103, v39, v185
	v_fma_f32 v40, v104, v40, v186
	v_fma_f32 v41, v105, v41, v187
	v_fma_f32 v42, v106, v42, v188
	v_fma_f32 v43, v107, v43, v189
	v_fma_f32 v44, v108, v44, v190
	v_fma_f32 v45, v109, v45, v191
	v_fma_f32 v46, v110, v46, v192
	v_fma_f32 v47, v111, v47, v193
	v_cvt_pk_f16_f32 v114, v32, v33
	v_cvt_pk_f16_f32 v115, v34, v35
	v_cvt_pk_f16_f32 v116, v36, v37
	v_cvt_pk_f16_f32 v117, v38, v39
	v_cvt_pk_f16_f32 v118, v40, v41
	v_cvt_pk_f16_f32 v119, v42, v43
	v_cvt_pk_f16_f32 v120, v44, v45
	v_cvt_pk_f16_f32 v121, v46, v47
	global_store_dwordx2 v128, v[114:115], s[54:55]
	global_store_dwordx2 v128, v[116:117], s[54:55] offset:512
	global_store_dwordx2 v128, v[118:119], s[54:55] offset:1024
	global_store_dwordx2 v128, v[120:121], s[54:55] offset:1536
	s_add_i32 s40, s40, s4
; DI void rows_norm_mod(const P& p, const float* xlat, const float* xctx, int l, const float* gain, int sh_idx, int sc_idx,
;                       h16* dst, int nrows) {
;     ...
;   for (int row = gw; row < nrows; row += nw) {
;     const float* xr = row < TL ? xlat + (size_t)row * 1024 : xctx + (size_t)(row - TL) * 1024;
;     const int mrow = row < TL ? (row >> 12) : 8;
;     const float* mr = mod + ((size_t)l * 9 + mrow) * 6144;
;     f32x4 v[4];
;     float ss = 0.f;
; #pragma unroll
;     for (int i = 0; i < 4; ++i) {
;       v[i] = *(const f32x4*)(xr + lane * 4 + 256 * i);
;       ss += v[i].x * v[i].x + v[i].y * v[i].y + v[i].z * v[i].z + v[i].w * v[i].w;
;     }
;     ss = wave_sum(ss);
;     const float rstd = rsqrtf(ss * (1.f / 1024.f) + EPS);
; #pragma unroll
;     for (int i = 0; i < 4; ++i) {
;       const int c = lane * 4 + 256 * i;
;       f32x4 g = *(const f32x4*)(gain + c), sc = *(const f32x4*)(mr + sc_idx * 1024 + c), sh = *(const f32x4*)(mr + sh_idx * 1024 + c);
;       h16x4 o;
;       o.x = (h16)(v[i].x * rstd * g.x * (1.f + sc.x) + sh.x);
;       o.y = (h16)(v[i].y * rstd * g.y * (1.f + sc.y) + sh.y);
;       o.z = (h16)(v[i].z * rstd * g.z * (1.f + sc.z) + sh.z);
;       o.w = (h16)(v[i].w * rstd * g.w * (1.f + sc.w) + sh.w);
;       *(h16x4*)(dst + (size_t)row * 1024 + c) = o;
;     }
;   }
.Lrnp_l2:
	s_lshr_b32 s41, s40, 12
	s_cmp_lt_u32 s40, 0x8000
	s_cselect_b32 s41, s41, 8
	s_mul_i32 s41, s41, 0x6000
	s_add_u32 s50, s56, s41
	s_addc_u32 s51, s57, 0
	s_add_u32 s52, s50, 0x1000
	s_addc_u32 s53, s51, 0
	s_lshl_b32 s41, s40, 11
	s_add_u32 s54, s58, s41
	s_addc_u32 s55, s59, 0
	global_load_dwordx4 v[96:99], v0, s[52:53]
	global_load_dwordx4 v[100:103], v0, s[52:53] offset:1024
	global_load_dwordx4 v[104:107], v0, s[52:53] offset:2048
	global_load_dwordx4 v[108:111], v0, s[52:53] offset:3072
	global_load_dwordx4 v[178:181], v0, s[50:51]
	global_load_dwordx4 v[182:185], v0, s[50:51] offset:1024
	global_load_dwordx4 v[186:189], v0, s[50:51] offset:2048
	global_load_dwordx4 v[190:193], v0, s[50:51] offset:3072
	s_add_i32 s46, s40, s4
	s_add_i32 s46, s46, s4
	s_add_i32 s46, s46, s4
	s_cmp_lt_i32 s46, s36
	s_cbranch_scc0 .Lrnp_tail2
	s_sub_u32 s42, s46, 0x8000
	s_cmp_lt_u32 s46, 0x8000
	s_cselect_b32 s42, s46, s42
	s_cselect_b32 s44, s82, s80
	s_cselect_b32 s45, s83, s81
	s_lshl_b32 s42, s42, 12
	s_add_u32 s44, s44, s42
	s_addc_u32 s45, s45, 0
	global_load_dwordx4 v[32:35], v0, s[44:45]
	global_load_dwordx4 v[36:39], v0, s[44:45] offset:1024
	global_load_dwordx4 v[40:43], v0, s[44:45] offset:2048
	global_load_dwordx4 v[44:47], v0, s[44:45] offset:3072
	s_waitcnt vmcnt(48)
	v_mul_f32_e32 v112, v163, v163
	v_mul_f32_e32 v113, v167, v167
	v_mul_f32_e32 v114, v171, v171
	v_mul_f32_e32 v115, v175, v175
	v_fmac_f32_e32 v112, v162, v162
	v_fmac_f32_e32 v113, v166, v166
	v_fmac_f32_e32 v114, v170, v170
	v_fmac_f32_e32 v115, v174, v174
	v_fmac_f32_e32 v112, v164, v164
	v_fmac_f32_e32 v113, v168, v168
	v_fmac_f32_e32 v114, v172, v172
	v_fmac_f32_e32 v115, v176, v176
	v_fmac_f32_e32 v112, v165, v165
	v_fmac_f32_e32 v113, v169, v169
	v_fmac_f32_e32 v114, v173, v173
	v_fmac_f32_e32 v115, v177, v177
	v_add_f32_e32 v112, v112, v113
	v_add_f32_e32 v112, v112, v114
	v_add_f32_e32 v112, v112, v115
	s_nop 1
	v_add_f32_dpp v112, v112, v112 quad_perm:[1,0,3,2] row_mask:0xf bank_mask:0xf bound_ctrl:1
	s_nop 1
	v_add_f32_dpp v112, v112, v112 quad_perm:[2,3,0,1] row_mask:0xf bank_mask:0xf bound_ctrl:1
	s_nop 1
	v_add_f32_dpp v112, v112, v112 row_half_mirror row_mask:0xf bank_mask:0xf bound_ctrl:1
	s_nop 1
	v_add_f32_dpp v112, v112, v112 row_mirror row_mask:0xf bank_mask:0xf bound_ctrl:1
	s_nop 1
	ds_swizzle_b32 v113, v112 offset:swizzle(SWAP,16)
	s_waitcnt lgkmcnt(0)
	v_add_f32_e32 v112, v112, v113
	v_mov_b32_e32 v113, v112
	s_nop 1
	v_permlane32_swap_b32_e32 v112, v113
	v_add_f32_e32 v112, v112, v113
	v_fmamk_f32 v112, v112, 0x3a800000, v224
	v_rsq_f32_e32 v112, v112
	s_waitcnt vmcnt(4)
	v_mul_f32_e32 v162, v162, v112
	v_mul_f32_e32 v163, v163, v112
	v_mul_f32_e32 v164, v164, v112
	v_mul_f32_e32 v165, v165, v112
	v_mul_f32_e32 v166, v166, v112
	v_mul_f32_e32 v167, v167, v112
	v_mul_f32_e32 v168, v168, v112
	v_mul_f32_e32 v169, v169, v112
	v_mul_f32_e32 v170, v170, v112
	v_mul_f32_e32 v171, v171, v112
	v_mul_f32_e32 v172, v172, v112
	v_mul_f32_e32 v173, v173, v112
	v_mul_f32_e32 v174, v174, v112
	v_mul_f32_e32 v175, v175, v112
	v_mul_f32_e32 v176, v176, v112
	v_mul_f32_e32 v177, v177, v112
	v_mul_f32_e32 v162, v80, v162
	v_mul_f32_e32 v163, v81, v163
	v_mul_f32_e32 v164, v82, v164
	v_mul_f32_e32 v165, v83, v165
	v_mul_f32_e32 v166, v84, v166
	v_mul_f32_e32 v167, v85, v167
	v_mul_f32_e32 v168, v86, v168
	v_mul_f32_e32 v169, v87, v169
	v_mul_f32_e32 v170, v88, v170
	v_mul_f32_e32 v171, v89, v171
	v_mul_f32_e32 v172, v90, v172
	v_mul_f32_e32 v173, v91, v173
	v_mul_f32_e32 v174, v92, v174
	v_mul_f32_e32 v175, v93, v175
	v_mul_f32_e32 v176, v94, v176
	v_mul_f32_e32 v177, v95, v177
	v_add_f32_e32 v96, 1.0, v96
	v_add_f32_e32 v97, 1.0, v97
	v_add_f32_e32 v98, 1.0, v98
	v_add_f32_e32 v99, 1.0, v99
	v_add_f32_e32 v100, 1.0, v100
	v_add_f32_e32 v101, 1.0, v101
	v_add_f32_e32 v102, 1.0, v102
	v_add_f32_e32 v103, 1.0, v103
	v_add_f32_e32 v104, 1.0, v104
	v_add_f32_e32 v105, 1.0, v105
	v_add_f32_e32 v106, 1.0, v106
	v_add_f32_e32 v107, 1.0, v107
	v_add_f32_e32 v108, 1.0, v108
	v_add_f32_e32 v109, 1.0, v109
	v_add_f32_e32 v110, 1.0, v110
	v_add_f32_e32 v111, 1.0, v111
	v_fma_f32 v162, v96, v162, v178
	v_fma_f32 v163, v97, v163, v179
	v_fma_f32 v164, v98, v164, v180
	v_fma_f32 v165, v99, v165, v181
	v_fma_f32 v166, v100, v166, v182
	v_fma_f32 v167, v101, v167, v183
	v_fma_f32 v168, v102, v168, v184
	v_fma_f32 v169, v103, v169, v185
	v_fma_f32 v170, v104, v170, v186
	v_fma_f32 v171, v105, v171, v187
	v_fma_f32 v172, v106, v172, v188
	v_fma_f32 v173, v107, v173, v189
	v_fma_f32 v174, v108, v174, v190
	v_fma_f32 v175, v109, v175, v191
	v_fma_f32 v176, v110, v176, v192
	v_fma_f32 v177, v111, v177, v193
	v_cvt_pk_f16_f32 v114, v162, v163
	v_cvt_pk_f16_f32 v115, v164, v165
	v_cvt_pk_f16_f32 v116, v166, v167
	v_cvt_pk_f16_f32 v117, v168, v169
	v_cvt_pk_f16_f32 v118, v170, v171
	v_cvt_pk_f16_f32 v119, v172, v173
	v_cvt_pk_f16_f32 v120, v174, v175
	v_cvt_pk_f16_f32 v121, v176, v177
	global_store_dwordx2 v128, v[114:115], s[54:55]
	global_store_dwordx2 v128, v[116:117], s[54:55] offset:512
	global_store_dwordx2 v128, v[118:119], s[54:55] offset:1024
	global_store_dwordx2 v128, v[120:121], s[54:55] offset:1536
	s_add_i32 s40, s40, s4
	s_branch .Lrnp_l3
; DI void rows_norm_mod(const P& p, const float* xlat, const float* xctx, int l, const float* gain, int sh_idx, int sc_idx,
;                       h16* dst, int nrows) {
;     ...
;   for (int row = gw; row < nrows; row += nw) {
;     const float* xr = row < TL ? xlat + (size_t)row * 1024 : xctx + (size_t)(row - TL) * 1024;
;     const int mrow = row < TL ? (row >> 12) : 8;
;     const float* mr = mod + ((size_t)l * 9 + mrow) * 6144;
;     f32x4 v[4];
;     float ss = 0.f;
; #pragma unroll
;     for (int i = 0; i < 4; ++i) {
;       v[i] = *(const f32x4*)(xr + lane * 4 + 256 * i);
;       ss += v[i].x * v[i].x + v[i].y * v[i].y + v[i].z * v[i].z + v[i].w * v[i].w;
;     }
;     ss = wave_sum(ss);
;     const float rstd = rsqrtf(ss * (1.f / 1024.f) + EPS);
; #pragma unroll
;     for (int i = 0; i < 4; ++i) {
;       const int c = lane * 4 + 256 * i;
;       f32x4 g = *(const f32x4*)(gain + c), sc = *(const f32x4*)(mr + sc_idx * 1024 + c), sh = *(const f32x4*)(mr + sh_idx * 1024 + c);
;       h16x4 o;
;       o.x = (h16)(v[i].x * rstd * g.x * (1.f + sc.x) + sh.x);
;       o.y = (h16)(v[i].y * rstd * g.y * (1.f + sc.y) + sh.y);
;       o.z = (h16)(v[i].z * rstd * g.z * (1.f + sc.z) + sh.z);
;       o.w = (h16)(v[i].w * rstd * g.w * (1.f + sc.w) + sh.w);
;       *(h16x4*)(dst + (size_t)row * 1024 + c) = o;
;     }
;   }
.Lrnp_tail0:
	s_waitcnt vmcnt(8)
	v_mul_f32_e32 v112, v3, v3
	v_mul_f32_e32 v113, v7, v7
	v_mul_f32_e32 v114, v11, v11
	v_mul_f32_e32 v115, v15, v15
	v_fmac_f32_e32 v112, v2, v2
	v_fmac_f32_e32 v113, v6, v6
	v_fmac_f32_e32 v114, v10, v10
	v_fmac_f32_e32 v115, v14, v14
	v_fmac_f32_e32 v112, v4, v4
	v_fmac_f32_e32 v113, v8, v8
	v_fmac_f32_e32 v114, v12, v12
	v_fmac_f32_e32 v115, v16, v16
	v_fmac_f32_e32 v112, v5, v5
	v_fmac_f32_e32 v113, v9, v9
	v_fmac_f32_e32 v114, v13, v13
	v_fmac_f32_e32 v115, v17, v17
	v_add_f32_e32 v112, v112, v113
	v_add_f32_e32 v112, v112, v114
	v_add_f32_e32 v112, v112, v115
	s_nop 1
	v_add_f32_dpp v112, v112, v112 quad_perm:[1,0,3,2] row_mask:0xf bank_mask:0xf bound_ctrl:1
	s_nop 1
	v_add_f32_dpp v112, v112, v112 quad_perm:[2,3,0,1] row_mask:0xf bank_mask:0xf bound_ctrl:1
	s_nop 1
	v_add_f32_dpp v112, v112, v112 row_half_mirror row_mask:0xf bank_mask:0xf bound_ctrl:1
	s_nop 1
	v_add_f32_dpp v112, v112, v112 row_mirror row_mask:0xf bank_mask:0xf bound_ctrl:1
	s_nop 1
	ds_swizzle_b32 v113, v112 offset:swizzle(SWAP,16)
	s_waitcnt lgkmcnt(0)
	v_add_f32_e32 v112, v112, v113
	v_mov_b32_e32 v113, v112
	s_nop 1
	v_permlane32_swap_b32_e32 v112, v113
	v_add_f32_e32 v112, v112, v113
	v_fmamk_f32 v112, v112, 0x3a800000, v224
	v_rsq_f32_e32 v112, v112
	s_waitcnt vmcnt(0)
	v_mul_f32_e32 v2, v2, v112
	v_mul_f32_e32 v3, v3, v112
	v_mul_f32_e32 v4, v4, v112
	v_mul_f32_e32 v5, v5, v112
	v_mul_f32_e32 v6, v6, v112
	v_mul_f32_e32 v7, v7, v112
	v_mul_f32_e32 v8, v8, v112
	v_mul_f32_e32 v9, v9, v112
	v_mul_f32_e32 v10, v10, v112
	v_mul_f32_e32 v11, v11, v112
	v_mul_f32_e32 v12, v12, v112
	v_mul_f32_e32 v13, v13, v112
	v_mul_f32_e32 v14, v14, v112
	v_mul_f32_e32 v15, v15, v112
	v_mul_f32_e32 v16, v16, v112
	v_mul_f32_e32 v17, v17, v112
	v_mul_f32_e32 v2, v80, v2
	v_mul_f32_e32 v3, v81, v3
	v_mul_f32_e32 v4, v82, v4
	v_mul_f32_e32 v5, v83, v5
	v_mul_f32_e32 v6, v84, v6
	v_mul_f32_e32 v7, v85, v7
	v_mul_f32_e32 v8, v86, v8
	v_mul_f32_e32 v9, v87, v9
	v_mul_f32_e32 v10, v88, v10
	v_mul_f32_e32 v11, v89, v11
	v_mul_f32_e32 v12, v90, v12
	v_mul_f32_e32 v13, v91, v13
	v_mul_f32_e32 v14, v92, v14
	v_mul_f32_e32 v15, v93, v15
	v_mul_f32_e32 v16, v94, v16
	v_mul_f32_e32 v17, v95, v17
	v_add_f32_e32 v96, 1.0, v96
	v_add_f32_e32 v97, 1.0, v97
	v_add_f32_e32 v98, 1.0, v98
	v_add_f32_e32 v99, 1.0, v99
	v_add_f32_e32 v100, 1.0, v100
	v_add_f32_e32 v101, 1.0, v101
	v_add_f32_e32 v102, 1.0, v102
	v_add_f32_e32 v103, 1.0, v103
	v_add_f32_e32 v104, 1.0, v104
	v_add_f32_e32 v105, 1.0, v105
	v_add_f32_e32 v106, 1.0, v106
	v_add_f32_e32 v107, 1.0, v107
	v_add_f32_e32 v108, 1.0, v108
	v_add_f32_e32 v109, 1.0, v109
	v_add_f32_e32 v110, 1.0, v110
	v_add_f32_e32 v111, 1.0, v111
	v_fma_f32 v2, v96, v2, v178
	v_fma_f32 v3, v97, v3, v179
	v_fma_f32 v4, v98, v4, v180
	v_fma_f32 v5, v99, v5, v181
	v_fma_f32 v6, v100, v6, v182
	v_fma_f32 v7, v101, v7, v183
	v_fma_f32 v8, v102, v8, v184
	v_fma_f32 v9, v103, v9, v185
	v_fma_f32 v10, v104, v10, v186
	v_fma_f32 v11, v105, v11, v187
	v_fma_f32 v12, v106, v12, v188
	v_fma_f32 v13, v107, v13, v189
	v_fma_f32 v14, v108, v14, v190
	v_fma_f32 v15, v109, v15, v191
	v_fma_f32 v16, v110, v16, v192
	v_fma_f32 v17, v111, v17, v193
	v_cvt_pk_f16_f32 v114, v2, v3
	v_cvt_pk_f16_f32 v115, v4, v5
	v_cvt_pk_f16_f32 v116, v6, v7
	v_cvt_pk_f16_f32 v117, v8, v9
	v_cvt_pk_f16_f32 v118, v10, v11
	v_cvt_pk_f16_f32 v119, v12, v13
	v_cvt_pk_f16_f32 v120, v14, v15
	v_cvt_pk_f16_f32 v121, v16, v17
	global_store_dwordx2 v128, v[114:115], s[54:55]
	global_store_dwordx2 v128, v[116:117], s[54:55] offset:512
	global_store_dwordx2 v128, v[118:119], s[54:55] offset:1024
	global_store_dwordx2 v128, v[120:121], s[54:55] offset:1536
	s_add_i32 s40, s40, s4
	s_cmp_lt_i32 s40, s36
	s_cbranch_scc0 .Lrnp_exit
	s_lshr_b32 s41, s40, 12
	s_cmp_lt_u32 s40, 0x8000
	s_cselect_b32 s41, s41, 8
	s_mul_i32 s41, s41, 0x6000
	s_add_u32 s50, s56, s41
	s_addc_u32 s51, s57, 0
	s_add_u32 s52, s50, 0x1000
	s_addc_u32 s53, s51, 0
	s_lshl_b32 s41, s40, 11
	s_add_u32 s54, s58, s41
	s_addc_u32 s55, s59, 0
	global_load_dwordx4 v[96:99], v0, s[52:53]
	global_load_dwordx4 v[100:103], v0, s[52:53] offset:1024
	global_load_dwordx4 v[104:107], v0, s[52:53] offset:2048
	global_load_dwordx4 v[108:111], v0, s[52:53] offset:3072
	global_load_dwordx4 v[178:181], v0, s[50:51]
	global_load_dwordx4 v[182:185], v0, s[50:51] offset:1024
	global_load_dwordx4 v[186:189], v0, s[50:51] offset:2048
	global_load_dwordx4 v[190:193], v0, s[50:51] offset:3072
	s_waitcnt vmcnt(8)
	v_mul_f32_e32 v112, v33, v33
	v_mul_f32_e32 v113, v37, v37
	v_mul_f32_e32 v114, v41, v41
	v_mul_f32_e32 v115, v45, v45
	v_fmac_f32_e32 v112, v32, v32
	v_fmac_f32_e32 v113, v36, v36
	v_fmac_f32_e32 v114, v40, v40
	v_fmac_f32_e32 v115, v44, v44
	v_fmac_f32_e32 v112, v34, v34
	v_fmac_f32_e32 v113, v38, v38
	v_fmac_f32_e32 v114, v42, v42
	v_fmac_f32_e32 v115, v46, v46
	v_fmac_f32_e32 v112, v35, v35
	v_fmac_f32_e32 v113, v39, v39
	v_fmac_f32_e32 v114, v43, v43
	v_fmac_f32_e32 v115, v47, v47
	v_add_f32_e32 v112, v112, v113
	v_add_f32_e32 v112, v112, v114
	v_add_f32_e32 v112, v112, v115
	s_nop 1
	v_add_f32_dpp v112, v112, v112 quad_perm:[1,0,3,2] row_mask:0xf bank_mask:0xf bound_ctrl:1
	s_nop 1
	v_add_f32_dpp v112, v112, v112 quad_perm:[2,3,0,1] row_mask:0xf bank_mask:0xf bound_ctrl:1
	s_nop 1
	v_add_f32_dpp v112, v112, v112 row_half_mirror row_mask:0xf bank_mask:0xf bound_ctrl:1
	s_nop 1
	v_add_f32_dpp v112, v112, v112 row_mirror row_mask:0xf bank_mask:0xf bound_ctrl:1
	s_nop 1
	ds_swizzle_b32 v113, v112 offset:swizzle(SWAP,16)
	s_waitcnt lgkmcnt(0)
; DI void rows_norm_mod(const P& p, const float* xlat, const float* xctx, int l, const float* gain, int sh_idx, int sc_idx,
;                       h16* dst, int nrows) {
;     ...
;   for (int row = gw; row < nrows; row += nw) {
;     const float* xr = row < TL ? xlat + (size_t)row * 1024 : xctx + (size_t)(row - TL) * 1024;
;     const int mrow = row < TL ? (row >> 12) : 8;
;     const float* mr = mod + ((size_t)l * 9 + mrow) * 6144;
;     f32x4 v[4];
;     float ss = 0.f;
; #pragma unroll
;     for (int i = 0; i < 4; ++i) {
;       v[i] = *(const f32x4*)(xr + lane * 4 + 256 * i);
;       ss += v[i].x * v[i].x + v[i].y * v[i].y + v[i].z * v[i].z + v[i].w * v[i].w;
;     }
;     ss = wave_sum(ss);
;     const float rstd = rsqrtf(ss * (1.f / 1024.f) + EPS);
; #pragma unroll
;     for (int i = 0; i < 4; ++i) {
;       const int c = lane * 4 + 256 * i;
;       f32x4 g = *(const f32x4*)(gain + c), sc = *(const f32x4*)(mr + sc_idx * 1024 + c), sh = *(const f32x4*)(mr + sh_idx * 1024 + c);
;       h16x4 o;
;       o.x = (h16)(v[i].x * rstd * g.x * (1.f + sc.x) + sh.x);
;       o.y = (h16)(v[i].y * rstd * g.y * (1.f + sc.y) + sh.y);
;       o.z = (h16)(v[i].z * rstd * g.z * (1.f + sc.z) + sh.z);
;       o.w = (h16)(v[i].w * rstd * g.w * (1.f + sc.w) + sh.w);
;       *(h16x4*)(dst + (size_t)row * 1024 + c) = o;
;     }
;   }
	v_add_f32_e32 v112, v112, v113
	v_mov_b32_e32 v113, v112
	s_nop 1
	v_permlane32_swap_b32_e32 v112, v113
	v_add_f32_e32 v112, v112, v113
	v_fmamk_f32 v112, v112, 0x3a800000, v224
	v_rsq_f32_e32 v112, v112
	s_waitcnt vmcnt(0)
	v_mul_f32_e32 v32, v32, v112
	v_mul_f32_e32 v33, v33, v112
	v_mul_f32_e32 v34, v34, v112
	v_mul_f32_e32 v35, v35, v112
	v_mul_f32_e32 v36, v36, v112
	v_mul_f32_e32 v37, v37, v112
	v_mul_f32_e32 v38, v38, v112
	v_mul_f32_e32 v39, v39, v112
	v_mul_f32_e32 v40, v40, v112
	v_mul_f32_e32 v41, v41, v112
	v_mul_f32_e32 v42, v42, v112
	v_mul_f32_e32 v43, v43, v112
	v_mul_f32_e32 v44, v44, v112
	v_mul_f32_e32 v45, v45, v112
	v_mul_f32_e32 v46, v46, v112
	v_mul_f32_e32 v47, v47, v112
	v_mul_f32_e32 v32, v80, v32
	v_mul_f32_e32 v33, v81, v33
	v_mul_f32_e32 v34, v82, v34
	v_mul_f32_e32 v35, v83, v35
	v_mul_f32_e32 v36, v84, v36
	v_mul_f32_e32 v37, v85, v37
	v_mul_f32_e32 v38, v86, v38
	v_mul_f32_e32 v39, v87, v39
	v_mul_f32_e32 v40, v88, v40
	v_mul_f32_e32 v41, v89, v41
	v_mul_f32_e32 v42, v90, v42
	v_mul_f32_e32 v43, v91, v43
	v_mul_f32_e32 v44, v92, v44
	v_mul_f32_e32 v45, v93, v45
	v_mul_f32_e32 v46, v94, v46
	v_mul_f32_e32 v47, v95, v47
	v_add_f32_e32 v96, 1.0, v96
	v_add_f32_e32 v97, 1.0, v97
	v_add_f32_e32 v98, 1.0, v98
	v_add_f32_e32 v99, 1.0, v99
	v_add_f32_e32 v100, 1.0, v100
	v_add_f32_e32 v101, 1.0, v101
	v_add_f32_e32 v102, 1.0, v102
	v_add_f32_e32 v103, 1.0, v103
	v_add_f32_e32 v104, 1.0, v104
	v_add_f32_e32 v105, 1.0, v105
	v_add_f32_e32 v106, 1.0, v106
	v_add_f32_e32 v107, 1.0, v107
	v_add_f32_e32 v108, 1.0, v108
	v_add_f32_e32 v109, 1.0, v109
	v_add_f32_e32 v110, 1.0, v110
	v_add_f32_e32 v111, 1.0, v111
	v_fma_f32 v32, v96, v32, v178
	v_fma_f32 v33, v97, v33, v179
	v_fma_f32 v34, v98, v34, v180
	v_fma_f32 v35, v99, v35, v181
	v_fma_f32 v36, v100, v36, v182
	v_fma_f32 v37, v101, v37, v183
	v_fma_f32 v38, v102, v38, v184
	v_fma_f32 v39, v103, v39, v185
	v_fma_f32 v40, v104, v40, v186
	v_fma_f32 v41, v105, v41, v187
	v_fma_f32 v42, v106, v42, v188
	v_fma_f32 v43, v107, v43, v189
	v_fma_f32 v44, v108, v44, v190
	v_fma_f32 v45, v109, v45, v191
	v_fma_f32 v46, v110, v46, v192
	v_fma_f32 v47, v111, v47, v193
	v_cvt_pk_f16_f32 v114, v32, v33
	v_cvt_pk_f16_f32 v115, v34, v35
	v_cvt_pk_f16_f32 v116, v36, v37
	v_cvt_pk_f16_f32 v117, v38, v39
	v_cvt_pk_f16_f32 v118, v40, v41
	v_cvt_pk_f16_f32 v119, v42, v43
	v_cvt_pk_f16_f32 v120, v44, v45
	v_cvt_pk_f16_f32 v121, v46, v47
	global_store_dwordx2 v128, v[114:115], s[54:55]
	global_store_dwordx2 v128, v[116:117], s[54:55] offset:512
	global_store_dwordx2 v128, v[118:119], s[54:55] offset:1024
	global_store_dwordx2 v128, v[120:121], s[54:55] offset:1536
	s_add_i32 s40, s40, s4
	s_cmp_lt_i32 s40, s36
	s_cbranch_scc0 .Lrnp_exit
	s_lshr_b32 s41, s40, 12
	s_cmp_lt_u32 s40, 0x8000
	s_cselect_b32 s41, s41, 8
	s_mul_i32 s41, s41, 0x6000
	s_add_u32 s50, s56, s41
	s_addc_u32 s51, s57, 0
	s_add_u32 s52, s50, 0x1000
	s_addc_u32 s53, s51, 0
	s_lshl_b32 s41, s40, 11
	s_add_u32 s54, s58, s41
	s_addc_u32 s55, s59, 0
	global_load_dwordx4 v[96:99], v0, s[52:53]
	global_load_dwordx4 v[100:103], v0, s[52:53] offset:1024
	global_load_dwordx4 v[104:107], v0, s[52:53] offset:2048
	global_load_dwordx4 v[108:111], v0, s[52:53] offset:3072
	global_load_dwordx4 v[178:181], v0, s[50:51]
	global_load_dwordx4 v[182:185], v0, s[50:51] offset:1024
	global_load_dwordx4 v[186:189], v0, s[50:51] offset:2048
	global_load_dwordx4 v[190:193], v0, s[50:51] offset:3072
	s_waitcnt vmcnt(8)
	v_mul_f32_e32 v112, v163, v163
	v_mul_f32_e32 v113, v167, v167
	v_mul_f32_e32 v114, v171, v171
	v_mul_f32_e32 v115, v175, v175
	v_fmac_f32_e32 v112, v162, v162
	v_fmac_f32_e32 v113, v166, v166
	v_fmac_f32_e32 v114, v170, v170
	v_fmac_f32_e32 v115, v174, v174
	v_fmac_f32_e32 v112, v164, v164
	v_fmac_f32_e32 v113, v168, v168
	v_fmac_f32_e32 v114, v172, v172
	v_fmac_f32_e32 v115, v176, v176
	v_fmac_f32_e32 v112, v165, v165
	v_fmac_f32_e32 v113, v169, v169
	v_fmac_f32_e32 v114, v173, v173
	v_fmac_f32_e32 v115, v177, v177
	v_add_f32_e32 v112, v112, v113
	v_add_f32_e32 v112, v112, v114
	v_add_f32_e32 v112, v112, v115
	s_nop 1
	v_add_f32_dpp v112, v112, v112 quad_perm:[1,0,3,2] row_mask:0xf bank_mask:0xf bound_ctrl:1
	s_nop 1
	v_add_f32_dpp v112, v112, v112 quad_perm:[2,3,0,1] row_mask:0xf bank_mask:0xf bound_ctrl:1
	s_nop 1
	v_add_f32_dpp v112, v112, v112 row_half_mirror row_mask:0xf bank_mask:0xf bound_ctrl:1
	s_nop 1
	v_add_f32_dpp v112, v112, v112 row_mirror row_mask:0xf bank_mask:0xf bound_ctrl:1
	s_nop 1
	ds_swizzle_b32 v113, v112 offset:swizzle(SWAP,16)
	s_waitcnt lgkmcnt(0)
	v_add_f32_e32 v112, v112, v113
	v_mov_b32_e32 v113, v112
	s_nop 1
	v_permlane32_swap_b32_e32 v112, v113
	v_add_f32_e32 v112, v112, v113
	v_fmamk_f32 v112, v112, 0x3a800000, v224
	v_rsq_f32_e32 v112, v112
	s_waitcnt vmcnt(0)
; DI void rows_norm_mod(const P& p, const float* xlat, const float* xctx, int l, const float* gain, int sh_idx, int sc_idx,
;                       h16* dst, int nrows) {
;     ...
;   for (int row = gw; row < nrows; row += nw) {
;     const float* xr = row < TL ? xlat + (size_t)row * 1024 : xctx + (size_t)(row - TL) * 1024;
;     const int mrow = row < TL ? (row >> 12) : 8;
;     const float* mr = mod + ((size_t)l * 9 + mrow) * 6144;
;     f32x4 v[4];
;     float ss = 0.f;
; #pragma unroll
;     for (int i = 0; i < 4; ++i) {
;       v[i] = *(const f32x4*)(xr + lane * 4 + 256 * i);
;       ss += v[i].x * v[i].x + v[i].y * v[i].y + v[i].z * v[i].z + v[i].w * v[i].w;
;     }
;     ss = wave_sum(ss);
;     const float rstd = rsqrtf(ss * (1.f / 1024.f) + EPS);
; #pragma unroll
;     for (int i = 0; i < 4; ++i) {
;       const int c = lane * 4 + 256 * i;
;       f32x4 g = *(const f32x4*)(gain + c), sc = *(const f32x4*)(mr + sc_idx * 1024 + c), sh = *(const f32x4*)(mr + sh_idx * 1024 + c);
;       h16x4 o;
;       o.x = (h16)(v[i].x * rstd * g.x * (1.f + sc.x) + sh.x);
;       o.y = (h16)(v[i].y * rstd * g.y * (1.f + sc.y) + sh.y);
;       o.z = (h16)(v[i].z * rstd * g.z * (1.f + sc.z) + sh.z);
;       o.w = (h16)(v[i].w * rstd * g.w * (1.f + sc.w) + sh.w);
;       *(h16x4*)(dst + (size_t)row * 1024 + c) = o;
;     }
;   }
	v_mul_f32_e32 v162, v162, v112
	v_mul_f32_e32 v163, v163, v112
	v_mul_f32_e32 v164, v164, v112
	v_mul_f32_e32 v165, v165, v112
	v_mul_f32_e32 v166, v166, v112
	v_mul_f32_e32 v167, v167, v112
	v_mul_f32_e32 v168, v168, v112
	v_mul_f32_e32 v169, v169, v112
	v_mul_f32_e32 v170, v170, v112
	v_mul_f32_e32 v171, v171, v112
	v_mul_f32_e32 v172, v172, v112
	v_mul_f32_e32 v173, v173, v112
	v_mul_f32_e32 v174, v174, v112
	v_mul_f32_e32 v175, v175, v112
	v_mul_f32_e32 v176, v176, v112
	v_mul_f32_e32 v177, v177, v112
	v_mul_f32_e32 v162, v80, v162
	v_mul_f32_e32 v163, v81, v163
	v_mul_f32_e32 v164, v82, v164
	v_mul_f32_e32 v165, v83, v165
	v_mul_f32_e32 v166, v84, v166
	v_mul_f32_e32 v167, v85, v167
	v_mul_f32_e32 v168, v86, v168
	v_mul_f32_e32 v169, v87, v169
	v_mul_f32_e32 v170, v88, v170
	v_mul_f32_e32 v171, v89, v171
	v_mul_f32_e32 v172, v90, v172
	v_mul_f32_e32 v173, v91, v173
	v_mul_f32_e32 v174, v92, v174
	v_mul_f32_e32 v175, v93, v175
	v_mul_f32_e32 v176, v94, v176
	v_mul_f32_e32 v177, v95, v177
	v_add_f32_e32 v96, 1.0, v96
	v_add_f32_e32 v97, 1.0, v97
	v_add_f32_e32 v98, 1.0, v98
	v_add_f32_e32 v99, 1.0, v99
	v_add_f32_e32 v100, 1.0, v100
	v_add_f32_e32 v101, 1.0, v101
	v_add_f32_e32 v102, 1.0, v102
	v_add_f32_e32 v103, 1.0, v103
	v_add_f32_e32 v104, 1.0, v104
	v_add_f32_e32 v105, 1.0, v105
	v_add_f32_e32 v106, 1.0, v106
	v_add_f32_e32 v107, 1.0, v107
	v_add_f32_e32 v108, 1.0, v108
	v_add_f32_e32 v109, 1.0, v109
	v_add_f32_e32 v110, 1.0, v110
	v_add_f32_e32 v111, 1.0, v111
	v_fma_f32 v162, v96, v162, v178
	v_fma_f32 v163, v97, v163, v179
	v_fma_f32 v164, v98, v164, v180
	v_fma_f32 v165, v99, v165, v181
	v_fma_f32 v166, v100, v166, v182
	v_fma_f32 v167, v101, v167, v183
	v_fma_f32 v168, v102, v168, v184
	v_fma_f32 v169, v103, v169, v185
	v_fma_f32 v170, v104, v170, v186
	v_fma_f32 v171, v105, v171, v187
	v_fma_f32 v172, v106, v172, v188
	v_fma_f32 v173, v107, v173, v189
	v_fma_f32 v174, v108, v174, v190
	v_fma_f32 v175, v109, v175, v191
	v_fma_f32 v176, v110, v176, v192
	v_fma_f32 v177, v111, v177, v193
	v_cvt_pk_f16_f32 v114, v162, v163
	v_cvt_pk_f16_f32 v115, v164, v165
	v_cvt_pk_f16_f32 v116, v166, v167
	v_cvt_pk_f16_f32 v117, v168, v169
	v_cvt_pk_f16_f32 v118, v170, v171
	v_cvt_pk_f16_f32 v119, v172, v173
	v_cvt_pk_f16_f32 v120, v174, v175
	v_cvt_pk_f16_f32 v121, v176, v177
	global_store_dwordx2 v128, v[114:115], s[54:55]
	global_store_dwordx2 v128, v[116:117], s[54:55] offset:512
	global_store_dwordx2 v128, v[118:119], s[54:55] offset:1024
	global_store_dwordx2 v128, v[120:121], s[54:55] offset:1536
	s_add_i32 s40, s40, s4
	s_branch .Lrnp_exit
.Lrnp_tail1:
	s_waitcnt vmcnt(8)
	v_mul_f32_e32 v112, v33, v33
	v_mul_f32_e32 v113, v37, v37
	v_mul_f32_e32 v114, v41, v41
	v_mul_f32_e32 v115, v45, v45
	v_fmac_f32_e32 v112, v32, v32
	v_fmac_f32_e32 v113, v36, v36
	v_fmac_f32_e32 v114, v40, v40
	v_fmac_f32_e32 v115, v44, v44
	v_fmac_f32_e32 v112, v34, v34
	v_fmac_f32_e32 v113, v38, v38
	v_fmac_f32_e32 v114, v42, v42
	v_fmac_f32_e32 v115, v46, v46
	v_fmac_f32_e32 v112, v35, v35
	v_fmac_f32_e32 v113, v39, v39
	v_fmac_f32_e32 v114, v43, v43
	v_fmac_f32_e32 v115, v47, v47
	v_add_f32_e32 v112, v112, v113
	v_add_f32_e32 v112, v112, v114
	v_add_f32_e32 v112, v112, v115
	s_nop 1
	v_add_f32_dpp v112, v112, v112 quad_perm:[1,0,3,2] row_mask:0xf bank_mask:0xf bound_ctrl:1
	s_nop 1
	v_add_f32_dpp v112, v112, v112 quad_perm:[2,3,0,1] row_mask:0xf bank_mask:0xf bound_ctrl:1
	s_nop 1
	v_add_f32_dpp v112, v112, v112 row_half_mirror row_mask:0xf bank_mask:0xf bound_ctrl:1
	s_nop 1
	v_add_f32_dpp v112, v112, v112 row_mirror row_mask:0xf bank_mask:0xf bound_ctrl:1
	s_nop 1
	ds_swizzle_b32 v113, v112 offset:swizzle(SWAP,16)
	s_waitcnt lgkmcnt(0)
	v_add_f32_e32 v112, v112, v113
	v_mov_b32_e32 v113, v112
	s_nop 1
	v_permlane32_swap_b32_e32 v112, v113
	v_add_f32_e32 v112, v112, v113
	v_fmamk_f32 v112, v112, 0x3a800000, v224
	v_rsq_f32_e32 v112, v112
	s_waitcnt vmcnt(0)
	v_mul_f32_e32 v32, v32, v112
	v_mul_f32_e32 v33, v33, v112
	v_mul_f32_e32 v34, v34, v112
	v_mul_f32_e32 v35, v35, v112
	v_mul_f32_e32 v36, v36, v112
	v_mul_f32_e32 v37, v37, v112
	v_mul_f32_e32 v38, v38, v112
	v_mul_f32_e32 v39, v39, v112
	v_mul_f32_e32 v40, v40, v112
	v_mul_f32_e32 v41, v41, v112
	v_mul_f32_e32 v42, v42, v112
	v_mul_f32_e32 v43, v43, v112
	v_mul_f32_e32 v44, v44, v112
	v_mul_f32_e32 v45, v45, v112
	v_mul_f32_e32 v46, v46, v112
	v_mul_f32_e32 v47, v47, v112
	v_mul_f32_e32 v32, v80, v32
	v_mul_f32_e32 v33, v81, v33
	v_mul_f32_e32 v34, v82, v34
	v_mul_f32_e32 v35, v83, v35
	v_mul_f32_e32 v36, v84, v36
	v_mul_f32_e32 v37, v85, v37
	v_mul_f32_e32 v38, v86, v38
	v_mul_f32_e32 v39, v87, v39
	v_mul_f32_e32 v40, v88, v40
	v_mul_f32_e32 v41, v89, v41
	v_mul_f32_e32 v42, v90, v42
	v_mul_f32_e32 v43, v91, v43
	v_mul_f32_e32 v44, v92, v44
	v_mul_f32_e32 v45, v93, v45
	v_mul_f32_e32 v46, v94, v46
	v_mul_f32_e32 v47, v95, v47
	v_add_f32_e32 v96, 1.0, v96
	v_add_f32_e32 v97, 1.0, v97
	v_add_f32_e32 v98, 1.0, v98
	v_add_f32_e32 v99, 1.0, v99
	v_add_f32_e32 v100, 1.0, v100
	v_add_f32_e32 v101, 1.0, v101
	v_add_f32_e32 v102, 1.0, v102
	v_add_f32_e32 v103, 1.0, v103
	v_add_f32_e32 v104, 1.0, v104
	v_add_f32_e32 v105, 1.0, v105
	v_add_f32_e32 v106, 1.0, v106
	v_add_f32_e32 v107, 1.0, v107
	v_add_f32_e32 v108, 1.0, v108
	v_add_f32_e32 v109, 1.0, v109
	v_add_f32_e32 v110, 1.0, v110
	v_add_f32_e32 v111, 1.0, v111
	v_fma_f32 v32, v96, v32, v178
	v_fma_f32 v33, v97, v33, v179
	v_fma_f32 v34, v98, v34, v180
	v_fma_f32 v35, v99, v35, v181
	v_fma_f32 v36, v100, v36, v182
	v_fma_f32 v37, v101, v37, v183
	v_fma_f32 v38, v102, v38, v184
	v_fma_f32 v39, v103, v39, v185
	v_fma_f32 v40, v104, v40, v186
	v_fma_f32 v41, v105, v41, v187
	v_fma_f32 v42, v106, v42, v188
	v_fma_f32 v43, v107, v43, v189
	v_fma_f32 v44, v108, v44, v190
	v_fma_f32 v45, v109, v45, v191
	v_fma_f32 v46, v110, v46, v192
	v_fma_f32 v47, v111, v47, v193
	v_cvt_pk_f16_f32 v114, v32, v33
	v_cvt_pk_f16_f32 v115, v34, v35
	v_cvt_pk_f16_f32 v116, v36, v37
	v_cvt_pk_f16_f32 v117, v38, v39
	v_cvt_pk_f16_f32 v118, v40, v41
	v_cvt_pk_f16_f32 v119, v42, v43
	v_cvt_pk_f16_f32 v120, v44, v45
	v_cvt_pk_f16_f32 v121, v46, v47
	global_store_dwordx2 v128, v[114:115], s[54:55]
	global_store_dwordx2 v128, v[116:117], s[54:55] offset:512
	global_store_dwordx2 v128, v[118:119], s[54:55] offset:1024
	global_store_dwordx2 v128, v[120:121], s[54:55] offset:1536
	s_add_i32 s40, s40, s4
	s_cmp_lt_i32 s40, s36
	s_cbranch_scc0 .Lrnp_exit
; DI void rows_norm_mod(const P& p, const float* xlat, const float* xctx, int l, const float* gain, int sh_idx, int sc_idx,
;                       h16* dst, int nrows) {
;     ...
;   for (int row = gw; row < nrows; row += nw) {
;     const float* xr = row < TL ? xlat + (size_t)row * 1024 : xctx + (size_t)(row - TL) * 1024;
;     const int mrow = row < TL ? (row >> 12) : 8;
;     const float* mr = mod + ((size_t)l * 9 + mrow) * 6144;
;     f32x4 v[4];
;     float ss = 0.f;
; #pragma unroll
;     for (int i = 0; i < 4; ++i) {
;       v[i] = *(const f32x4*)(xr + lane * 4 + 256 * i);
;       ss += v[i].x * v[i].x + v[i].y * v[i].y + v[i].z * v[i].z + v[i].w * v[i].w;
;     }
;     ss = wave_sum(ss);
;     const float rstd = rsqrtf(ss * (1.f / 1024.f) + EPS);
; #pragma unroll
;     for (int i = 0; i < 4; ++i) {
;       const int c = lane * 4 + 256 * i;
;       f32x4 g = *(const f32x4*)(gain + c), sc = *(const f32x4*)(mr + sc_idx * 1024 + c), sh = *(const f32x4*)(mr + sh_idx * 1024 + c);
;       h16x4 o;
;       o.x = (h16)(v[i].x * rstd * g.x * (1.f + sc.x) + sh.x);
;       o.y = (h16)(v[i].y * rstd * g.y * (1.f + sc.y) + sh.y);
;       o.z = (h16)(v[i].z * rstd * g.z * (1.f + sc.z) + sh.z);
;       o.w = (h16)(v[i].w * rstd * g.w * (1.f + sc.w) + sh.w);
;       *(h16x4*)(dst + (size_t)row * 1024 + c) = o;
;     }
;   }
	s_lshr_b32 s41, s40, 12
	s_cmp_lt_u32 s40, 0x8000
	s_cselect_b32 s41, s41, 8
	s_mul_i32 s41, s41, 0x6000
	s_add_u32 s50, s56, s41
	s_addc_u32 s51, s57, 0
	s_add_u32 s52, s50, 0x1000
	s_addc_u32 s53, s51, 0
	s_lshl_b32 s41, s40, 11
	s_add_u32 s54, s58, s41
	s_addc_u32 s55, s59, 0
	global_load_dwordx4 v[96:99], v0, s[52:53]
	global_load_dwordx4 v[100:103], v0, s[52:53] offset:1024
	global_load_dwordx4 v[104:107], v0, s[52:53] offset:2048
	global_load_dwordx4 v[108:111], v0, s[52:53] offset:3072
	global_load_dwordx4 v[178:181], v0, s[50:51]
	global_load_dwordx4 v[182:185], v0, s[50:51] offset:1024
	global_load_dwordx4 v[186:189], v0, s[50:51] offset:2048
	global_load_dwordx4 v[190:193], v0, s[50:51] offset:3072
	s_waitcnt vmcnt(8)
	v_mul_f32_e32 v112, v163, v163
	v_mul_f32_e32 v113, v167, v167
	v_mul_f32_e32 v114, v171, v171
	v_mul_f32_e32 v115, v175, v175
	v_fmac_f32_e32 v112, v162, v162
	v_fmac_f32_e32 v113, v166, v166
	v_fmac_f32_e32 v114, v170, v170
	v_fmac_f32_e32 v115, v174, v174
	v_fmac_f32_e32 v112, v164, v164
	v_fmac_f32_e32 v113, v168, v168
	v_fmac_f32_e32 v114, v172, v172
	v_fmac_f32_e32 v115, v176, v176
	v_fmac_f32_e32 v112, v165, v165
	v_fmac_f32_e32 v113, v169, v169
	v_fmac_f32_e32 v114, v173, v173
	v_fmac_f32_e32 v115, v177, v177
	v_add_f32_e32 v112, v112, v113
	v_add_f32_e32 v112, v112, v114
	v_add_f32_e32 v112, v112, v115
	s_nop 1
	v_add_f32_dpp v112, v112, v112 quad_perm:[1,0,3,2] row_mask:0xf bank_mask:0xf bound_ctrl:1
	s_nop 1
	v_add_f32_dpp v112, v112, v112 quad_perm:[2,3,0,1] row_mask:0xf bank_mask:0xf bound_ctrl:1
	s_nop 1
	v_add_f32_dpp v112, v112, v112 row_half_mirror row_mask:0xf bank_mask:0xf bound_ctrl:1
	s_nop 1
	v_add_f32_dpp v112, v112, v112 row_mirror row_mask:0xf bank_mask:0xf bound_ctrl:1
	s_nop 1
	ds_swizzle_b32 v113, v112 offset:swizzle(SWAP,16)
	s_waitcnt lgkmcnt(0)
	v_add_f32_e32 v112, v112, v113
	v_mov_b32_e32 v113, v112
	s_nop 1
	v_permlane32_swap_b32_e32 v112, v113
	v_add_f32_e32 v112, v112, v113
	v_fmamk_f32 v112, v112, 0x3a800000, v224
	v_rsq_f32_e32 v112, v112
	s_waitcnt vmcnt(0)
	v_mul_f32_e32 v162, v162, v112
	v_mul_f32_e32 v163, v163, v112
	v_mul_f32_e32 v164, v164, v112
	v_mul_f32_e32 v165, v165, v112
	v_mul_f32_e32 v166, v166, v112
	v_mul_f32_e32 v167, v167, v112
	v_mul_f32_e32 v168, v168, v112
	v_mul_f32_e32 v169, v169, v112
	v_mul_f32_e32 v170, v170, v112
	v_mul_f32_e32 v171, v171, v112
	v_mul_f32_e32 v172, v172, v112
	v_mul_f32_e32 v173, v173, v112
	v_mul_f32_e32 v174, v174, v112
	v_mul_f32_e32 v175, v175, v112
	v_mul_f32_e32 v176, v176, v112
	v_mul_f32_e32 v177, v177, v112
	v_mul_f32_e32 v162, v80, v162
	v_mul_f32_e32 v163, v81, v163
	v_mul_f32_e32 v164, v82, v164
	v_mul_f32_e32 v165, v83, v165
	v_mul_f32_e32 v166, v84, v166
	v_mul_f32_e32 v167, v85, v167
	v_mul_f32_e32 v168, v86, v168
	v_mul_f32_e32 v169, v87, v169
	v_mul_f32_e32 v170, v88, v170
	v_mul_f32_e32 v171, v89, v171
	v_mul_f32_e32 v172, v90, v172
	v_mul_f32_e32 v173, v91, v173
	v_mul_f32_e32 v174, v92, v174
	v_mul_f32_e32 v175, v93, v175
	v_mul_f32_e32 v176, v94, v176
	v_mul_f32_e32 v177, v95, v177
	v_add_f32_e32 v96, 1.0, v96
	v_add_f32_e32 v97, 1.0, v97
	v_add_f32_e32 v98, 1.0, v98
	v_add_f32_e32 v99, 1.0, v99
	v_add_f32_e32 v100, 1.0, v100
	v_add_f32_e32 v101, 1.0, v101
	v_add_f32_e32 v102, 1.0, v102
	v_add_f32_e32 v103, 1.0, v103
	v_add_f32_e32 v104, 1.0, v104
	v_add_f32_e32 v105, 1.0, v105
	v_add_f32_e32 v106, 1.0, v106
	v_add_f32_e32 v107, 1.0, v107
	v_add_f32_e32 v108, 1.0, v108
	v_add_f32_e32 v109, 1.0, v109
	v_add_f32_e32 v110, 1.0, v110
	v_add_f32_e32 v111, 1.0, v111
	v_fma_f32 v162, v96, v162, v178
	v_fma_f32 v163, v97, v163, v179
	v_fma_f32 v164, v98, v164, v180
	v_fma_f32 v165, v99, v165, v181
	v_fma_f32 v166, v100, v166, v182
	v_fma_f32 v167, v101, v167, v183
	v_fma_f32 v168, v102, v168, v184
	v_fma_f32 v169, v103, v169, v185
	v_fma_f32 v170, v104, v170, v186
	v_fma_f32 v171, v105, v171, v187
	v_fma_f32 v172, v106, v172, v188
	v_fma_f32 v173, v107, v173, v189
	v_fma_f32 v174, v108, v174, v190
	v_fma_f32 v175, v109, v175, v191
	v_fma_f32 v176, v110, v176, v192
	v_fma_f32 v177, v111, v177, v193
	v_cvt_pk_f16_f32 v114, v162, v163
	v_cvt_pk_f16_f32 v115, v164, v165
	v_cvt_pk_f16_f32 v116, v166, v167
	v_cvt_pk_f16_f32 v117, v168, v169
	v_cvt_pk_f16_f32 v118, v170, v171
	v_cvt_pk_f16_f32 v119, v172, v173
	v_cvt_pk_f16_f32 v120, v174, v175
	v_cvt_pk_f16_f32 v121, v176, v177
	global_store_dwordx2 v128, v[114:115], s[54:55]
	global_store_dwordx2 v128, v[116:117], s[54:55] offset:512
	global_store_dwordx2 v128, v[118:119], s[54:55] offset:1024
	global_store_dwordx2 v128, v[120:121], s[54:55] offset:1536
	s_add_i32 s40, s40, s4
	s_cmp_lt_i32 s40, s36
	s_cbranch_scc0 .Lrnp_exit
; DI void rows_norm_mod(const P& p, const float* xlat, const float* xctx, int l, const float* gain, int sh_idx, int sc_idx,
;                       h16* dst, int nrows) {
;     ...
;   for (int row = gw; row < nrows; row += nw) {
;     const float* xr = row < TL ? xlat + (size_t)row * 1024 : xctx + (size_t)(row - TL) * 1024;
;     const int mrow = row < TL ? (row >> 12) : 8;
;     const float* mr = mod + ((size_t)l * 9 + mrow) * 6144;
;     f32x4 v[4];
;     float ss = 0.f;
; #pragma unroll
;     for (int i = 0; i < 4; ++i) {
;       v[i] = *(const f32x4*)(xr + lane * 4 + 256 * i);
;       ss += v[i].x * v[i].x + v[i].y * v[i].y + v[i].z * v[i].z + v[i].w * v[i].w;
;     }
;     ss = wave_sum(ss);
;     const float rstd = rsqrtf(ss * (1.f / 1024.f) + EPS);
; #pragma unroll
;     for (int i = 0; i < 4; ++i) {
;       const int c = lane * 4 + 256 * i;
;       f32x4 g = *(const f32x4*)(gain + c), sc = *(const f32x4*)(mr + sc_idx * 1024 + c), sh = *(const f32x4*)(mr + sh_idx * 1024 + c);
;       h16x4 o;
;       o.x = (h16)(v[i].x * rstd * g.x * (1.f + sc.x) + sh.x);
;       o.y = (h16)(v[i].y * rstd * g.y * (1.f + sc.y) + sh.y);
;       o.z = (h16)(v[i].z * rstd * g.z * (1.f + sc.z) + sh.z);
;       o.w = (h16)(v[i].w * rstd * g.w * (1.f + sc.w) + sh.w);
;       *(h16x4*)(dst + (size_t)row * 1024 + c) = o;
;     }
;   }
	s_lshr_b32 s41, s40, 12
	s_cmp_lt_u32 s40, 0x8000
	s_cselect_b32 s41, s41, 8
	s_mul_i32 s41, s41, 0x6000
	s_add_u32 s50, s56, s41
	s_addc_u32 s51, s57, 0
	s_add_u32 s52, s50, 0x1000
	s_addc_u32 s53, s51, 0
	s_lshl_b32 s41, s40, 11
	s_add_u32 s54, s58, s41
	s_addc_u32 s55, s59, 0
	global_load_dwordx4 v[96:99], v0, s[52:53]
	global_load_dwordx4 v[100:103], v0, s[52:53] offset:1024
	global_load_dwordx4 v[104:107], v0, s[52:53] offset:2048
	global_load_dwordx4 v[108:111], v0, s[52:53] offset:3072
	global_load_dwordx4 v[178:181], v0, s[50:51]
	global_load_dwordx4 v[182:185], v0, s[50:51] offset:1024
	global_load_dwordx4 v[186:189], v0, s[50:51] offset:2048
	global_load_dwordx4 v[190:193], v0, s[50:51] offset:3072
	s_waitcnt vmcnt(8)
	v_mul_f32_e32 v112, v205, v205
	v_mul_f32_e32 v113, v209, v209
	v_mul_f32_e32 v114, v213, v213
	v_mul_f32_e32 v115, v217, v217
	v_fmac_f32_e32 v112, v204, v204
	v_fmac_f32_e32 v113, v208, v208
	v_fmac_f32_e32 v114, v212, v212
	v_fmac_f32_e32 v115, v216, v216
	v_fmac_f32_e32 v112, v206, v206
	v_fmac_f32_e32 v113, v210, v210
	v_fmac_f32_e32 v114, v214, v214
	v_fmac_f32_e32 v115, v218, v218
	v_fmac_f32_e32 v112, v207, v207
	v_fmac_f32_e32 v113, v211, v211
	v_fmac_f32_e32 v114, v215, v215
	v_fmac_f32_e32 v115, v219, v219
	v_add_f32_e32 v112, v112, v113
	v_add_f32_e32 v112, v112, v114
	v_add_f32_e32 v112, v112, v115
	s_nop 1
	v_add_f32_dpp v112, v112, v112 quad_perm:[1,0,3,2] row_mask:0xf bank_mask:0xf bound_ctrl:1
	s_nop 1
	v_add_f32_dpp v112, v112, v112 quad_perm:[2,3,0,1] row_mask:0xf bank_mask:0xf bound_ctrl:1
	s_nop 1
	v_add_f32_dpp v112, v112, v112 row_half_mirror row_mask:0xf bank_mask:0xf bound_ctrl:1
	s_nop 1
	v_add_f32_dpp v112, v112, v112 row_mirror row_mask:0xf bank_mask:0xf bound_ctrl:1
	s_nop 1
	ds_swizzle_b32 v113, v112 offset:swizzle(SWAP,16)
	s_waitcnt lgkmcnt(0)
	v_add_f32_e32 v112, v112, v113
	v_mov_b32_e32 v113, v112
	s_nop 1
	v_permlane32_swap_b32_e32 v112, v113
	v_add_f32_e32 v112, v112, v113
	v_fmamk_f32 v112, v112, 0x3a800000, v224
	v_rsq_f32_e32 v112, v112
	s_waitcnt vmcnt(0)
	v_mul_f32_e32 v204, v204, v112
	v_mul_f32_e32 v205, v205, v112
	v_mul_f32_e32 v206, v206, v112
	v_mul_f32_e32 v207, v207, v112
	v_mul_f32_e32 v208, v208, v112
	v_mul_f32_e32 v209, v209, v112
	v_mul_f32_e32 v210, v210, v112
	v_mul_f32_e32 v211, v211, v112
	v_mul_f32_e32 v212, v212, v112
	v_mul_f32_e32 v213, v213, v112
	v_mul_f32_e32 v214, v214, v112
	v_mul_f32_e32 v215, v215, v112
	v_mul_f32_e32 v216, v216, v112
	v_mul_f32_e32 v217, v217, v112
	v_mul_f32_e32 v218, v218, v112
	v_mul_f32_e32 v219, v219, v112
	v_mul_f32_e32 v204, v80, v204
	v_mul_f32_e32 v205, v81, v205
	v_mul_f32_e32 v206, v82, v206
	v_mul_f32_e32 v207, v83, v207
	v_mul_f32_e32 v208, v84, v208
	v_mul_f32_e32 v209, v85, v209
	v_mul_f32_e32 v210, v86, v210
	v_mul_f32_e32 v211, v87, v211
	v_mul_f32_e32 v212, v88, v212
	v_mul_f32_e32 v213, v89, v213
	v_mul_f32_e32 v214, v90, v214
	v_mul_f32_e32 v215, v91, v215
	v_mul_f32_e32 v216, v92, v216
	v_mul_f32_e32 v217, v93, v217
	v_mul_f32_e32 v218, v94, v218
	v_mul_f32_e32 v219, v95, v219
	v_add_f32_e32 v96, 1.0, v96
	v_add_f32_e32 v97, 1.0, v97
	v_add_f32_e32 v98, 1.0, v98
	v_add_f32_e32 v99, 1.0, v99
	v_add_f32_e32 v100, 1.0, v100
	v_add_f32_e32 v101, 1.0, v101
	v_add_f32_e32 v102, 1.0, v102
	v_add_f32_e32 v103, 1.0, v103
	v_add_f32_e32 v104, 1.0, v104
	v_add_f32_e32 v105, 1.0, v105
	v_add_f32_e32 v106, 1.0, v106
	v_add_f32_e32 v107, 1.0, v107
	v_add_f32_e32 v108, 1.0, v108
	v_add_f32_e32 v109, 1.0, v109
	v_add_f32_e32 v110, 1.0, v110
	v_add_f32_e32 v111, 1.0, v111
	v_fma_f32 v204, v96, v204, v178
	v_fma_f32 v205, v97, v205, v179
	v_fma_f32 v206, v98, v206, v180
	v_fma_f32 v207, v99, v207, v181
	v_fma_f32 v208, v100, v208, v182
	v_fma_f32 v209, v101, v209, v183
	v_fma_f32 v210, v102, v210, v184
	v_fma_f32 v211, v103, v211, v185
	v_fma_f32 v212, v104, v212, v186
	v_fma_f32 v213, v105, v213, v187
	v_fma_f32 v214, v106, v214, v188
	v_fma_f32 v215, v107, v215, v189
	v_fma_f32 v216, v108, v216, v190
	v_fma_f32 v217, v109, v217, v191
	v_fma_f32 v218, v110, v218, v192
	v_fma_f32 v219, v111, v219, v193
	v_cvt_pk_f16_f32 v114, v204, v205
	v_cvt_pk_f16_f32 v115, v206, v207
	v_cvt_pk_f16_f32 v116, v208, v209
	v_cvt_pk_f16_f32 v117, v210, v211
	v_cvt_pk_f16_f32 v118, v212, v213
	v_cvt_pk_f16_f32 v119, v214, v215
	v_cvt_pk_f16_f32 v120, v216, v217
	v_cvt_pk_f16_f32 v121, v218, v219
	global_store_dwordx2 v128, v[114:115], s[54:55]
	global_store_dwordx2 v128, v[116:117], s[54:55] offset:512
	global_store_dwordx2 v128, v[118:119], s[54:55] offset:1024
	global_store_dwordx2 v128, v[120:121], s[54:55] offset:1536
	s_add_i32 s40, s40, s4
	s_branch .Lrnp_exit
; DI void rows_norm_mod(const P& p, const float* xlat, const float* xctx, int l, const float* gain, int sh_idx, int sc_idx,
;                       h16* dst, int nrows) {
;     ...
;   for (int row = gw; row < nrows; row += nw) {
;     const float* xr = row < TL ? xlat + (size_t)row * 1024 : xctx + (size_t)(row - TL) * 1024;
;     const int mrow = row < TL ? (row >> 12) : 8;
;     const float* mr = mod + ((size_t)l * 9 + mrow) * 6144;
;     f32x4 v[4];
;     float ss = 0.f;
; #pragma unroll
;     for (int i = 0; i < 4; ++i) {
;       v[i] = *(const f32x4*)(xr + lane * 4 + 256 * i);
;       ss += v[i].x * v[i].x + v[i].y * v[i].y + v[i].z * v[i].z + v[i].w * v[i].w;
;     }
;     ss = wave_sum(ss);
;     const float rstd = rsqrtf(ss * (1.f / 1024.f) + EPS);
; #pragma unroll
;     for (int i = 0; i < 4; ++i) {
;       const int c = lane * 4 + 256 * i;
;       f32x4 g = *(const f32x4*)(gain + c), sc = *(const f32x4*)(mr + sc_idx * 1024 + c), sh = *(const f32x4*)(mr + sh_idx * 1024 + c);
;       h16x4 o;
;       o.x = (h16)(v[i].x * rstd * g.x * (1.f + sc.x) + sh.x);
;       o.y = (h16)(v[i].y * rstd * g.y * (1.f + sc.y) + sh.y);
;       o.z = (h16)(v[i].z * rstd * g.z * (1.f + sc.z) + sh.z);
;       o.w = (h16)(v[i].w * rstd * g.w * (1.f + sc.w) + sh.w);
;       *(h16x4*)(dst + (size_t)row * 1024 + c) = o;
;     }
;   }
.Lrnp_tail2:
	s_waitcnt vmcnt(8)
	v_mul_f32_e32 v112, v163, v163
	v_mul_f32_e32 v113, v167, v167
	v_mul_f32_e32 v114, v171, v171
	v_mul_f32_e32 v115, v175, v175
	v_fmac_f32_e32 v112, v162, v162
	v_fmac_f32_e32 v113, v166, v166
	v_fmac_f32_e32 v114, v170, v170
	v_fmac_f32_e32 v115, v174, v174
	v_fmac_f32_e32 v112, v164, v164
	v_fmac_f32_e32 v113, v168, v168
	v_fmac_f32_e32 v114, v172, v172
	v_fmac_f32_e32 v115, v176, v176
	v_fmac_f32_e32 v112, v165, v165
	v_fmac_f32_e32 v113, v169, v169
	v_fmac_f32_e32 v114, v173, v173
	v_fmac_f32_e32 v115, v177, v177
	v_add_f32_e32 v112, v112, v113
	v_add_f32_e32 v112, v112, v114
	v_add_f32_e32 v112, v112, v115
	s_nop 1
	v_add_f32_dpp v112, v112, v112 quad_perm:[1,0,3,2] row_mask:0xf bank_mask:0xf bound_ctrl:1
	s_nop 1
	v_add_f32_dpp v112, v112, v112 quad_perm:[2,3,0,1] row_mask:0xf bank_mask:0xf bound_ctrl:1
	s_nop 1
	v_add_f32_dpp v112, v112, v112 row_half_mirror row_mask:0xf bank_mask:0xf bound_ctrl:1
	s_nop 1
	v_add_f32_dpp v112, v112, v112 row_mirror row_mask:0xf bank_mask:0xf bound_ctrl:1
	s_nop 1
	ds_swizzle_b32 v113, v112 offset:swizzle(SWAP,16)
	s_waitcnt lgkmcnt(0)
	v_add_f32_e32 v112, v112, v113
	v_mov_b32_e32 v113, v112
	s_nop 1
	v_permlane32_swap_b32_e32 v112, v113
	v_add_f32_e32 v112, v112, v113
	v_fmamk_f32 v112, v112, 0x3a800000, v224
	v_rsq_f32_e32 v112, v112
	s_waitcnt vmcnt(0)
	v_mul_f32_e32 v162, v162, v112
	v_mul_f32_e32 v163, v163, v112
	v_mul_f32_e32 v164, v164, v112
	v_mul_f32_e32 v165, v165, v112
	v_mul_f32_e32 v166, v166, v112
	v_mul_f32_e32 v167, v167, v112
	v_mul_f32_e32 v168, v168, v112
	v_mul_f32_e32 v169, v169, v112
	v_mul_f32_e32 v170, v170, v112
	v_mul_f32_e32 v171, v171, v112
	v_mul_f32_e32 v172, v172, v112
	v_mul_f32_e32 v173, v173, v112
	v_mul_f32_e32 v174, v174, v112
	v_mul_f32_e32 v175, v175, v112
	v_mul_f32_e32 v176, v176, v112
	v_mul_f32_e32 v177, v177, v112
	v_mul_f32_e32 v162, v80, v162
	v_mul_f32_e32 v163, v81, v163
	v_mul_f32_e32 v164, v82, v164
	v_mul_f32_e32 v165, v83, v165
	v_mul_f32_e32 v166, v84, v166
	v_mul_f32_e32 v167, v85, v167
	v_mul_f32_e32 v168, v86, v168
	v_mul_f32_e32 v169, v87, v169
	v_mul_f32_e32 v170, v88, v170
	v_mul_f32_e32 v171, v89, v171
	v_mul_f32_e32 v172, v90, v172
	v_mul_f32_e32 v173, v91, v173
	v_mul_f32_e32 v174, v92, v174
	v_mul_f32_e32 v175, v93, v175
	v_mul_f32_e32 v176, v94, v176
	v_mul_f32_e32 v177, v95, v177
	v_add_f32_e32 v96, 1.0, v96
	v_add_f32_e32 v97, 1.0, v97
	v_add_f32_e32 v98, 1.0, v98
	v_add_f32_e32 v99, 1.0, v99
	v_add_f32_e32 v100, 1.0, v100
	v_add_f32_e32 v101, 1.0, v101
	v_add_f32_e32 v102, 1.0, v102
	v_add_f32_e32 v103, 1.0, v103
	v_add_f32_e32 v104, 1.0, v104
	v_add_f32_e32 v105, 1.0, v105
	v_add_f32_e32 v106, 1.0, v106
	v_add_f32_e32 v107, 1.0, v107
	v_add_f32_e32 v108, 1.0, v108
	v_add_f32_e32 v109, 1.0, v109
	v_add_f32_e32 v110, 1.0, v110
	v_add_f32_e32 v111, 1.0, v111
	v_fma_f32 v162, v96, v162, v178
	v_fma_f32 v163, v97, v163, v179
	v_fma_f32 v164, v98, v164, v180
	v_fma_f32 v165, v99, v165, v181
	v_fma_f32 v166, v100, v166, v182
	v_fma_f32 v167, v101, v167, v183
	v_fma_f32 v168, v102, v168, v184
	v_fma_f32 v169, v103, v169, v185
	v_fma_f32 v170, v104, v170, v186
	v_fma_f32 v171, v105, v171, v187
	v_fma_f32 v172, v106, v172, v188
	v_fma_f32 v173, v107, v173, v189
	v_fma_f32 v174, v108, v174, v190
	v_fma_f32 v175, v109, v175, v191
	v_fma_f32 v176, v110, v176, v192
	v_fma_f32 v177, v111, v177, v193
	v_cvt_pk_f16_f32 v114, v162, v163
	v_cvt_pk_f16_f32 v115, v164, v165
	v_cvt_pk_f16_f32 v116, v166, v167
	v_cvt_pk_f16_f32 v117, v168, v169
	v_cvt_pk_f16_f32 v118, v170, v171
	v_cvt_pk_f16_f32 v119, v172, v173
	v_cvt_pk_f16_f32 v120, v174, v175
	v_cvt_pk_f16_f32 v121, v176, v177
	global_store_dwordx2 v128, v[114:115], s[54:55]
	global_store_dwordx2 v128, v[116:117], s[54:55] offset:512
	global_store_dwordx2 v128, v[118:119], s[54:55] offset:1024
	global_store_dwordx2 v128, v[120:121], s[54:55] offset:1536
	s_add_i32 s40, s40, s4
	s_cmp_lt_i32 s40, s36
	s_cbranch_scc0 .Lrnp_exit
	s_lshr_b32 s41, s40, 12
	s_cmp_lt_u32 s40, 0x8000
	s_cselect_b32 s41, s41, 8
	s_mul_i32 s41, s41, 0x6000
	s_add_u32 s50, s56, s41
	s_addc_u32 s51, s57, 0
	s_add_u32 s52, s50, 0x1000
	s_addc_u32 s53, s51, 0
	s_lshl_b32 s41, s40, 11
	s_add_u32 s54, s58, s41
	s_addc_u32 s55, s59, 0
	global_load_dwordx4 v[96:99], v0, s[52:53]
	global_load_dwordx4 v[100:103], v0, s[52:53] offset:1024
	global_load_dwordx4 v[104:107], v0, s[52:53] offset:2048
	global_load_dwordx4 v[108:111], v0, s[52:53] offset:3072
	global_load_dwordx4 v[178:181], v0, s[50:51]
	global_load_dwordx4 v[182:185], v0, s[50:51] offset:1024
	global_load_dwordx4 v[186:189], v0, s[50:51] offset:2048
	global_load_dwordx4 v[190:193], v0, s[50:51] offset:3072
	s_waitcnt vmcnt(8)
	v_mul_f32_e32 v112, v205, v205
	v_mul_f32_e32 v113, v209, v209
	v_mul_f32_e32 v114, v213, v213
	v_mul_f32_e32 v115, v217, v217
	v_fmac_f32_e32 v112, v204, v204
	v_fmac_f32_e32 v113, v208, v208
	v_fmac_f32_e32 v114, v212, v212
	v_fmac_f32_e32 v115, v216, v216
	v_fmac_f32_e32 v112, v206, v206
	v_fmac_f32_e32 v113, v210, v210
	v_fmac_f32_e32 v114, v214, v214
	v_fmac_f32_e32 v115, v218, v218
	v_fmac_f32_e32 v112, v207, v207
	v_fmac_f32_e32 v113, v211, v211
	v_fmac_f32_e32 v114, v215, v215
	v_fmac_f32_e32 v115, v219, v219
	v_add_f32_e32 v112, v112, v113
	v_add_f32_e32 v112, v112, v114
	v_add_f32_e32 v112, v112, v115
	s_nop 1
	v_add_f32_dpp v112, v112, v112 quad_perm:[1,0,3,2] row_mask:0xf bank_mask:0xf bound_ctrl:1
	s_nop 1
	v_add_f32_dpp v112, v112, v112 quad_perm:[2,3,0,1] row_mask:0xf bank_mask:0xf bound_ctrl:1
	s_nop 1
	v_add_f32_dpp v112, v112, v112 row_half_mirror row_mask:0xf bank_mask:0xf bound_ctrl:1
	s_nop 1
	v_add_f32_dpp v112, v112, v112 row_mirror row_mask:0xf bank_mask:0xf bound_ctrl:1
	s_nop 1
	ds_swizzle_b32 v113, v112 offset:swizzle(SWAP,16)
	s_waitcnt lgkmcnt(0)
; DI void rows_norm_mod(const P& p, const float* xlat, const float* xctx, int l, const float* gain, int sh_idx, int sc_idx,
;                       h16* dst, int nrows) {
;     ...
;   for (int row = gw; row < nrows; row += nw) {
;     const float* xr = row < TL ? xlat + (size_t)row * 1024 : xctx + (size_t)(row - TL) * 1024;
;     const int mrow = row < TL ? (row >> 12) : 8;
;     const float* mr = mod + ((size_t)l * 9 + mrow) * 6144;
;     f32x4 v[4];
;     float ss = 0.f;
; #pragma unroll
;     for (int i = 0; i < 4; ++i) {
;       v[i] = *(const f32x4*)(xr + lane * 4 + 256 * i);
;       ss += v[i].x * v[i].x + v[i].y * v[i].y + v[i].z * v[i].z + v[i].w * v[i].w;
;     }
;     ss = wave_sum(ss);
;     const float rstd = rsqrtf(ss * (1.f / 1024.f) + EPS);
; #pragma unroll
;     for (int i = 0; i < 4; ++i) {
;       const int c = lane * 4 + 256 * i;
;       f32x4 g = *(const f32x4*)(gain + c), sc = *(const f32x4*)(mr + sc_idx * 1024 + c), sh = *(const f32x4*)(mr + sh_idx * 1024 + c);
;       h16x4 o;
;       o.x = (h16)(v[i].x * rstd * g.x * (1.f + sc.x) + sh.x);
;       o.y = (h16)(v[i].y * rstd * g.y * (1.f + sc.y) + sh.y);
;       o.z = (h16)(v[i].z * rstd * g.z * (1.f + sc.z) + sh.z);
;       o.w = (h16)(v[i].w * rstd * g.w * (1.f + sc.w) + sh.w);
;       *(h16x4*)(dst + (size_t)row * 1024 + c) = o;
;     }
;   }
	v_add_f32_e32 v112, v112, v113
	v_mov_b32_e32 v113, v112
	s_nop 1
	v_permlane32_swap_b32_e32 v112, v113
	v_add_f32_e32 v112, v112, v113
	v_fmamk_f32 v112, v112, 0x3a800000, v224
	v_rsq_f32_e32 v112, v112
	s_waitcnt vmcnt(0)
	v_mul_f32_e32 v204, v204, v112
	v_mul_f32_e32 v205, v205, v112
	v_mul_f32_e32 v206, v206, v112
	v_mul_f32_e32 v207, v207, v112
	v_mul_f32_e32 v208, v208, v112
	v_mul_f32_e32 v209, v209, v112
	v_mul_f32_e32 v210, v210, v112
	v_mul_f32_e32 v211, v211, v112
	v_mul_f32_e32 v212, v212, v112
	v_mul_f32_e32 v213, v213, v112
	v_mul_f32_e32 v214, v214, v112
	v_mul_f32_e32 v215, v215, v112
	v_mul_f32_e32 v216, v216, v112
	v_mul_f32_e32 v217, v217, v112
	v_mul_f32_e32 v218, v218, v112
	v_mul_f32_e32 v219, v219, v112
	v_mul_f32_e32 v204, v80, v204
	v_mul_f32_e32 v205, v81, v205
	v_mul_f32_e32 v206, v82, v206
	v_mul_f32_e32 v207, v83, v207
	v_mul_f32_e32 v208, v84, v208
	v_mul_f32_e32 v209, v85, v209
	v_mul_f32_e32 v210, v86, v210
	v_mul_f32_e32 v211, v87, v211
	v_mul_f32_e32 v212, v88, v212
	v_mul_f32_e32 v213, v89, v213
	v_mul_f32_e32 v214, v90, v214
	v_mul_f32_e32 v215, v91, v215
	v_mul_f32_e32 v216, v92, v216
	v_mul_f32_e32 v217, v93, v217
	v_mul_f32_e32 v218, v94, v218
	v_mul_f32_e32 v219, v95, v219
	v_add_f32_e32 v96, 1.0, v96
	v_add_f32_e32 v97, 1.0, v97
	v_add_f32_e32 v98, 1.0, v98
	v_add_f32_e32 v99, 1.0, v99
	v_add_f32_e32 v100, 1.0, v100
	v_add_f32_e32 v101, 1.0, v101
	v_add_f32_e32 v102, 1.0, v102
	v_add_f32_e32 v103, 1.0, v103
	v_add_f32_e32 v104, 1.0, v104
	v_add_f32_e32 v105, 1.0, v105
	v_add_f32_e32 v106, 1.0, v106
	v_add_f32_e32 v107, 1.0, v107
	v_add_f32_e32 v108, 1.0, v108
	v_add_f32_e32 v109, 1.0, v109
	v_add_f32_e32 v110, 1.0, v110
	v_add_f32_e32 v111, 1.0, v111
	v_fma_f32 v204, v96, v204, v178
	v_fma_f32 v205, v97, v205, v179
	v_fma_f32 v206, v98, v206, v180
	v_fma_f32 v207, v99, v207, v181
	v_fma_f32 v208, v100, v208, v182
	v_fma_f32 v209, v101, v209, v183
	v_fma_f32 v210, v102, v210, v184
	v_fma_f32 v211, v103, v211, v185
	v_fma_f32 v212, v104, v212, v186
	v_fma_f32 v213, v105, v213, v187
	v_fma_f32 v214, v106, v214, v188
	v_fma_f32 v215, v107, v215, v189
	v_fma_f32 v216, v108, v216, v190
	v_fma_f32 v217, v109, v217, v191
	v_fma_f32 v218, v110, v218, v192
	v_fma_f32 v219, v111, v219, v193
	v_cvt_pk_f16_f32 v114, v204, v205
	v_cvt_pk_f16_f32 v115, v206, v207
	v_cvt_pk_f16_f32 v116, v208, v209
	v_cvt_pk_f16_f32 v117, v210, v211
	v_cvt_pk_f16_f32 v118, v212, v213
	v_cvt_pk_f16_f32 v119, v214, v215
	v_cvt_pk_f16_f32 v120, v216, v217
	v_cvt_pk_f16_f32 v121, v218, v219
	global_store_dwordx2 v128, v[114:115], s[54:55]
	global_store_dwordx2 v128, v[116:117], s[54:55] offset:512
	global_store_dwordx2 v128, v[118:119], s[54:55] offset:1024
	global_store_dwordx2 v128, v[120:121], s[54:55] offset:1536
	s_add_i32 s40, s40, s4
	s_cmp_lt_i32 s40, s36
	s_cbranch_scc0 .Lrnp_exit
	s_lshr_b32 s41, s40, 12
	s_cmp_lt_u32 s40, 0x8000
	s_cselect_b32 s41, s41, 8
	s_mul_i32 s41, s41, 0x6000
	s_add_u32 s50, s56, s41
	s_addc_u32 s51, s57, 0
	s_add_u32 s52, s50, 0x1000
	s_addc_u32 s53, s51, 0
	s_lshl_b32 s41, s40, 11
	s_add_u32 s54, s58, s41
	s_addc_u32 s55, s59, 0
	global_load_dwordx4 v[96:99], v0, s[52:53]
	global_load_dwordx4 v[100:103], v0, s[52:53] offset:1024
	global_load_dwordx4 v[104:107], v0, s[52:53] offset:2048
	global_load_dwordx4 v[108:111], v0, s[52:53] offset:3072
	global_load_dwordx4 v[178:181], v0, s[50:51]
	global_load_dwordx4 v[182:185], v0, s[50:51] offset:1024
	global_load_dwordx4 v[186:189], v0, s[50:51] offset:2048
	global_load_dwordx4 v[190:193], v0, s[50:51] offset:3072
	s_waitcnt vmcnt(8)
	v_mul_f32_e32 v112, v3, v3
	v_mul_f32_e32 v113, v7, v7
	v_mul_f32_e32 v114, v11, v11
	v_mul_f32_e32 v115, v15, v15
	v_fmac_f32_e32 v112, v2, v2
	v_fmac_f32_e32 v113, v6, v6
	v_fmac_f32_e32 v114, v10, v10
	v_fmac_f32_e32 v115, v14, v14
	v_fmac_f32_e32 v112, v4, v4
	v_fmac_f32_e32 v113, v8, v8
	v_fmac_f32_e32 v114, v12, v12
	v_fmac_f32_e32 v115, v16, v16
	v_fmac_f32_e32 v112, v5, v5
	v_fmac_f32_e32 v113, v9, v9
	v_fmac_f32_e32 v114, v13, v13
	v_fmac_f32_e32 v115, v17, v17
	v_add_f32_e32 v112, v112, v113
	v_add_f32_e32 v112, v112, v114
	v_add_f32_e32 v112, v112, v115
	s_nop 1
	v_add_f32_dpp v112, v112, v112 quad_perm:[1,0,3,2] row_mask:0xf bank_mask:0xf bound_ctrl:1
	s_nop 1
	v_add_f32_dpp v112, v112, v112 quad_perm:[2,3,0,1] row_mask:0xf bank_mask:0xf bound_ctrl:1
	s_nop 1
	v_add_f32_dpp v112, v112, v112 row_half_mirror row_mask:0xf bank_mask:0xf bound_ctrl:1
	s_nop 1
	v_add_f32_dpp v112, v112, v112 row_mirror row_mask:0xf bank_mask:0xf bound_ctrl:1
	s_nop 1
	ds_swizzle_b32 v113, v112 offset:swizzle(SWAP,16)
	s_waitcnt lgkmcnt(0)
	v_add_f32_e32 v112, v112, v113
	v_mov_b32_e32 v113, v112
	s_nop 1
	v_permlane32_swap_b32_e32 v112, v113
	v_add_f32_e32 v112, v112, v113
	v_fmamk_f32 v112, v112, 0x3a800000, v224
	v_rsq_f32_e32 v112, v112
	s_waitcnt vmcnt(0)
; DI void rows_norm_mod(const P& p, const float* xlat, const float* xctx, int l, const float* gain, int sh_idx, int sc_idx,
;                       h16* dst, int nrows) {
;     ...
;   for (int row = gw; row < nrows; row += nw) {
;     const float* xr = row < TL ? xlat + (size_t)row * 1024 : xctx + (size_t)(row - TL) * 1024;
;     const int mrow = row < TL ? (row >> 12) : 8;
;     const float* mr = mod + ((size_t)l * 9 + mrow) * 6144;
;     f32x4 v[4];
;     float ss = 0.f;
; #pragma unroll
;     for (int i = 0; i < 4; ++i) {
;       v[i] = *(const f32x4*)(xr + lane * 4 + 256 * i);
;       ss += v[i].x * v[i].x + v[i].y * v[i].y + v[i].z * v[i].z + v[i].w * v[i].w;
;     }
;     ss = wave_sum(ss);
;     const float rstd = rsqrtf(ss * (1.f / 1024.f) + EPS);
; #pragma unroll
;     for (int i = 0; i < 4; ++i) {
;       const int c = lane * 4 + 256 * i;
;       f32x4 g = *(const f32x4*)(gain + c), sc = *(const f32x4*)(mr + sc_idx * 1024 + c), sh = *(const f32x4*)(mr + sh_idx * 1024 + c);
;       h16x4 o;
;       o.x = (h16)(v[i].x * rstd * g.x * (1.f + sc.x) + sh.x);
;       o.y = (h16)(v[i].y * rstd * g.y * (1.f + sc.y) + sh.y);
;       o.z = (h16)(v[i].z * rstd * g.z * (1.f + sc.z) + sh.z);
;       o.w = (h16)(v[i].w * rstd * g.w * (1.f + sc.w) + sh.w);
;       *(h16x4*)(dst + (size_t)row * 1024 + c) = o;
;     }
;   }
	v_mul_f32_e32 v2, v2, v112
	v_mul_f32_e32 v3, v3, v112
	v_mul_f32_e32 v4, v4, v112
	v_mul_f32_e32 v5, v5, v112
	v_mul_f32_e32 v6, v6, v112
	v_mul_f32_e32 v7, v7, v112
	v_mul_f32_e32 v8, v8, v112
	v_mul_f32_e32 v9, v9, v112
	v_mul_f32_e32 v10, v10, v112
	v_mul_f32_e32 v11, v11, v112
	v_mul_f32_e32 v12, v12, v112
	v_mul_f32_e32 v13, v13, v112
	v_mul_f32_e32 v14, v14, v112
	v_mul_f32_e32 v15, v15, v112
	v_mul_f32_e32 v16, v16, v112
	v_mul_f32_e32 v17, v17, v112
	v_mul_f32_e32 v2, v80, v2
	v_mul_f32_e32 v3, v81, v3
	v_mul_f32_e32 v4, v82, v4
	v_mul_f32_e32 v5, v83, v5
	v_mul_f32_e32 v6, v84, v6
	v_mul_f32_e32 v7, v85, v7
	v_mul_f32_e32 v8, v86, v8
	v_mul_f32_e32 v9, v87, v9
	v_mul_f32_e32 v10, v88, v10
	v_mul_f32_e32 v11, v89, v11
	v_mul_f32_e32 v12, v90, v12
	v_mul_f32_e32 v13, v91, v13
	v_mul_f32_e32 v14, v92, v14
	v_mul_f32_e32 v15, v93, v15
	v_mul_f32_e32 v16, v94, v16
	v_mul_f32_e32 v17, v95, v17
	v_add_f32_e32 v96, 1.0, v96
	v_add_f32_e32 v97, 1.0, v97
	v_add_f32_e32 v98, 1.0, v98
	v_add_f32_e32 v99, 1.0, v99
	v_add_f32_e32 v100, 1.0, v100
	v_add_f32_e32 v101, 1.0, v101
	v_add_f32_e32 v102, 1.0, v102
	v_add_f32_e32 v103, 1.0, v103
	v_add_f32_e32 v104, 1.0, v104
	v_add_f32_e32 v105, 1.0, v105
	v_add_f32_e32 v106, 1.0, v106
	v_add_f32_e32 v107, 1.0, v107
	v_add_f32_e32 v108, 1.0, v108
	v_add_f32_e32 v109, 1.0, v109
	v_add_f32_e32 v110, 1.0, v110
	v_add_f32_e32 v111, 1.0, v111
	v_fma_f32 v2, v96, v2, v178
	v_fma_f32 v3, v97, v3, v179
	v_fma_f32 v4, v98, v4, v180
	v_fma_f32 v5, v99, v5, v181
	v_fma_f32 v6, v100, v6, v182
	v_fma_f32 v7, v101, v7, v183
	v_fma_f32 v8, v102, v8, v184
	v_fma_f32 v9, v103, v9, v185
	v_fma_f32 v10, v104, v10, v186
	v_fma_f32 v11, v105, v11, v187
	v_fma_f32 v12, v106, v12, v188
	v_fma_f32 v13, v107, v13, v189
	v_fma_f32 v14, v108, v14, v190
	v_fma_f32 v15, v109, v15, v191
	v_fma_f32 v16, v110, v16, v192
	v_fma_f32 v17, v111, v17, v193
	v_cvt_pk_f16_f32 v114, v2, v3
	v_cvt_pk_f16_f32 v115, v4, v5
	v_cvt_pk_f16_f32 v116, v6, v7
	v_cvt_pk_f16_f32 v117, v8, v9
	v_cvt_pk_f16_f32 v118, v10, v11
	v_cvt_pk_f16_f32 v119, v12, v13
	v_cvt_pk_f16_f32 v120, v14, v15
	v_cvt_pk_f16_f32 v121, v16, v17
	global_store_dwordx2 v128, v[114:115], s[54:55]
	global_store_dwordx2 v128, v[116:117], s[54:55] offset:512
	global_store_dwordx2 v128, v[118:119], s[54:55] offset:1024
	global_store_dwordx2 v128, v[120:121], s[54:55] offset:1536
	s_add_i32 s40, s40, s4
	s_branch .Lrnp_exit
.Lrnp_tail3:
	s_waitcnt vmcnt(8)
	v_mul_f32_e32 v112, v205, v205
	v_mul_f32_e32 v113, v209, v209
	v_mul_f32_e32 v114, v213, v213
	v_mul_f32_e32 v115, v217, v217
	v_fmac_f32_e32 v112, v204, v204
	v_fmac_f32_e32 v113, v208, v208
	v_fmac_f32_e32 v114, v212, v212
	v_fmac_f32_e32 v115, v216, v216
	v_fmac_f32_e32 v112, v206, v206
	v_fmac_f32_e32 v113, v210, v210
	v_fmac_f32_e32 v114, v214, v214
	v_fmac_f32_e32 v115, v218, v218
	v_fmac_f32_e32 v112, v207, v207
	v_fmac_f32_e32 v113, v211, v211
	v_fmac_f32_e32 v114, v215, v215
	v_fmac_f32_e32 v115, v219, v219
	v_add_f32_e32 v112, v112, v113
	v_add_f32_e32 v112, v112, v114
	v_add_f32_e32 v112, v112, v115
	s_nop 1
	v_add_f32_dpp v112, v112, v112 quad_perm:[1,0,3,2] row_mask:0xf bank_mask:0xf bound_ctrl:1
	s_nop 1
	v_add_f32_dpp v112, v112, v112 quad_perm:[2,3,0,1] row_mask:0xf bank_mask:0xf bound_ctrl:1
	s_nop 1
	v_add_f32_dpp v112, v112, v112 row_half_mirror row_mask:0xf bank_mask:0xf bound_ctrl:1
	s_nop 1
	v_add_f32_dpp v112, v112, v112 row_mirror row_mask:0xf bank_mask:0xf bound_ctrl:1
	s_nop 1
	ds_swizzle_b32 v113, v112 offset:swizzle(SWAP,16)
	s_waitcnt lgkmcnt(0)
	v_add_f32_e32 v112, v112, v113
	v_mov_b32_e32 v113, v112
	s_nop 1
	v_permlane32_swap_b32_e32 v112, v113
	v_add_f32_e32 v112, v112, v113
	v_fmamk_f32 v112, v112, 0x3a800000, v224
	v_rsq_f32_e32 v112, v112
	s_waitcnt vmcnt(0)
	v_mul_f32_e32 v204, v204, v112
	v_mul_f32_e32 v205, v205, v112
	v_mul_f32_e32 v206, v206, v112
	v_mul_f32_e32 v207, v207, v112
	v_mul_f32_e32 v208, v208, v112
	v_mul_f32_e32 v209, v209, v112
	v_mul_f32_e32 v210, v210, v112
	v_mul_f32_e32 v211, v211, v112
	v_mul_f32_e32 v212, v212, v112
	v_mul_f32_e32 v213, v213, v112
	v_mul_f32_e32 v214, v214, v112
	v_mul_f32_e32 v215, v215, v112
	v_mul_f32_e32 v216, v216, v112
	v_mul_f32_e32 v217, v217, v112
	v_mul_f32_e32 v218, v218, v112
	v_mul_f32_e32 v219, v219, v112
	v_mul_f32_e32 v204, v80, v204
	v_mul_f32_e32 v205, v81, v205
	v_mul_f32_e32 v206, v82, v206
	v_mul_f32_e32 v207, v83, v207
	v_mul_f32_e32 v208, v84, v208
	v_mul_f32_e32 v209, v85, v209
	v_mul_f32_e32 v210, v86, v210
	v_mul_f32_e32 v211, v87, v211
	v_mul_f32_e32 v212, v88, v212
	v_mul_f32_e32 v213, v89, v213
	v_mul_f32_e32 v214, v90, v214
	v_mul_f32_e32 v215, v91, v215
	v_mul_f32_e32 v216, v92, v216
	v_mul_f32_e32 v217, v93, v217
	v_mul_f32_e32 v218, v94, v218
	v_mul_f32_e32 v219, v95, v219
	v_add_f32_e32 v96, 1.0, v96
	v_add_f32_e32 v97, 1.0, v97
	v_add_f32_e32 v98, 1.0, v98
	v_add_f32_e32 v99, 1.0, v99
	v_add_f32_e32 v100, 1.0, v100
	v_add_f32_e32 v101, 1.0, v101
	v_add_f32_e32 v102, 1.0, v102
	v_add_f32_e32 v103, 1.0, v103
	v_add_f32_e32 v104, 1.0, v104
	v_add_f32_e32 v105, 1.0, v105
	v_add_f32_e32 v106, 1.0, v106
	v_add_f32_e32 v107, 1.0, v107
	v_add_f32_e32 v108, 1.0, v108
	v_add_f32_e32 v109, 1.0, v109
	v_add_f32_e32 v110, 1.0, v110
	v_add_f32_e32 v111, 1.0, v111
	v_fma_f32 v204, v96, v204, v178
	v_fma_f32 v205, v97, v205, v179
	v_fma_f32 v206, v98, v206, v180
	v_fma_f32 v207, v99, v207, v181
	v_fma_f32 v208, v100, v208, v182
	v_fma_f32 v209, v101, v209, v183
	v_fma_f32 v210, v102, v210, v184
	v_fma_f32 v211, v103, v211, v185
	v_fma_f32 v212, v104, v212, v186
	v_fma_f32 v213, v105, v213, v187
	v_fma_f32 v214, v106, v214, v188
	v_fma_f32 v215, v107, v215, v189
	v_fma_f32 v216, v108, v216, v190
	v_fma_f32 v217, v109, v217, v191
	v_fma_f32 v218, v110, v218, v192
	v_fma_f32 v219, v111, v219, v193
	v_cvt_pk_f16_f32 v114, v204, v205
	v_cvt_pk_f16_f32 v115, v206, v207
	v_cvt_pk_f16_f32 v116, v208, v209
	v_cvt_pk_f16_f32 v117, v210, v211
	v_cvt_pk_f16_f32 v118, v212, v213
	v_cvt_pk_f16_f32 v119, v214, v215
	v_cvt_pk_f16_f32 v120, v216, v217
	v_cvt_pk_f16_f32 v121, v218, v219
	global_store_dwordx2 v128, v[114:115], s[54:55]
	global_store_dwordx2 v128, v[116:117], s[54:55] offset:512
	global_store_dwordx2 v128, v[118:119], s[54:55] offset:1024
	global_store_dwordx2 v128, v[120:121], s[54:55] offset:1536
	s_add_i32 s40, s40, s4
	s_cmp_lt_i32 s40, s36
	s_cbranch_scc0 .Lrnp_exit
; DI void rows_norm_mod(const P& p, const float* xlat, const float* xctx, int l, const float* gain, int sh_idx, int sc_idx,
;                       h16* dst, int nrows) {
;     ...
;   for (int row = gw; row < nrows; row += nw) {
;     const float* xr = row < TL ? xlat + (size_t)row * 1024 : xctx + (size_t)(row - TL) * 1024;
;     const int mrow = row < TL ? (row >> 12) : 8;
;     const float* mr = mod + ((size_t)l * 9 + mrow) * 6144;
;     f32x4 v[4];
;     float ss = 0.f;
; #pragma unroll
;     for (int i = 0; i < 4; ++i) {
;       v[i] = *(const f32x4*)(xr + lane * 4 + 256 * i);
;       ss += v[i].x * v[i].x + v[i].y * v[i].y + v[i].z * v[i].z + v[i].w * v[i].w;
;     }
;     ss = wave_sum(ss);
;     const float rstd = rsqrtf(ss * (1.f / 1024.f) + EPS);
; #pragma unroll
;     for (int i = 0; i < 4; ++i) {
;       const int c = lane * 4 + 256 * i;
;       f32x4 g = *(const f32x4*)(gain + c), sc = *(const f32x4*)(mr + sc_idx * 1024 + c), sh = *(const f32x4*)(mr + sh_idx * 1024 + c);
;       h16x4 o;
;       o.x = (h16)(v[i].x * rstd * g.x * (1.f + sc.x) + sh.x);
;       o.y = (h16)(v[i].y * rstd * g.y * (1.f + sc.y) + sh.y);
;       o.z = (h16)(v[i].z * rstd * g.z * (1.f + sc.z) + sh.z);
;       o.w = (h16)(v[i].w * rstd * g.w * (1.f + sc.w) + sh.w);
;       *(h16x4*)(dst + (size_t)row * 1024 + c) = o;
;     }
;   }
	s_lshr_b32 s41, s40, 12
	s_cmp_lt_u32 s40, 0x8000
	s_cselect_b32 s41, s41, 8
	s_mul_i32 s41, s41, 0x6000
	s_add_u32 s50, s56, s41
	s_addc_u32 s51, s57, 0
	s_add_u32 s52, s50, 0x1000
	s_addc_u32 s53, s51, 0
	s_lshl_b32 s41, s40, 11
	s_add_u32 s54, s58, s41
	s_addc_u32 s55, s59, 0
	global_load_dwordx4 v[96:99], v0, s[52:53]
	global_load_dwordx4 v[100:103], v0, s[52:53] offset:1024
	global_load_dwordx4 v[104:107], v0, s[52:53] offset:2048
	global_load_dwordx4 v[108:111], v0, s[52:53] offset:3072
	global_load_dwordx4 v[178:181], v0, s[50:51]
	global_load_dwordx4 v[182:185], v0, s[50:51] offset:1024
	global_load_dwordx4 v[186:189], v0, s[50:51] offset:2048
	global_load_dwordx4 v[190:193], v0, s[50:51] offset:3072
	s_waitcnt vmcnt(8)
	v_mul_f32_e32 v112, v3, v3
	v_mul_f32_e32 v113, v7, v7
	v_mul_f32_e32 v114, v11, v11
	v_mul_f32_e32 v115, v15, v15
	v_fmac_f32_e32 v112, v2, v2
	v_fmac_f32_e32 v113, v6, v6
	v_fmac_f32_e32 v114, v10, v10
	v_fmac_f32_e32 v115, v14, v14
	v_fmac_f32_e32 v112, v4, v4
	v_fmac_f32_e32 v113, v8, v8
	v_fmac_f32_e32 v114, v12, v12
	v_fmac_f32_e32 v115, v16, v16
	v_fmac_f32_e32 v112, v5, v5
	v_fmac_f32_e32 v113, v9, v9
	v_fmac_f32_e32 v114, v13, v13
	v_fmac_f32_e32 v115, v17, v17
	v_add_f32_e32 v112, v112, v113
	v_add_f32_e32 v112, v112, v114
	v_add_f32_e32 v112, v112, v115
	s_nop 1
	v_add_f32_dpp v112, v112, v112 quad_perm:[1,0,3,2] row_mask:0xf bank_mask:0xf bound_ctrl:1
	s_nop 1
	v_add_f32_dpp v112, v112, v112 quad_perm:[2,3,0,1] row_mask:0xf bank_mask:0xf bound_ctrl:1
	s_nop 1
	v_add_f32_dpp v112, v112, v112 row_half_mirror row_mask:0xf bank_mask:0xf bound_ctrl:1
	s_nop 1
	v_add_f32_dpp v112, v112, v112 row_mirror row_mask:0xf bank_mask:0xf bound_ctrl:1
	s_nop 1
	ds_swizzle_b32 v113, v112 offset:swizzle(SWAP,16)
	s_waitcnt lgkmcnt(0)
	v_add_f32_e32 v112, v112, v113
	v_mov_b32_e32 v113, v112
	s_nop 1
	v_permlane32_swap_b32_e32 v112, v113
	v_add_f32_e32 v112, v112, v113
	v_fmamk_f32 v112, v112, 0x3a800000, v224
	v_rsq_f32_e32 v112, v112
	s_waitcnt vmcnt(0)
	v_mul_f32_e32 v2, v2, v112
	v_mul_f32_e32 v3, v3, v112
	v_mul_f32_e32 v4, v4, v112
	v_mul_f32_e32 v5, v5, v112
	v_mul_f32_e32 v6, v6, v112
	v_mul_f32_e32 v7, v7, v112
	v_mul_f32_e32 v8, v8, v112
	v_mul_f32_e32 v9, v9, v112
	v_mul_f32_e32 v10, v10, v112
	v_mul_f32_e32 v11, v11, v112
	v_mul_f32_e32 v12, v12, v112
	v_mul_f32_e32 v13, v13, v112
	v_mul_f32_e32 v14, v14, v112
	v_mul_f32_e32 v15, v15, v112
	v_mul_f32_e32 v16, v16, v112
	v_mul_f32_e32 v17, v17, v112
	v_mul_f32_e32 v2, v80, v2
	v_mul_f32_e32 v3, v81, v3
	v_mul_f32_e32 v4, v82, v4
	v_mul_f32_e32 v5, v83, v5
	v_mul_f32_e32 v6, v84, v6
	v_mul_f32_e32 v7, v85, v7
	v_mul_f32_e32 v8, v86, v8
	v_mul_f32_e32 v9, v87, v9
	v_mul_f32_e32 v10, v88, v10
	v_mul_f32_e32 v11, v89, v11
	v_mul_f32_e32 v12, v90, v12
	v_mul_f32_e32 v13, v91, v13
	v_mul_f32_e32 v14, v92, v14
	v_mul_f32_e32 v15, v93, v15
	v_mul_f32_e32 v16, v94, v16
	v_mul_f32_e32 v17, v95, v17
	v_add_f32_e32 v96, 1.0, v96
	v_add_f32_e32 v97, 1.0, v97
	v_add_f32_e32 v98, 1.0, v98
	v_add_f32_e32 v99, 1.0, v99
	v_add_f32_e32 v100, 1.0, v100
	v_add_f32_e32 v101, 1.0, v101
	v_add_f32_e32 v102, 1.0, v102
	v_add_f32_e32 v103, 1.0, v103
	v_add_f32_e32 v104, 1.0, v104
	v_add_f32_e32 v105, 1.0, v105
	v_add_f32_e32 v106, 1.0, v106
	v_add_f32_e32 v107, 1.0, v107
	v_add_f32_e32 v108, 1.0, v108
	v_add_f32_e32 v109, 1.0, v109
	v_add_f32_e32 v110, 1.0, v110
	v_add_f32_e32 v111, 1.0, v111
	v_fma_f32 v2, v96, v2, v178
	v_fma_f32 v3, v97, v3, v179
	v_fma_f32 v4, v98, v4, v180
	v_fma_f32 v5, v99, v5, v181
	v_fma_f32 v6, v100, v6, v182
	v_fma_f32 v7, v101, v7, v183
	v_fma_f32 v8, v102, v8, v184
	v_fma_f32 v9, v103, v9, v185
	v_fma_f32 v10, v104, v10, v186
	v_fma_f32 v11, v105, v11, v187
	v_fma_f32 v12, v106, v12, v188
	v_fma_f32 v13, v107, v13, v189
	v_fma_f32 v14, v108, v14, v190
	v_fma_f32 v15, v109, v15, v191
	v_fma_f32 v16, v110, v16, v192
	v_fma_f32 v17, v111, v17, v193
	v_cvt_pk_f16_f32 v114, v2, v3
	v_cvt_pk_f16_f32 v115, v4, v5
	v_cvt_pk_f16_f32 v116, v6, v7
	v_cvt_pk_f16_f32 v117, v8, v9
	v_cvt_pk_f16_f32 v118, v10, v11
	v_cvt_pk_f16_f32 v119, v12, v13
	v_cvt_pk_f16_f32 v120, v14, v15
	v_cvt_pk_f16_f32 v121, v16, v17
	global_store_dwordx2 v128, v[114:115], s[54:55]
	global_store_dwordx2 v128, v[116:117], s[54:55] offset:512
	global_store_dwordx2 v128, v[118:119], s[54:55] offset:1024
	global_store_dwordx2 v128, v[120:121], s[54:55] offset:1536
	s_add_i32 s40, s40, s4
	s_cmp_lt_i32 s40, s36
	s_cbranch_scc0 .Lrnp_exit
; DI void rows_norm_mod(const P& p, const float* xlat, const float* xctx, int l, const float* gain, int sh_idx, int sc_idx,
;                       h16* dst, int nrows) {
;     ...
;   for (int row = gw; row < nrows; row += nw) {
;     const float* xr = row < TL ? xlat + (size_t)row * 1024 : xctx + (size_t)(row - TL) * 1024;
;     const int mrow = row < TL ? (row >> 12) : 8;
;     const float* mr = mod + ((size_t)l * 9 + mrow) * 6144;
;     f32x4 v[4];
;     float ss = 0.f;
; #pragma unroll
;     for (int i = 0; i < 4; ++i) {
;       v[i] = *(const f32x4*)(xr + lane * 4 + 256 * i);
;       ss += v[i].x * v[i].x + v[i].y * v[i].y + v[i].z * v[i].z + v[i].w * v[i].w;
;     }
;     ss = wave_sum(ss);
;     const float rstd = rsqrtf(ss * (1.f / 1024.f) + EPS);
; #pragma unroll
;     for (int i = 0; i < 4; ++i) {
;       const int c = lane * 4 + 256 * i;
;       f32x4 g = *(const f32x4*)(gain + c), sc = *(const f32x4*)(mr + sc_idx * 1024 + c), sh = *(const f32x4*)(mr + sh_idx * 1024 + c);
;       h16x4 o;
;       o.x = (h16)(v[i].x * rstd * g.x * (1.f + sc.x) + sh.x);
;       o.y = (h16)(v[i].y * rstd * g.y * (1.f + sc.y) + sh.y);
;       o.z = (h16)(v[i].z * rstd * g.z * (1.f + sc.z) + sh.z);
;       o.w = (h16)(v[i].w * rstd * g.w * (1.f + sc.w) + sh.w);
;       *(h16x4*)(dst + (size_t)row * 1024 + c) = o;
;     }
;   }
	s_lshr_b32 s41, s40, 12
	s_cmp_lt_u32 s40, 0x8000
	s_cselect_b32 s41, s41, 8
	s_mul_i32 s41, s41, 0x6000
	s_add_u32 s50, s56, s41
	s_addc_u32 s51, s57, 0
	s_add_u32 s52, s50, 0x1000
	s_addc_u32 s53, s51, 0
	s_lshl_b32 s41, s40, 11
	s_add_u32 s54, s58, s41
	s_addc_u32 s55, s59, 0
	global_load_dwordx4 v[96:99], v0, s[52:53]
	global_load_dwordx4 v[100:103], v0, s[52:53] offset:1024
	global_load_dwordx4 v[104:107], v0, s[52:53] offset:2048
	global_load_dwordx4 v[108:111], v0, s[52:53] offset:3072
	global_load_dwordx4 v[178:181], v0, s[50:51]
	global_load_dwordx4 v[182:185], v0, s[50:51] offset:1024
	global_load_dwordx4 v[186:189], v0, s[50:51] offset:2048
	global_load_dwordx4 v[190:193], v0, s[50:51] offset:3072
	s_waitcnt vmcnt(8)
	v_mul_f32_e32 v112, v33, v33
	v_mul_f32_e32 v113, v37, v37
	v_mul_f32_e32 v114, v41, v41
	v_mul_f32_e32 v115, v45, v45
	v_fmac_f32_e32 v112, v32, v32
	v_fmac_f32_e32 v113, v36, v36
	v_fmac_f32_e32 v114, v40, v40
	v_fmac_f32_e32 v115, v44, v44
	v_fmac_f32_e32 v112, v34, v34
	v_fmac_f32_e32 v113, v38, v38
	v_fmac_f32_e32 v114, v42, v42
	v_fmac_f32_e32 v115, v46, v46
	v_fmac_f32_e32 v112, v35, v35
	v_fmac_f32_e32 v113, v39, v39
	v_fmac_f32_e32 v114, v43, v43
	v_fmac_f32_e32 v115, v47, v47
	v_add_f32_e32 v112, v112, v113
	v_add_f32_e32 v112, v112, v114
	v_add_f32_e32 v112, v112, v115
	s_nop 1
	v_add_f32_dpp v112, v112, v112 quad_perm:[1,0,3,2] row_mask:0xf bank_mask:0xf bound_ctrl:1
	s_nop 1
	v_add_f32_dpp v112, v112, v112 quad_perm:[2,3,0,1] row_mask:0xf bank_mask:0xf bound_ctrl:1
	s_nop 1
	v_add_f32_dpp v112, v112, v112 row_half_mirror row_mask:0xf bank_mask:0xf bound_ctrl:1
	s_nop 1
	v_add_f32_dpp v112, v112, v112 row_mirror row_mask:0xf bank_mask:0xf bound_ctrl:1
	s_nop 1
	ds_swizzle_b32 v113, v112 offset:swizzle(SWAP,16)
	s_waitcnt lgkmcnt(0)
	v_add_f32_e32 v112, v112, v113
	v_mov_b32_e32 v113, v112
	s_nop 1
	v_permlane32_swap_b32_e32 v112, v113
	v_add_f32_e32 v112, v112, v113
	v_fmamk_f32 v112, v112, 0x3a800000, v224
	v_rsq_f32_e32 v112, v112
	s_waitcnt vmcnt(0)
	v_mul_f32_e32 v32, v32, v112
	v_mul_f32_e32 v33, v33, v112
	v_mul_f32_e32 v34, v34, v112
	v_mul_f32_e32 v35, v35, v112
	v_mul_f32_e32 v36, v36, v112
	v_mul_f32_e32 v37, v37, v112
	v_mul_f32_e32 v38, v38, v112
	v_mul_f32_e32 v39, v39, v112
	v_mul_f32_e32 v40, v40, v112
	v_mul_f32_e32 v41, v41, v112
	v_mul_f32_e32 v42, v42, v112
	v_mul_f32_e32 v43, v43, v112
	v_mul_f32_e32 v44, v44, v112
	v_mul_f32_e32 v45, v45, v112
	v_mul_f32_e32 v46, v46, v112
	v_mul_f32_e32 v47, v47, v112
	v_mul_f32_e32 v32, v80, v32
	v_mul_f32_e32 v33, v81, v33
	v_mul_f32_e32 v34, v82, v34
	v_mul_f32_e32 v35, v83, v35
	v_mul_f32_e32 v36, v84, v36
	v_mul_f32_e32 v37, v85, v37
	v_mul_f32_e32 v38, v86, v38
	v_mul_f32_e32 v39, v87, v39
	v_mul_f32_e32 v40, v88, v40
	v_mul_f32_e32 v41, v89, v41
	v_mul_f32_e32 v42, v90, v42
	v_mul_f32_e32 v43, v91, v43
	v_mul_f32_e32 v44, v92, v44
	v_mul_f32_e32 v45, v93, v45
	v_mul_f32_e32 v46, v94, v46
	v_mul_f32_e32 v47, v95, v47
	v_add_f32_e32 v96, 1.0, v96
	v_add_f32_e32 v97, 1.0, v97
	v_add_f32_e32 v98, 1.0, v98
	v_add_f32_e32 v99, 1.0, v99
	v_add_f32_e32 v100, 1.0, v100
	v_add_f32_e32 v101, 1.0, v101
	v_add_f32_e32 v102, 1.0, v102
	v_add_f32_e32 v103, 1.0, v103
	v_add_f32_e32 v104, 1.0, v104
	v_add_f32_e32 v105, 1.0, v105
	v_add_f32_e32 v106, 1.0, v106
	v_add_f32_e32 v107, 1.0, v107
	v_add_f32_e32 v108, 1.0, v108
	v_add_f32_e32 v109, 1.0, v109
	v_add_f32_e32 v110, 1.0, v110
	v_add_f32_e32 v111, 1.0, v111
	v_fma_f32 v32, v96, v32, v178
	v_fma_f32 v33, v97, v33, v179
	v_fma_f32 v34, v98, v34, v180
	v_fma_f32 v35, v99, v35, v181
	v_fma_f32 v36, v100, v36, v182
	v_fma_f32 v37, v101, v37, v183
	v_fma_f32 v38, v102, v38, v184
	v_fma_f32 v39, v103, v39, v185
	v_fma_f32 v40, v104, v40, v186
	v_fma_f32 v41, v105, v41, v187
	v_fma_f32 v42, v106, v42, v188
	v_fma_f32 v43, v107, v43, v189
	v_fma_f32 v44, v108, v44, v190
	v_fma_f32 v45, v109, v45, v191
	v_fma_f32 v46, v110, v46, v192
	v_fma_f32 v47, v111, v47, v193
	v_cvt_pk_f16_f32 v114, v32, v33
	v_cvt_pk_f16_f32 v115, v34, v35
	v_cvt_pk_f16_f32 v116, v36, v37
	v_cvt_pk_f16_f32 v117, v38, v39
	v_cvt_pk_f16_f32 v118, v40, v41
	v_cvt_pk_f16_f32 v119, v42, v43
	v_cvt_pk_f16_f32 v120, v44, v45
	v_cvt_pk_f16_f32 v121, v46, v47
	global_store_dwordx2 v128, v[114:115], s[54:55]
	global_store_dwordx2 v128, v[116:117], s[54:55] offset:512
	global_store_dwordx2 v128, v[118:119], s[54:55] offset:1024
	global_store_dwordx2 v128, v[120:121], s[54:55] offset:1536
	s_add_i32 s40, s40, s4
	s_branch .Lrnp_exit

; DI int TIDX() { int t = threadIdx.x; asm volatile("" : "+v"(t)); return t; }
; DI int BIDX() { int b = blockIdx.x; asm volatile("" : "+s"(b)); return b; }
; DI void rows_norm_mod(const P& p, const float* xlat, const float* xctx, int l, const float* gain, int sh_idx, int sc_idx,
;                       h16* dst, int nrows) {
;   const int lane = TIDX() & 63;
;   const int gw = BIDX() * 4 + (TIDX() >> 6), nw = gridDim.x * 4;
;   const float* mod = (const float*)(p.ws + OFF_MOD);
;   for (int row = gw; row < nrows; row += nw) {
;     const float* xr = row < TL ? xlat + (size_t)row * 1024 : xctx + (size_t)(row - TL) * 1024;
;     const int mrow = row < TL ? (row >> 12) : 8;
;     const float* mr = mod + ((size_t)l * 9 + mrow) * 6144;
;     f32x4 v[4];
;     float ss = 0.f;
; #pragma unroll
;     for (int i = 0; i < 4; ++i) {
;       v[i] = *(const f32x4*)(xr + lane * 4 + 256 * i);
;       ss += v[i].x * v[i].x + v[i].y * v[i].y + v[i].z * v[i].z + v[i].w * v[i].w;
;     }
;     ss = wave_sum(ss);
;     const float rstd = rsqrtf(ss * (1.f / 1024.f) + EPS);
; #pragma unroll
;     for (int i = 0; i < 4; ++i) {
;       const int c = lane * 4 + 256 * i;
;       f32x4 g = *(const f32x4*)(gain + c), sc = *(const f32x4*)(mr + sc_idx * 1024 + c), sh = *(const f32x4*)(mr + sh_idx * 1024 + c);
;       h16x4 o;
;       o.x = (h16)(v[i].x * rstd * g.x * (1.f + sc.x) + sh.x);
;       o.y = (h16)(v[i].y * rstd * g.y * (1.f + sc.y) + sh.y);
;       o.z = (h16)(v[i].z * rstd * g.z * (1.f + sc.z) + sh.z);
;       o.w = (h16)(v[i].w * rstd * g.w * (1.f + sc.w) + sh.w);
;       *(h16x4*)(dst + (size_t)row * 1024 + c) = o;
;     }
;   }
.LBB0_1961:
	v_readlane_b32 s12, v254, 53
	v_readlane_b32 s13, v254, 54
	v_readlane_b32 s16, v254, 57
	v_readlane_b32 s17, v254, 58
	v_readlane_b32 s20, v255, 1
	v_readlane_b32 s21, v255, 2
	v_readlane_b32 s2, v255, 5
	s_add_u32 s18, s48, 0x316c000
	s_addc_u32 s19, s49, 0
	v_lshrrev_b32_e32 v128, 1, v0
	global_load_dwordx4 v[80:83], v0, s[20:21]
	global_load_dwordx4 v[84:87], v0, s[20:21] offset:1024
	global_load_dwordx4 v[88:91], v0, s[20:21] offset:2048
	global_load_dwordx4 v[92:95], v0, s[20:21] offset:3072
	v_readfirstlane_b32 s3, v22
	s_nop 3
	s_sub_u32 s7, s3, 0x8000
	s_cmp_lt_u32 s3, 0x8000
	s_cselect_b32 s7, s3, s7
	s_cselect_b32 s8, s12, s16
	s_cselect_b32 s9, s13, s17
	s_lshl_b32 s7, s7, 12
	s_add_u32 s8, s8, s7
	s_addc_u32 s9, s9, 0
	global_load_dwordx4 v[2:5], v0, s[8:9]
	global_load_dwordx4 v[6:9], v0, s[8:9] offset:1024
	global_load_dwordx4 v[10:13], v0, s[8:9] offset:2048
	global_load_dwordx4 v[14:17], v0, s[8:9] offset:3072
	s_mov_b32 s14, s3
	s_add_i32 s14, s14, s2
	s_cmp_lt_i32 s14, 0x8800
	s_cbranch_scc0 .Lrn2_pre0
	s_sub_u32 s7, s14, 0x8000
	s_cmp_lt_u32 s14, 0x8000
	s_cselect_b32 s7, s14, s7
	s_cselect_b32 s8, s12, s16
	s_cselect_b32 s9, s13, s17
	s_lshl_b32 s7, s7, 12
	s_add_u32 s8, s8, s7
	s_addc_u32 s9, s9, 0
	global_load_dwordx4 v[32:35], v0, s[8:9]
	global_load_dwordx4 v[36:39], v0, s[8:9] offset:1024
	global_load_dwordx4 v[40:43], v0, s[8:9] offset:2048
	global_load_dwordx4 v[44:47], v0, s[8:9] offset:3072
	s_add_i32 s14, s14, s2
	s_cmp_lt_i32 s14, 0x8800
	s_cbranch_scc0 .Lrn2_pre0
	s_sub_u32 s7, s14, 0x8000
	s_cmp_lt_u32 s14, 0x8000
	s_cselect_b32 s7, s14, s7
	s_cselect_b32 s8, s12, s16
	s_cselect_b32 s9, s13, s17
	s_lshl_b32 s7, s7, 12
	s_add_u32 s8, s8, s7
	s_addc_u32 s9, s9, 0
	global_load_dwordx4 v[162:165], v0, s[8:9]
	global_load_dwordx4 v[166:169], v0, s[8:9] offset:1024
	global_load_dwordx4 v[170:173], v0, s[8:9] offset:2048
	global_load_dwordx4 v[174:177], v0, s[8:9] offset:3072
.Lrn2_pre0:
	s_lshr_b32 s6, s3, 12
	s_cmp_lt_u32 s3, 0x8000
	s_cselect_b32 s6, s6, 8
	s_mul_i32 s6, s6, 0x6000
	s_add_u32 s22, s4, s6
	s_addc_u32 s23, s5, 0
	s_add_u32 s32, s22, 0x1000
	s_addc_u32 s33, s23, 0
	s_lshl_b32 s6, s3, 11
	s_add_u32 s24, s18, s6
	s_addc_u32 s25, s19, 0
	global_load_dwordx4 v[96:99], v0, s[32:33]
	global_load_dwordx4 v[100:103], v0, s[32:33] offset:1024
	global_load_dwordx4 v[104:107], v0, s[32:33] offset:2048
	global_load_dwordx4 v[108:111], v0, s[32:33] offset:3072
	global_load_dwordx4 v[178:181], v0, s[22:23]
	global_load_dwordx4 v[182:185], v0, s[22:23] offset:1024
	global_load_dwordx4 v[186:189], v0, s[22:23] offset:2048
	global_load_dwordx4 v[190:193], v0, s[22:23] offset:3072
	s_add_i32 s34, s3, s2
	s_add_i32 s34, s34, s2
	s_add_i32 s34, s34, s2
	s_cmp_lt_i32 s34, 0x8800
	s_cbranch_scc0 .Lrn2_tail0
	s_sub_u32 s7, s34, 0x8000
	s_cmp_lt_u32 s34, 0x8000
	s_cselect_b32 s7, s34, s7
	s_cselect_b32 s8, s12, s16
	s_cselect_b32 s9, s13, s17
	s_lshl_b32 s7, s7, 12
	s_add_u32 s8, s8, s7
	s_addc_u32 s9, s9, 0
	global_load_dwordx4 v[204:207], v0, s[8:9]
	global_load_dwordx4 v[208:211], v0, s[8:9] offset:1024
	global_load_dwordx4 v[212:215], v0, s[8:9] offset:2048
	global_load_dwordx4 v[216:219], v0, s[8:9] offset:3072
	s_waitcnt vmcnt(20)
	v_mul_f32_e32 v112, v3, v3
	v_mul_f32_e32 v113, v7, v7
	v_mul_f32_e32 v114, v11, v11
	v_mul_f32_e32 v115, v15, v15
	v_fmac_f32_e32 v112, v2, v2
	v_fmac_f32_e32 v113, v6, v6
	v_fmac_f32_e32 v114, v10, v10
	v_fmac_f32_e32 v115, v14, v14
	v_fmac_f32_e32 v112, v4, v4
	v_fmac_f32_e32 v113, v8, v8
	v_fmac_f32_e32 v114, v12, v12
	v_fmac_f32_e32 v115, v16, v16
	v_fmac_f32_e32 v112, v5, v5
	v_fmac_f32_e32 v113, v9, v9
	v_fmac_f32_e32 v114, v13, v13
	v_fmac_f32_e32 v115, v17, v17
	v_add_f32_e32 v112, v112, v113
	v_add_f32_e32 v112, v112, v114
	v_add_f32_e32 v112, v112, v115
	s_nop 1
	v_add_f32_dpp v112, v112, v112 quad_perm:[1,0,3,2] row_mask:0xf bank_mask:0xf bound_ctrl:1
	s_nop 1
	v_add_f32_dpp v112, v112, v112 quad_perm:[2,3,0,1] row_mask:0xf bank_mask:0xf bound_ctrl:1
	s_nop 1
	v_add_f32_dpp v112, v112, v112 row_half_mirror row_mask:0xf bank_mask:0xf bound_ctrl:1
	s_nop 1
	v_add_f32_dpp v112, v112, v112 row_mirror row_mask:0xf bank_mask:0xf bound_ctrl:1
	s_nop 1
	ds_swizzle_b32 v113, v112 offset:swizzle(SWAP,16)
	s_waitcnt lgkmcnt(0)
	v_add_f32_e32 v112, v112, v113
	v_mov_b32_e32 v113, v112
	s_nop 1
	v_permlane32_swap_b32_e32 v112, v113
	v_add_f32_e32 v112, v112, v113
	v_fmamk_f32 v112, v112, 0x3a800000, v224
	v_rsq_f32_e32 v112, v112
	s_waitcnt vmcnt(4)
	v_mul_f32_e32 v2, v2, v112
	v_mul_f32_e32 v3, v3, v112
	v_mul_f32_e32 v4, v4, v112
	v_mul_f32_e32 v5, v5, v112
	v_mul_f32_e32 v6, v6, v112
	v_mul_f32_e32 v7, v7, v112
	v_mul_f32_e32 v8, v8, v112
	v_mul_f32_e32 v9, v9, v112
	v_mul_f32_e32 v10, v10, v112
	v_mul_f32_e32 v11, v11, v112
	v_mul_f32_e32 v12, v12, v112
	v_mul_f32_e32 v13, v13, v112
	v_mul_f32_e32 v14, v14, v112
	v_mul_f32_e32 v15, v15, v112
	v_mul_f32_e32 v16, v16, v112
	v_mul_f32_e32 v17, v17, v112
	v_mul_f32_e32 v2, v80, v2
	v_mul_f32_e32 v3, v81, v3
	v_mul_f32_e32 v4, v82, v4
	v_mul_f32_e32 v5, v83, v5
	v_mul_f32_e32 v6, v84, v6
	v_mul_f32_e32 v7, v85, v7
	v_mul_f32_e32 v8, v86, v8
	v_mul_f32_e32 v9, v87, v9
	v_mul_f32_e32 v10, v88, v10
	v_mul_f32_e32 v11, v89, v11
	v_mul_f32_e32 v12, v90, v12
	v_mul_f32_e32 v13, v91, v13
	v_mul_f32_e32 v14, v92, v14
	v_mul_f32_e32 v15, v93, v15
	v_mul_f32_e32 v16, v94, v16
	v_mul_f32_e32 v17, v95, v17
	v_add_f32_e32 v96, 1.0, v96
	v_add_f32_e32 v97, 1.0, v97
	v_add_f32_e32 v98, 1.0, v98
	v_add_f32_e32 v99, 1.0, v99
	v_add_f32_e32 v100, 1.0, v100
	v_add_f32_e32 v101, 1.0, v101
	v_add_f32_e32 v102, 1.0, v102
	v_add_f32_e32 v103, 1.0, v103
	v_add_f32_e32 v104, 1.0, v104
	v_add_f32_e32 v105, 1.0, v105
	v_add_f32_e32 v106, 1.0, v106
	v_add_f32_e32 v107, 1.0, v107
	v_add_f32_e32 v108, 1.0, v108
	v_add_f32_e32 v109, 1.0, v109
	v_add_f32_e32 v110, 1.0, v110
	v_add_f32_e32 v111, 1.0, v111
	v_fma_f32 v2, v96, v2, v178
	v_fma_f32 v3, v97, v3, v179
	v_fma_f32 v4, v98, v4, v180
	v_fma_f32 v5, v99, v5, v181
	v_fma_f32 v6, v100, v6, v182
	v_fma_f32 v7, v101, v7, v183
	v_fma_f32 v8, v102, v8, v184
	v_fma_f32 v9, v103, v9, v185
	v_fma_f32 v10, v104, v10, v186
	v_fma_f32 v11, v105, v11, v187
	v_fma_f32 v12, v106, v12, v188
	v_fma_f32 v13, v107, v13, v189
	v_fma_f32 v14, v108, v14, v190
	v_fma_f32 v15, v109, v15, v191
	v_fma_f32 v16, v110, v16, v192
	v_fma_f32 v17, v111, v17, v193
	v_cvt_pk_f16_f32 v114, v2, v3
	v_cvt_pk_f16_f32 v115, v4, v5
	v_cvt_pk_f16_f32 v116, v6, v7
	v_cvt_pk_f16_f32 v117, v8, v9
	v_cvt_pk_f16_f32 v118, v10, v11
	v_cvt_pk_f16_f32 v119, v12, v13
	v_cvt_pk_f16_f32 v120, v14, v15
	v_cvt_pk_f16_f32 v121, v16, v17
	global_store_dwordx2 v128, v[114:115], s[24:25]
	global_store_dwordx2 v128, v[116:117], s[24:25] offset:512
	global_store_dwordx2 v128, v[118:119], s[24:25] offset:1024
	global_store_dwordx2 v128, v[120:121], s[24:25] offset:1536
	s_add_i32 s3, s3, s2
; DI void rows_norm_mod(const P& p, const float* xlat, const float* xctx, int l, const float* gain, int sh_idx, int sc_idx,
;                       h16* dst, int nrows) {
;     ...
;   for (int row = gw; row < nrows; row += nw) {
;     const float* xr = row < TL ? xlat + (size_t)row * 1024 : xctx + (size_t)(row - TL) * 1024;
;     const int mrow = row < TL ? (row >> 12) : 8;
;     const float* mr = mod + ((size_t)l * 9 + mrow) * 6144;
;     f32x4 v[4];
;     float ss = 0.f;
; #pragma unroll
;     for (int i = 0; i < 4; ++i) {
;       v[i] = *(const f32x4*)(xr + lane * 4 + 256 * i);
;       ss += v[i].x * v[i].x + v[i].y * v[i].y + v[i].z * v[i].z + v[i].w * v[i].w;
;     }
;     ss = wave_sum(ss);
;     const float rstd = rsqrtf(ss * (1.f / 1024.f) + EPS);
; #pragma unroll
;     for (int i = 0; i < 4; ++i) {
;       const int c = lane * 4 + 256 * i;
;       f32x4 g = *(const f32x4*)(gain + c), sc = *(const f32x4*)(mr + sc_idx * 1024 + c), sh = *(const f32x4*)(mr + sh_idx * 1024 + c);
;       h16x4 o;
;       o.x = (h16)(v[i].x * rstd * g.x * (1.f + sc.x) + sh.x);
;       o.y = (h16)(v[i].y * rstd * g.y * (1.f + sc.y) + sh.y);
;       o.z = (h16)(v[i].z * rstd * g.z * (1.f + sc.z) + sh.z);
;       o.w = (h16)(v[i].w * rstd * g.w * (1.f + sc.w) + sh.w);
;       *(h16x4*)(dst + (size_t)row * 1024 + c) = o;
;     }
;   }
.Lrn2_pre1:
	s_lshr_b32 s6, s3, 12
	s_cmp_lt_u32 s3, 0x8000
	s_cselect_b32 s6, s6, 8
	s_mul_i32 s6, s6, 0x6000
	s_add_u32 s22, s4, s6
	s_addc_u32 s23, s5, 0
	s_add_u32 s32, s22, 0x1000
	s_addc_u32 s33, s23, 0
	s_lshl_b32 s6, s3, 11
	s_add_u32 s24, s18, s6
	s_addc_u32 s25, s19, 0
	global_load_dwordx4 v[96:99], v0, s[32:33]
	global_load_dwordx4 v[100:103], v0, s[32:33] offset:1024
	global_load_dwordx4 v[104:107], v0, s[32:33] offset:2048
	global_load_dwordx4 v[108:111], v0, s[32:33] offset:3072
	global_load_dwordx4 v[178:181], v0, s[22:23]
	global_load_dwordx4 v[182:185], v0, s[22:23] offset:1024
	global_load_dwordx4 v[186:189], v0, s[22:23] offset:2048
	global_load_dwordx4 v[190:193], v0, s[22:23] offset:3072
	s_add_i32 s34, s3, s2
	s_add_i32 s34, s34, s2
	s_add_i32 s34, s34, s2
	s_cmp_lt_i32 s34, 0x8800
	s_cbranch_scc0 .Lrn2_tail1
	s_sub_u32 s7, s34, 0x8000
	s_cmp_lt_u32 s34, 0x8000
	s_cselect_b32 s7, s34, s7
	s_cselect_b32 s8, s12, s16
	s_cselect_b32 s9, s13, s17
	s_lshl_b32 s7, s7, 12
	s_add_u32 s8, s8, s7
	s_addc_u32 s9, s9, 0
	global_load_dwordx4 v[2:5], v0, s[8:9]
	global_load_dwordx4 v[6:9], v0, s[8:9] offset:1024
	global_load_dwordx4 v[10:13], v0, s[8:9] offset:2048
	global_load_dwordx4 v[14:17], v0, s[8:9] offset:3072
	s_waitcnt vmcnt(20)
	v_mul_f32_e32 v112, v33, v33
	v_mul_f32_e32 v113, v37, v37
	v_mul_f32_e32 v114, v41, v41
	v_mul_f32_e32 v115, v45, v45
	v_fmac_f32_e32 v112, v32, v32
	v_fmac_f32_e32 v113, v36, v36
	v_fmac_f32_e32 v114, v40, v40
	v_fmac_f32_e32 v115, v44, v44
	v_fmac_f32_e32 v112, v34, v34
	v_fmac_f32_e32 v113, v38, v38
	v_fmac_f32_e32 v114, v42, v42
	v_fmac_f32_e32 v115, v46, v46
	v_fmac_f32_e32 v112, v35, v35
	v_fmac_f32_e32 v113, v39, v39
	v_fmac_f32_e32 v114, v43, v43
	v_fmac_f32_e32 v115, v47, v47
	v_add_f32_e32 v112, v112, v113
	v_add_f32_e32 v112, v112, v114
	v_add_f32_e32 v112, v112, v115
	s_nop 1
	v_add_f32_dpp v112, v112, v112 quad_perm:[1,0,3,2] row_mask:0xf bank_mask:0xf bound_ctrl:1
	s_nop 1
	v_add_f32_dpp v112, v112, v112 quad_perm:[2,3,0,1] row_mask:0xf bank_mask:0xf bound_ctrl:1
	s_nop 1
	v_add_f32_dpp v112, v112, v112 row_half_mirror row_mask:0xf bank_mask:0xf bound_ctrl:1
	s_nop 1
	v_add_f32_dpp v112, v112, v112 row_mirror row_mask:0xf bank_mask:0xf bound_ctrl:1
	s_nop 1
	ds_swizzle_b32 v113, v112 offset:swizzle(SWAP,16)
	s_waitcnt lgkmcnt(0)
	v_add_f32_e32 v112, v112, v113
	v_mov_b32_e32 v113, v112
	s_nop 1
	v_permlane32_swap_b32_e32 v112, v113
	v_add_f32_e32 v112, v112, v113
	v_fmamk_f32 v112, v112, 0x3a800000, v224
	v_rsq_f32_e32 v112, v112
	s_waitcnt vmcnt(4)
	v_mul_f32_e32 v32, v32, v112
	v_mul_f32_e32 v33, v33, v112
	v_mul_f32_e32 v34, v34, v112
	v_mul_f32_e32 v35, v35, v112
	v_mul_f32_e32 v36, v36, v112
	v_mul_f32_e32 v37, v37, v112
	v_mul_f32_e32 v38, v38, v112
	v_mul_f32_e32 v39, v39, v112
	v_mul_f32_e32 v40, v40, v112
	v_mul_f32_e32 v41, v41, v112
	v_mul_f32_e32 v42, v42, v112
	v_mul_f32_e32 v43, v43, v112
	v_mul_f32_e32 v44, v44, v112
	v_mul_f32_e32 v45, v45, v112
	v_mul_f32_e32 v46, v46, v112
	v_mul_f32_e32 v47, v47, v112
	v_mul_f32_e32 v32, v80, v32
	v_mul_f32_e32 v33, v81, v33
	v_mul_f32_e32 v34, v82, v34
	v_mul_f32_e32 v35, v83, v35
	v_mul_f32_e32 v36, v84, v36
	v_mul_f32_e32 v37, v85, v37
	v_mul_f32_e32 v38, v86, v38
	v_mul_f32_e32 v39, v87, v39
	v_mul_f32_e32 v40, v88, v40
	v_mul_f32_e32 v41, v89, v41
	v_mul_f32_e32 v42, v90, v42
	v_mul_f32_e32 v43, v91, v43
	v_mul_f32_e32 v44, v92, v44
	v_mul_f32_e32 v45, v93, v45
	v_mul_f32_e32 v46, v94, v46
	v_mul_f32_e32 v47, v95, v47
	v_add_f32_e32 v96, 1.0, v96
	v_add_f32_e32 v97, 1.0, v97
	v_add_f32_e32 v98, 1.0, v98
	v_add_f32_e32 v99, 1.0, v99
	v_add_f32_e32 v100, 1.0, v100
	v_add_f32_e32 v101, 1.0, v101
	v_add_f32_e32 v102, 1.0, v102
	v_add_f32_e32 v103, 1.0, v103
	v_add_f32_e32 v104, 1.0, v104
	v_add_f32_e32 v105, 1.0, v105
	v_add_f32_e32 v106, 1.0, v106
	v_add_f32_e32 v107, 1.0, v107
	v_add_f32_e32 v108, 1.0, v108
	v_add_f32_e32 v109, 1.0, v109
	v_add_f32_e32 v110, 1.0, v110
	v_add_f32_e32 v111, 1.0, v111
	v_fma_f32 v32, v96, v32, v178
	v_fma_f32 v33, v97, v33, v179
	v_fma_f32 v34, v98, v34, v180
	v_fma_f32 v35, v99, v35, v181
	v_fma_f32 v36, v100, v36, v182
	v_fma_f32 v37, v101, v37, v183
	v_fma_f32 v38, v102, v38, v184
	v_fma_f32 v39, v103, v39, v185
	v_fma_f32 v40, v104, v40, v186
	v_fma_f32 v41, v105, v41, v187
	v_fma_f32 v42, v106, v42, v188
	v_fma_f32 v43, v107, v43, v189
	v_fma_f32 v44, v108, v44, v190
	v_fma_f32 v45, v109, v45, v191
	v_fma_f32 v46, v110, v46, v192
	v_fma_f32 v47, v111, v47, v193
	v_cvt_pk_f16_f32 v114, v32, v33
	v_cvt_pk_f16_f32 v115, v34, v35
	v_cvt_pk_f16_f32 v116, v36, v37
	v_cvt_pk_f16_f32 v117, v38, v39
	v_cvt_pk_f16_f32 v118, v40, v41
	v_cvt_pk_f16_f32 v119, v42, v43
	v_cvt_pk_f16_f32 v120, v44, v45
	v_cvt_pk_f16_f32 v121, v46, v47
	global_store_dwordx2 v128, v[114:115], s[24:25]
	global_store_dwordx2 v128, v[116:117], s[24:25] offset:512
	global_store_dwordx2 v128, v[118:119], s[24:25] offset:1024
	global_store_dwordx2 v128, v[120:121], s[24:25] offset:1536
	s_add_i32 s3, s3, s2
; DI void rows_norm_mod(const P& p, const float* xlat, const float* xctx, int l, const float* gain, int sh_idx, int sc_idx,
;                       h16* dst, int nrows) {
;     ...
;   for (int row = gw; row < nrows; row += nw) {
;     const float* xr = row < TL ? xlat + (size_t)row * 1024 : xctx + (size_t)(row - TL) * 1024;
;     const int mrow = row < TL ? (row >> 12) : 8;
;     const float* mr = mod + ((size_t)l * 9 + mrow) * 6144;
;     f32x4 v[4];
;     float ss = 0.f;
; #pragma unroll
;     for (int i = 0; i < 4; ++i) {
;       v[i] = *(const f32x4*)(xr + lane * 4 + 256 * i);
;       ss += v[i].x * v[i].x + v[i].y * v[i].y + v[i].z * v[i].z + v[i].w * v[i].w;
;     }
;     ss = wave_sum(ss);
;     const float rstd = rsqrtf(ss * (1.f / 1024.f) + EPS);
; #pragma unroll
;     for (int i = 0; i < 4; ++i) {
;       const int c = lane * 4 + 256 * i;
;       f32x4 g = *(const f32x4*)(gain + c), sc = *(const f32x4*)(mr + sc_idx * 1024 + c), sh = *(const f32x4*)(mr + sh_idx * 1024 + c);
;       h16x4 o;
;       o.x = (h16)(v[i].x * rstd * g.x * (1.f + sc.x) + sh.x);
;       o.y = (h16)(v[i].y * rstd * g.y * (1.f + sc.y) + sh.y);
;       o.z = (h16)(v[i].z * rstd * g.z * (1.f + sc.z) + sh.z);
;       o.w = (h16)(v[i].w * rstd * g.w * (1.f + sc.w) + sh.w);
;       *(h16x4*)(dst + (size_t)row * 1024 + c) = o;
;     }
;   }
.Lrn2_pre2:
	s_lshr_b32 s6, s3, 12
	s_cmp_lt_u32 s3, 0x8000
	s_cselect_b32 s6, s6, 8
	s_mul_i32 s6, s6, 0x6000
	s_add_u32 s22, s4, s6
	s_addc_u32 s23, s5, 0
	s_add_u32 s32, s22, 0x1000
	s_addc_u32 s33, s23, 0
	s_lshl_b32 s6, s3, 11
	s_add_u32 s24, s18, s6
	s_addc_u32 s25, s19, 0
	global_load_dwordx4 v[96:99], v0, s[32:33]
	global_load_dwordx4 v[100:103], v0, s[32:33] offset:1024
	global_load_dwordx4 v[104:107], v0, s[32:33] offset:2048
	global_load_dwordx4 v[108:111], v0, s[32:33] offset:3072
	global_load_dwordx4 v[178:181], v0, s[22:23]
	global_load_dwordx4 v[182:185], v0, s[22:23] offset:1024
	global_load_dwordx4 v[186:189], v0, s[22:23] offset:2048
	global_load_dwordx4 v[190:193], v0, s[22:23] offset:3072
	s_add_i32 s34, s3, s2
	s_add_i32 s34, s34, s2
	s_add_i32 s34, s34, s2
	s_cmp_lt_i32 s34, 0x8800
	s_cbranch_scc0 .Lrn2_tail2
	s_sub_u32 s7, s34, 0x8000
	s_cmp_lt_u32 s34, 0x8000
	s_cselect_b32 s7, s34, s7
	s_cselect_b32 s8, s12, s16
	s_cselect_b32 s9, s13, s17
	s_lshl_b32 s7, s7, 12
	s_add_u32 s8, s8, s7
	s_addc_u32 s9, s9, 0
	global_load_dwordx4 v[32:35], v0, s[8:9]
	global_load_dwordx4 v[36:39], v0, s[8:9] offset:1024
	global_load_dwordx4 v[40:43], v0, s[8:9] offset:2048
	global_load_dwordx4 v[44:47], v0, s[8:9] offset:3072
	s_waitcnt vmcnt(20)
	v_mul_f32_e32 v112, v163, v163
	v_mul_f32_e32 v113, v167, v167
	v_mul_f32_e32 v114, v171, v171
	v_mul_f32_e32 v115, v175, v175
	v_fmac_f32_e32 v112, v162, v162
	v_fmac_f32_e32 v113, v166, v166
	v_fmac_f32_e32 v114, v170, v170
	v_fmac_f32_e32 v115, v174, v174
	v_fmac_f32_e32 v112, v164, v164
	v_fmac_f32_e32 v113, v168, v168
	v_fmac_f32_e32 v114, v172, v172
	v_fmac_f32_e32 v115, v176, v176
	v_fmac_f32_e32 v112, v165, v165
	v_fmac_f32_e32 v113, v169, v169
	v_fmac_f32_e32 v114, v173, v173
	v_fmac_f32_e32 v115, v177, v177
	v_add_f32_e32 v112, v112, v113
	v_add_f32_e32 v112, v112, v114
	v_add_f32_e32 v112, v112, v115
	s_nop 1
	v_add_f32_dpp v112, v112, v112 quad_perm:[1,0,3,2] row_mask:0xf bank_mask:0xf bound_ctrl:1
	s_nop 1
	v_add_f32_dpp v112, v112, v112 quad_perm:[2,3,0,1] row_mask:0xf bank_mask:0xf bound_ctrl:1
	s_nop 1
	v_add_f32_dpp v112, v112, v112 row_half_mirror row_mask:0xf bank_mask:0xf bound_ctrl:1
	s_nop 1
	v_add_f32_dpp v112, v112, v112 row_mirror row_mask:0xf bank_mask:0xf bound_ctrl:1
	s_nop 1
	ds_swizzle_b32 v113, v112 offset:swizzle(SWAP,16)
	s_waitcnt lgkmcnt(0)
	v_add_f32_e32 v112, v112, v113
	v_mov_b32_e32 v113, v112
	s_nop 1
	v_permlane32_swap_b32_e32 v112, v113
	v_add_f32_e32 v112, v112, v113
	v_fmamk_f32 v112, v112, 0x3a800000, v224
	v_rsq_f32_e32 v112, v112
	s_waitcnt vmcnt(4)
	v_mul_f32_e32 v162, v162, v112
	v_mul_f32_e32 v163, v163, v112
	v_mul_f32_e32 v164, v164, v112
	v_mul_f32_e32 v165, v165, v112
	v_mul_f32_e32 v166, v166, v112
	v_mul_f32_e32 v167, v167, v112
	v_mul_f32_e32 v168, v168, v112
	v_mul_f32_e32 v169, v169, v112
	v_mul_f32_e32 v170, v170, v112
	v_mul_f32_e32 v171, v171, v112
	v_mul_f32_e32 v172, v172, v112
	v_mul_f32_e32 v173, v173, v112
	v_mul_f32_e32 v174, v174, v112
	v_mul_f32_e32 v175, v175, v112
	v_mul_f32_e32 v176, v176, v112
	v_mul_f32_e32 v177, v177, v112
	v_mul_f32_e32 v162, v80, v162
	v_mul_f32_e32 v163, v81, v163
	v_mul_f32_e32 v164, v82, v164
	v_mul_f32_e32 v165, v83, v165
	v_mul_f32_e32 v166, v84, v166
	v_mul_f32_e32 v167, v85, v167
	v_mul_f32_e32 v168, v86, v168
	v_mul_f32_e32 v169, v87, v169
	v_mul_f32_e32 v170, v88, v170
	v_mul_f32_e32 v171, v89, v171
	v_mul_f32_e32 v172, v90, v172
	v_mul_f32_e32 v173, v91, v173
	v_mul_f32_e32 v174, v92, v174
	v_mul_f32_e32 v175, v93, v175
	v_mul_f32_e32 v176, v94, v176
	v_mul_f32_e32 v177, v95, v177
	v_add_f32_e32 v96, 1.0, v96
	v_add_f32_e32 v97, 1.0, v97
	v_add_f32_e32 v98, 1.0, v98
	v_add_f32_e32 v99, 1.0, v99
	v_add_f32_e32 v100, 1.0, v100
	v_add_f32_e32 v101, 1.0, v101
	v_add_f32_e32 v102, 1.0, v102
	v_add_f32_e32 v103, 1.0, v103
	v_add_f32_e32 v104, 1.0, v104
	v_add_f32_e32 v105, 1.0, v105
	v_add_f32_e32 v106, 1.0, v106
	v_add_f32_e32 v107, 1.0, v107
	v_add_f32_e32 v108, 1.0, v108
	v_add_f32_e32 v109, 1.0, v109
	v_add_f32_e32 v110, 1.0, v110
	v_add_f32_e32 v111, 1.0, v111
	v_fma_f32 v162, v96, v162, v178
	v_fma_f32 v163, v97, v163, v179
	v_fma_f32 v164, v98, v164, v180
	v_fma_f32 v165, v99, v165, v181
	v_fma_f32 v166, v100, v166, v182
	v_fma_f32 v167, v101, v167, v183
	v_fma_f32 v168, v102, v168, v184
	v_fma_f32 v169, v103, v169, v185
	v_fma_f32 v170, v104, v170, v186
	v_fma_f32 v171, v105, v171, v187
	v_fma_f32 v172, v106, v172, v188
	v_fma_f32 v173, v107, v173, v189
	v_fma_f32 v174, v108, v174, v190
	v_fma_f32 v175, v109, v175, v191
	v_fma_f32 v176, v110, v176, v192
	v_fma_f32 v177, v111, v177, v193
	v_cvt_pk_f16_f32 v114, v162, v163
	v_cvt_pk_f16_f32 v115, v164, v165
	v_cvt_pk_f16_f32 v116, v166, v167
	v_cvt_pk_f16_f32 v117, v168, v169
	v_cvt_pk_f16_f32 v118, v170, v171
	v_cvt_pk_f16_f32 v119, v172, v173
	v_cvt_pk_f16_f32 v120, v174, v175
	v_cvt_pk_f16_f32 v121, v176, v177
	global_store_dwordx2 v128, v[114:115], s[24:25]
	global_store_dwordx2 v128, v[116:117], s[24:25] offset:512
	global_store_dwordx2 v128, v[118:119], s[24:25] offset:1024
	global_store_dwordx2 v128, v[120:121], s[24:25] offset:1536
	s_add_i32 s3, s3, s2
; DI void rows_norm_mod(const P& p, const float* xlat, const float* xctx, int l, const float* gain, int sh_idx, int sc_idx,
;                       h16* dst, int nrows) {
;     ...
;   for (int row = gw; row < nrows; row += nw) {
;     const float* xr = row < TL ? xlat + (size_t)row * 1024 : xctx + (size_t)(row - TL) * 1024;
;     const int mrow = row < TL ? (row >> 12) : 8;
;     const float* mr = mod + ((size_t)l * 9 + mrow) * 6144;
;     f32x4 v[4];
;     float ss = 0.f;
; #pragma unroll
;     for (int i = 0; i < 4; ++i) {
;       v[i] = *(const f32x4*)(xr + lane * 4 + 256 * i);
;       ss += v[i].x * v[i].x + v[i].y * v[i].y + v[i].z * v[i].z + v[i].w * v[i].w;
;     }
;     ss = wave_sum(ss);
;     const float rstd = rsqrtf(ss * (1.f / 1024.f) + EPS);
; #pragma unroll
;     for (int i = 0; i < 4; ++i) {
;       const int c = lane * 4 + 256 * i;
;       f32x4 g = *(const f32x4*)(gain + c), sc = *(const f32x4*)(mr + sc_idx * 1024 + c), sh = *(const f32x4*)(mr + sh_idx * 1024 + c);
;       h16x4 o;
;       o.x = (h16)(v[i].x * rstd * g.x * (1.f + sc.x) + sh.x);
;       o.y = (h16)(v[i].y * rstd * g.y * (1.f + sc.y) + sh.y);
;       o.z = (h16)(v[i].z * rstd * g.z * (1.f + sc.z) + sh.z);
;       o.w = (h16)(v[i].w * rstd * g.w * (1.f + sc.w) + sh.w);
;       *(h16x4*)(dst + (size_t)row * 1024 + c) = o;
;     }
;   }
.Lrn2_l3:
	s_lshr_b32 s6, s3, 12
	s_cmp_lt_u32 s3, 0x8000
	s_cselect_b32 s6, s6, 8
	s_mul_i32 s6, s6, 0x6000
	s_add_u32 s22, s4, s6
	s_addc_u32 s23, s5, 0
	s_add_u32 s32, s22, 0x1000
	s_addc_u32 s33, s23, 0
	s_lshl_b32 s6, s3, 11
	s_add_u32 s24, s18, s6
	s_addc_u32 s25, s19, 0
	global_load_dwordx4 v[96:99], v0, s[32:33]
	global_load_dwordx4 v[100:103], v0, s[32:33] offset:1024
	global_load_dwordx4 v[104:107], v0, s[32:33] offset:2048
	global_load_dwordx4 v[108:111], v0, s[32:33] offset:3072
	global_load_dwordx4 v[178:181], v0, s[22:23]
	global_load_dwordx4 v[182:185], v0, s[22:23] offset:1024
	global_load_dwordx4 v[186:189], v0, s[22:23] offset:2048
	global_load_dwordx4 v[190:193], v0, s[22:23] offset:3072
	s_add_i32 s34, s3, s2
	s_add_i32 s34, s34, s2
	s_add_i32 s34, s34, s2
	s_cmp_lt_i32 s34, 0x8800
	s_cbranch_scc0 .Lrn2_tail3
	s_sub_u32 s7, s34, 0x8000
	s_cmp_lt_u32 s34, 0x8000
	s_cselect_b32 s7, s34, s7
	s_cselect_b32 s8, s12, s16
	s_cselect_b32 s9, s13, s17
	s_lshl_b32 s7, s7, 12
	s_add_u32 s8, s8, s7
	s_addc_u32 s9, s9, 0
	global_load_dwordx4 v[162:165], v0, s[8:9]
	global_load_dwordx4 v[166:169], v0, s[8:9] offset:1024
	global_load_dwordx4 v[170:173], v0, s[8:9] offset:2048
	global_load_dwordx4 v[174:177], v0, s[8:9] offset:3072
	s_waitcnt vmcnt(48)
	v_mul_f32_e32 v112, v205, v205
	v_mul_f32_e32 v113, v209, v209
	v_mul_f32_e32 v114, v213, v213
	v_mul_f32_e32 v115, v217, v217
	v_fmac_f32_e32 v112, v204, v204
	v_fmac_f32_e32 v113, v208, v208
	v_fmac_f32_e32 v114, v212, v212
	v_fmac_f32_e32 v115, v216, v216
	v_fmac_f32_e32 v112, v206, v206
	v_fmac_f32_e32 v113, v210, v210
	v_fmac_f32_e32 v114, v214, v214
	v_fmac_f32_e32 v115, v218, v218
	v_fmac_f32_e32 v112, v207, v207
	v_fmac_f32_e32 v113, v211, v211
	v_fmac_f32_e32 v114, v215, v215
	v_fmac_f32_e32 v115, v219, v219
	v_add_f32_e32 v112, v112, v113
	v_add_f32_e32 v112, v112, v114
	v_add_f32_e32 v112, v112, v115
	s_nop 1
	v_add_f32_dpp v112, v112, v112 quad_perm:[1,0,3,2] row_mask:0xf bank_mask:0xf bound_ctrl:1
	s_nop 1
	v_add_f32_dpp v112, v112, v112 quad_perm:[2,3,0,1] row_mask:0xf bank_mask:0xf bound_ctrl:1
	s_nop 1
	v_add_f32_dpp v112, v112, v112 row_half_mirror row_mask:0xf bank_mask:0xf bound_ctrl:1
	s_nop 1
	v_add_f32_dpp v112, v112, v112 row_mirror row_mask:0xf bank_mask:0xf bound_ctrl:1
	s_nop 1
	ds_swizzle_b32 v113, v112 offset:swizzle(SWAP,16)
	s_waitcnt lgkmcnt(0)
	v_add_f32_e32 v112, v112, v113
	v_mov_b32_e32 v113, v112
	s_nop 1
	v_permlane32_swap_b32_e32 v112, v113
	v_add_f32_e32 v112, v112, v113
	v_fmamk_f32 v112, v112, 0x3a800000, v224
	v_rsq_f32_e32 v112, v112
	s_waitcnt vmcnt(4)
	v_mul_f32_e32 v204, v204, v112
	v_mul_f32_e32 v205, v205, v112
	v_mul_f32_e32 v206, v206, v112
	v_mul_f32_e32 v207, v207, v112
	v_mul_f32_e32 v208, v208, v112
	v_mul_f32_e32 v209, v209, v112
	v_mul_f32_e32 v210, v210, v112
	v_mul_f32_e32 v211, v211, v112
	v_mul_f32_e32 v212, v212, v112
	v_mul_f32_e32 v213, v213, v112
	v_mul_f32_e32 v214, v214, v112
	v_mul_f32_e32 v215, v215, v112
	v_mul_f32_e32 v216, v216, v112
	v_mul_f32_e32 v217, v217, v112
	v_mul_f32_e32 v218, v218, v112
	v_mul_f32_e32 v219, v219, v112
	v_mul_f32_e32 v204, v80, v204
	v_mul_f32_e32 v205, v81, v205
	v_mul_f32_e32 v206, v82, v206
	v_mul_f32_e32 v207, v83, v207
	v_mul_f32_e32 v208, v84, v208
	v_mul_f32_e32 v209, v85, v209
	v_mul_f32_e32 v210, v86, v210
	v_mul_f32_e32 v211, v87, v211
	v_mul_f32_e32 v212, v88, v212
	v_mul_f32_e32 v213, v89, v213
	v_mul_f32_e32 v214, v90, v214
	v_mul_f32_e32 v215, v91, v215
	v_mul_f32_e32 v216, v92, v216
	v_mul_f32_e32 v217, v93, v217
	v_mul_f32_e32 v218, v94, v218
	v_mul_f32_e32 v219, v95, v219
	v_add_f32_e32 v96, 1.0, v96
	v_add_f32_e32 v97, 1.0, v97
	v_add_f32_e32 v98, 1.0, v98
	v_add_f32_e32 v99, 1.0, v99
	v_add_f32_e32 v100, 1.0, v100
	v_add_f32_e32 v101, 1.0, v101
	v_add_f32_e32 v102, 1.0, v102
	v_add_f32_e32 v103, 1.0, v103
	v_add_f32_e32 v104, 1.0, v104
	v_add_f32_e32 v105, 1.0, v105
	v_add_f32_e32 v106, 1.0, v106
	v_add_f32_e32 v107, 1.0, v107
	v_add_f32_e32 v108, 1.0, v108
	v_add_f32_e32 v109, 1.0, v109
	v_add_f32_e32 v110, 1.0, v110
	v_add_f32_e32 v111, 1.0, v111
	v_fma_f32 v204, v96, v204, v178
	v_fma_f32 v205, v97, v205, v179
	v_fma_f32 v206, v98, v206, v180
	v_fma_f32 v207, v99, v207, v181
	v_fma_f32 v208, v100, v208, v182
	v_fma_f32 v209, v101, v209, v183
	v_fma_f32 v210, v102, v210, v184
	v_fma_f32 v211, v103, v211, v185
	v_fma_f32 v212, v104, v212, v186
	v_fma_f32 v213, v105, v213, v187
	v_fma_f32 v214, v106, v214, v188
	v_fma_f32 v215, v107, v215, v189
	v_fma_f32 v216, v108, v216, v190
	v_fma_f32 v217, v109, v217, v191
	v_fma_f32 v218, v110, v218, v192
	v_fma_f32 v219, v111, v219, v193
	v_cvt_pk_f16_f32 v114, v204, v205
	v_cvt_pk_f16_f32 v115, v206, v207
	v_cvt_pk_f16_f32 v116, v208, v209
	v_cvt_pk_f16_f32 v117, v210, v211
	v_cvt_pk_f16_f32 v118, v212, v213
	v_cvt_pk_f16_f32 v119, v214, v215
	v_cvt_pk_f16_f32 v120, v216, v217
	v_cvt_pk_f16_f32 v121, v218, v219
	global_store_dwordx2 v128, v[114:115], s[24:25]
	global_store_dwordx2 v128, v[116:117], s[24:25] offset:512
	global_store_dwordx2 v128, v[118:119], s[24:25] offset:1024
	global_store_dwordx2 v128, v[120:121], s[24:25] offset:1536
	s_add_i32 s3, s3, s2
; DI void rows_norm_mod(const P& p, const float* xlat, const float* xctx, int l, const float* gain, int sh_idx, int sc_idx,
;                       h16* dst, int nrows) {
;     ...
;   for (int row = gw; row < nrows; row += nw) {
;     const float* xr = row < TL ? xlat + (size_t)row * 1024 : xctx + (size_t)(row - TL) * 1024;
;     const int mrow = row < TL ? (row >> 12) : 8;
;     const float* mr = mod + ((size_t)l * 9 + mrow) * 6144;
;     f32x4 v[4];
;     float ss = 0.f;
; #pragma unroll
;     for (int i = 0; i < 4; ++i) {
;       v[i] = *(const f32x4*)(xr + lane * 4 + 256 * i);
;       ss += v[i].x * v[i].x + v[i].y * v[i].y + v[i].z * v[i].z + v[i].w * v[i].w;
;     }
;     ss = wave_sum(ss);
;     const float rstd = rsqrtf(ss * (1.f / 1024.f) + EPS);
; #pragma unroll
;     for (int i = 0; i < 4; ++i) {
;       const int c = lane * 4 + 256 * i;
;       f32x4 g = *(const f32x4*)(gain + c), sc = *(const f32x4*)(mr + sc_idx * 1024 + c), sh = *(const f32x4*)(mr + sh_idx * 1024 + c);
;       h16x4 o;
;       o.x = (h16)(v[i].x * rstd * g.x * (1.f + sc.x) + sh.x);
;       o.y = (h16)(v[i].y * rstd * g.y * (1.f + sc.y) + sh.y);
;       o.z = (h16)(v[i].z * rstd * g.z * (1.f + sc.z) + sh.z);
;       o.w = (h16)(v[i].w * rstd * g.w * (1.f + sc.w) + sh.w);
;       *(h16x4*)(dst + (size_t)row * 1024 + c) = o;
;     }
;   }
.Lrn2_l0:
	s_lshr_b32 s6, s3, 12
	s_cmp_lt_u32 s3, 0x8000
	s_cselect_b32 s6, s6, 8
	s_mul_i32 s6, s6, 0x6000
	s_add_u32 s22, s4, s6
	s_addc_u32 s23, s5, 0
	s_add_u32 s32, s22, 0x1000
	s_addc_u32 s33, s23, 0
	s_lshl_b32 s6, s3, 11
	s_add_u32 s24, s18, s6
	s_addc_u32 s25, s19, 0
	global_load_dwordx4 v[96:99], v0, s[32:33]
	global_load_dwordx4 v[100:103], v0, s[32:33] offset:1024
	global_load_dwordx4 v[104:107], v0, s[32:33] offset:2048
	global_load_dwordx4 v[108:111], v0, s[32:33] offset:3072
	global_load_dwordx4 v[178:181], v0, s[22:23]
	global_load_dwordx4 v[182:185], v0, s[22:23] offset:1024
	global_load_dwordx4 v[186:189], v0, s[22:23] offset:2048
	global_load_dwordx4 v[190:193], v0, s[22:23] offset:3072
	s_add_i32 s34, s3, s2
	s_add_i32 s34, s34, s2
	s_add_i32 s34, s34, s2
	s_cmp_lt_i32 s34, 0x8800
	s_cbranch_scc0 .Lrn2_tail0
	s_sub_u32 s7, s34, 0x8000
	s_cmp_lt_u32 s34, 0x8000
	s_cselect_b32 s7, s34, s7
	s_cselect_b32 s8, s12, s16
	s_cselect_b32 s9, s13, s17
	s_lshl_b32 s7, s7, 12
	s_add_u32 s8, s8, s7
	s_addc_u32 s9, s9, 0
	global_load_dwordx4 v[204:207], v0, s[8:9]
	global_load_dwordx4 v[208:211], v0, s[8:9] offset:1024
	global_load_dwordx4 v[212:215], v0, s[8:9] offset:2048
	global_load_dwordx4 v[216:219], v0, s[8:9] offset:3072
	s_waitcnt vmcnt(48)
	v_mul_f32_e32 v112, v3, v3
	v_mul_f32_e32 v113, v7, v7
	v_mul_f32_e32 v114, v11, v11
	v_mul_f32_e32 v115, v15, v15
	v_fmac_f32_e32 v112, v2, v2
	v_fmac_f32_e32 v113, v6, v6
	v_fmac_f32_e32 v114, v10, v10
	v_fmac_f32_e32 v115, v14, v14
	v_fmac_f32_e32 v112, v4, v4
	v_fmac_f32_e32 v113, v8, v8
	v_fmac_f32_e32 v114, v12, v12
	v_fmac_f32_e32 v115, v16, v16
	v_fmac_f32_e32 v112, v5, v5
	v_fmac_f32_e32 v113, v9, v9
	v_fmac_f32_e32 v114, v13, v13
	v_fmac_f32_e32 v115, v17, v17
	v_add_f32_e32 v112, v112, v113
	v_add_f32_e32 v112, v112, v114
	v_add_f32_e32 v112, v112, v115
	s_nop 1
	v_add_f32_dpp v112, v112, v112 quad_perm:[1,0,3,2] row_mask:0xf bank_mask:0xf bound_ctrl:1
	s_nop 1
	v_add_f32_dpp v112, v112, v112 quad_perm:[2,3,0,1] row_mask:0xf bank_mask:0xf bound_ctrl:1
	s_nop 1
	v_add_f32_dpp v112, v112, v112 row_half_mirror row_mask:0xf bank_mask:0xf bound_ctrl:1
	s_nop 1
	v_add_f32_dpp v112, v112, v112 row_mirror row_mask:0xf bank_mask:0xf bound_ctrl:1
	s_nop 1
	ds_swizzle_b32 v113, v112 offset:swizzle(SWAP,16)
	s_waitcnt lgkmcnt(0)
	v_add_f32_e32 v112, v112, v113
	v_mov_b32_e32 v113, v112
	s_nop 1
	v_permlane32_swap_b32_e32 v112, v113
	v_add_f32_e32 v112, v112, v113
	v_fmamk_f32 v112, v112, 0x3a800000, v224
	v_rsq_f32_e32 v112, v112
	s_waitcnt vmcnt(4)
	v_mul_f32_e32 v2, v2, v112
	v_mul_f32_e32 v3, v3, v112
	v_mul_f32_e32 v4, v4, v112
	v_mul_f32_e32 v5, v5, v112
	v_mul_f32_e32 v6, v6, v112
	v_mul_f32_e32 v7, v7, v112
	v_mul_f32_e32 v8, v8, v112
	v_mul_f32_e32 v9, v9, v112
	v_mul_f32_e32 v10, v10, v112
	v_mul_f32_e32 v11, v11, v112
	v_mul_f32_e32 v12, v12, v112
	v_mul_f32_e32 v13, v13, v112
	v_mul_f32_e32 v14, v14, v112
	v_mul_f32_e32 v15, v15, v112
	v_mul_f32_e32 v16, v16, v112
	v_mul_f32_e32 v17, v17, v112
	v_mul_f32_e32 v2, v80, v2
	v_mul_f32_e32 v3, v81, v3
	v_mul_f32_e32 v4, v82, v4
	v_mul_f32_e32 v5, v83, v5
	v_mul_f32_e32 v6, v84, v6
	v_mul_f32_e32 v7, v85, v7
	v_mul_f32_e32 v8, v86, v8
	v_mul_f32_e32 v9, v87, v9
	v_mul_f32_e32 v10, v88, v10
	v_mul_f32_e32 v11, v89, v11
	v_mul_f32_e32 v12, v90, v12
	v_mul_f32_e32 v13, v91, v13
	v_mul_f32_e32 v14, v92, v14
	v_mul_f32_e32 v15, v93, v15
	v_mul_f32_e32 v16, v94, v16
	v_mul_f32_e32 v17, v95, v17
	v_add_f32_e32 v96, 1.0, v96
	v_add_f32_e32 v97, 1.0, v97
	v_add_f32_e32 v98, 1.0, v98
	v_add_f32_e32 v99, 1.0, v99
	v_add_f32_e32 v100, 1.0, v100
	v_add_f32_e32 v101, 1.0, v101
	v_add_f32_e32 v102, 1.0, v102
	v_add_f32_e32 v103, 1.0, v103
	v_add_f32_e32 v104, 1.0, v104
	v_add_f32_e32 v105, 1.0, v105
	v_add_f32_e32 v106, 1.0, v106
	v_add_f32_e32 v107, 1.0, v107
	v_add_f32_e32 v108, 1.0, v108
	v_add_f32_e32 v109, 1.0, v109
	v_add_f32_e32 v110, 1.0, v110
	v_add_f32_e32 v111, 1.0, v111
	v_fma_f32 v2, v96, v2, v178
	v_fma_f32 v3, v97, v3, v179
	v_fma_f32 v4, v98, v4, v180
	v_fma_f32 v5, v99, v5, v181
	v_fma_f32 v6, v100, v6, v182
	v_fma_f32 v7, v101, v7, v183
	v_fma_f32 v8, v102, v8, v184
	v_fma_f32 v9, v103, v9, v185
	v_fma_f32 v10, v104, v10, v186
	v_fma_f32 v11, v105, v11, v187
	v_fma_f32 v12, v106, v12, v188
	v_fma_f32 v13, v107, v13, v189
	v_fma_f32 v14, v108, v14, v190
	v_fma_f32 v15, v109, v15, v191
	v_fma_f32 v16, v110, v16, v192
	v_fma_f32 v17, v111, v17, v193
	v_cvt_pk_f16_f32 v114, v2, v3
	v_cvt_pk_f16_f32 v115, v4, v5
	v_cvt_pk_f16_f32 v116, v6, v7
	v_cvt_pk_f16_f32 v117, v8, v9
	v_cvt_pk_f16_f32 v118, v10, v11
	v_cvt_pk_f16_f32 v119, v12, v13
	v_cvt_pk_f16_f32 v120, v14, v15
	v_cvt_pk_f16_f32 v121, v16, v17
	global_store_dwordx2 v128, v[114:115], s[24:25]
	global_store_dwordx2 v128, v[116:117], s[24:25] offset:512
	global_store_dwordx2 v128, v[118:119], s[24:25] offset:1024
	global_store_dwordx2 v128, v[120:121], s[24:25] offset:1536
	s_add_i32 s3, s3, s2
; DI void rows_norm_mod(const P& p, const float* xlat, const float* xctx, int l, const float* gain, int sh_idx, int sc_idx,
;                       h16* dst, int nrows) {
;     ...
;   for (int row = gw; row < nrows; row += nw) {
;     const float* xr = row < TL ? xlat + (size_t)row * 1024 : xctx + (size_t)(row - TL) * 1024;
;     const int mrow = row < TL ? (row >> 12) : 8;
;     const float* mr = mod + ((size_t)l * 9 + mrow) * 6144;
;     f32x4 v[4];
;     float ss = 0.f;
; #pragma unroll
;     for (int i = 0; i < 4; ++i) {
;       v[i] = *(const f32x4*)(xr + lane * 4 + 256 * i);
;       ss += v[i].x * v[i].x + v[i].y * v[i].y + v[i].z * v[i].z + v[i].w * v[i].w;
;     }
;     ss = wave_sum(ss);
;     const float rstd = rsqrtf(ss * (1.f / 1024.f) + EPS);
; #pragma unroll
;     for (int i = 0; i < 4; ++i) {
;       const int c = lane * 4 + 256 * i;
;       f32x4 g = *(const f32x4*)(gain + c), sc = *(const f32x4*)(mr + sc_idx * 1024 + c), sh = *(const f32x4*)(mr + sh_idx * 1024 + c);
;       h16x4 o;
;       o.x = (h16)(v[i].x * rstd * g.x * (1.f + sc.x) + sh.x);
;       o.y = (h16)(v[i].y * rstd * g.y * (1.f + sc.y) + sh.y);
;       o.z = (h16)(v[i].z * rstd * g.z * (1.f + sc.z) + sh.z);
;       o.w = (h16)(v[i].w * rstd * g.w * (1.f + sc.w) + sh.w);
;       *(h16x4*)(dst + (size_t)row * 1024 + c) = o;
;     }
;   }
.Lrn2_l1:
	s_lshr_b32 s6, s3, 12
	s_cmp_lt_u32 s3, 0x8000
	s_cselect_b32 s6, s6, 8
	s_mul_i32 s6, s6, 0x6000
	s_add_u32 s22, s4, s6
	s_addc_u32 s23, s5, 0
	s_add_u32 s32, s22, 0x1000
	s_addc_u32 s33, s23, 0
	s_lshl_b32 s6, s3, 11
	s_add_u32 s24, s18, s6
	s_addc_u32 s25, s19, 0
	global_load_dwordx4 v[96:99], v0, s[32:33]
	global_load_dwordx4 v[100:103], v0, s[32:33] offset:1024
	global_load_dwordx4 v[104:107], v0, s[32:33] offset:2048
	global_load_dwordx4 v[108:111], v0, s[32:33] offset:3072
	global_load_dwordx4 v[178:181], v0, s[22:23]
	global_load_dwordx4 v[182:185], v0, s[22:23] offset:1024
	global_load_dwordx4 v[186:189], v0, s[22:23] offset:2048
	global_load_dwordx4 v[190:193], v0, s[22:23] offset:3072
	s_add_i32 s34, s3, s2
	s_add_i32 s34, s34, s2
	s_add_i32 s34, s34, s2
	s_cmp_lt_i32 s34, 0x8800
	s_cbranch_scc0 .Lrn2_tail1
	s_sub_u32 s7, s34, 0x8000
	s_cmp_lt_u32 s34, 0x8000
	s_cselect_b32 s7, s34, s7
	s_cselect_b32 s8, s12, s16
	s_cselect_b32 s9, s13, s17
	s_lshl_b32 s7, s7, 12
	s_add_u32 s8, s8, s7
	s_addc_u32 s9, s9, 0
	global_load_dwordx4 v[2:5], v0, s[8:9]
	global_load_dwordx4 v[6:9], v0, s[8:9] offset:1024
	global_load_dwordx4 v[10:13], v0, s[8:9] offset:2048
	global_load_dwordx4 v[14:17], v0, s[8:9] offset:3072
	s_waitcnt vmcnt(48)
	v_mul_f32_e32 v112, v33, v33
	v_mul_f32_e32 v113, v37, v37
	v_mul_f32_e32 v114, v41, v41
	v_mul_f32_e32 v115, v45, v45
	v_fmac_f32_e32 v112, v32, v32
	v_fmac_f32_e32 v113, v36, v36
	v_fmac_f32_e32 v114, v40, v40
	v_fmac_f32_e32 v115, v44, v44
	v_fmac_f32_e32 v112, v34, v34
	v_fmac_f32_e32 v113, v38, v38
	v_fmac_f32_e32 v114, v42, v42
	v_fmac_f32_e32 v115, v46, v46
	v_fmac_f32_e32 v112, v35, v35
	v_fmac_f32_e32 v113, v39, v39
	v_fmac_f32_e32 v114, v43, v43
	v_fmac_f32_e32 v115, v47, v47
	v_add_f32_e32 v112, v112, v113
	v_add_f32_e32 v112, v112, v114
	v_add_f32_e32 v112, v112, v115
	s_nop 1
	v_add_f32_dpp v112, v112, v112 quad_perm:[1,0,3,2] row_mask:0xf bank_mask:0xf bound_ctrl:1
	s_nop 1
	v_add_f32_dpp v112, v112, v112 quad_perm:[2,3,0,1] row_mask:0xf bank_mask:0xf bound_ctrl:1
	s_nop 1
	v_add_f32_dpp v112, v112, v112 row_half_mirror row_mask:0xf bank_mask:0xf bound_ctrl:1
	s_nop 1
	v_add_f32_dpp v112, v112, v112 row_mirror row_mask:0xf bank_mask:0xf bound_ctrl:1
	s_nop 1
	ds_swizzle_b32 v113, v112 offset:swizzle(SWAP,16)
	s_waitcnt lgkmcnt(0)
	v_add_f32_e32 v112, v112, v113
	v_mov_b32_e32 v113, v112
	s_nop 1
	v_permlane32_swap_b32_e32 v112, v113
	v_add_f32_e32 v112, v112, v113
	v_fmamk_f32 v112, v112, 0x3a800000, v224
	v_rsq_f32_e32 v112, v112
	s_waitcnt vmcnt(4)
	v_mul_f32_e32 v32, v32, v112
	v_mul_f32_e32 v33, v33, v112
	v_mul_f32_e32 v34, v34, v112
	v_mul_f32_e32 v35, v35, v112
	v_mul_f32_e32 v36, v36, v112
	v_mul_f32_e32 v37, v37, v112
	v_mul_f32_e32 v38, v38, v112
	v_mul_f32_e32 v39, v39, v112
	v_mul_f32_e32 v40, v40, v112
	v_mul_f32_e32 v41, v41, v112
	v_mul_f32_e32 v42, v42, v112
	v_mul_f32_e32 v43, v43, v112
	v_mul_f32_e32 v44, v44, v112
	v_mul_f32_e32 v45, v45, v112
	v_mul_f32_e32 v46, v46, v112
	v_mul_f32_e32 v47, v47, v112
	v_mul_f32_e32 v32, v80, v32
	v_mul_f32_e32 v33, v81, v33
	v_mul_f32_e32 v34, v82, v34
	v_mul_f32_e32 v35, v83, v35
	v_mul_f32_e32 v36, v84, v36
	v_mul_f32_e32 v37, v85, v37
	v_mul_f32_e32 v38, v86, v38
	v_mul_f32_e32 v39, v87, v39
	v_mul_f32_e32 v40, v88, v40
	v_mul_f32_e32 v41, v89, v41
	v_mul_f32_e32 v42, v90, v42
	v_mul_f32_e32 v43, v91, v43
	v_mul_f32_e32 v44, v92, v44
	v_mul_f32_e32 v45, v93, v45
	v_mul_f32_e32 v46, v94, v46
	v_mul_f32_e32 v47, v95, v47
	v_add_f32_e32 v96, 1.0, v96
	v_add_f32_e32 v97, 1.0, v97
	v_add_f32_e32 v98, 1.0, v98
	v_add_f32_e32 v99, 1.0, v99
	v_add_f32_e32 v100, 1.0, v100
	v_add_f32_e32 v101, 1.0, v101
	v_add_f32_e32 v102, 1.0, v102
	v_add_f32_e32 v103, 1.0, v103
	v_add_f32_e32 v104, 1.0, v104
	v_add_f32_e32 v105, 1.0, v105
	v_add_f32_e32 v106, 1.0, v106
	v_add_f32_e32 v107, 1.0, v107
	v_add_f32_e32 v108, 1.0, v108
	v_add_f32_e32 v109, 1.0, v109
	v_add_f32_e32 v110, 1.0, v110
	v_add_f32_e32 v111, 1.0, v111
	v_fma_f32 v32, v96, v32, v178
	v_fma_f32 v33, v97, v33, v179
	v_fma_f32 v34, v98, v34, v180
	v_fma_f32 v35, v99, v35, v181
	v_fma_f32 v36, v100, v36, v182
	v_fma_f32 v37, v101, v37, v183
	v_fma_f32 v38, v102, v38, v184
	v_fma_f32 v39, v103, v39, v185
	v_fma_f32 v40, v104, v40, v186
	v_fma_f32 v41, v105, v41, v187
	v_fma_f32 v42, v106, v42, v188
	v_fma_f32 v43, v107, v43, v189
	v_fma_f32 v44, v108, v44, v190
	v_fma_f32 v45, v109, v45, v191
	v_fma_f32 v46, v110, v46, v192
	v_fma_f32 v47, v111, v47, v193
	v_cvt_pk_f16_f32 v114, v32, v33
	v_cvt_pk_f16_f32 v115, v34, v35
	v_cvt_pk_f16_f32 v116, v36, v37
	v_cvt_pk_f16_f32 v117, v38, v39
	v_cvt_pk_f16_f32 v118, v40, v41
	v_cvt_pk_f16_f32 v119, v42, v43
	v_cvt_pk_f16_f32 v120, v44, v45
	v_cvt_pk_f16_f32 v121, v46, v47
	global_store_dwordx2 v128, v[114:115], s[24:25]
	global_store_dwordx2 v128, v[116:117], s[24:25] offset:512
	global_store_dwordx2 v128, v[118:119], s[24:25] offset:1024
	global_store_dwordx2 v128, v[120:121], s[24:25] offset:1536
	s_add_i32 s3, s3, s2
; DI void rows_norm_mod(const P& p, const float* xlat, const float* xctx, int l, const float* gain, int sh_idx, int sc_idx,
;                       h16* dst, int nrows) {
;     ...
;   for (int row = gw; row < nrows; row += nw) {
;     const float* xr = row < TL ? xlat + (size_t)row * 1024 : xctx + (size_t)(row - TL) * 1024;
;     const int mrow = row < TL ? (row >> 12) : 8;
;     const float* mr = mod + ((size_t)l * 9 + mrow) * 6144;
;     f32x4 v[4];
;     float ss = 0.f;
; #pragma unroll
;     for (int i = 0; i < 4; ++i) {
;       v[i] = *(const f32x4*)(xr + lane * 4 + 256 * i);
;       ss += v[i].x * v[i].x + v[i].y * v[i].y + v[i].z * v[i].z + v[i].w * v[i].w;
;     }
;     ss = wave_sum(ss);
;     const float rstd = rsqrtf(ss * (1.f / 1024.f) + EPS);
; #pragma unroll
;     for (int i = 0; i < 4; ++i) {
;       const int c = lane * 4 + 256 * i;
;       f32x4 g = *(const f32x4*)(gain + c), sc = *(const f32x4*)(mr + sc_idx * 1024 + c), sh = *(const f32x4*)(mr + sh_idx * 1024 + c);
;       h16x4 o;
;       o.x = (h16)(v[i].x * rstd * g.x * (1.f + sc.x) + sh.x);
;       o.y = (h16)(v[i].y * rstd * g.y * (1.f + sc.y) + sh.y);
;       o.z = (h16)(v[i].z * rstd * g.z * (1.f + sc.z) + sh.z);
;       o.w = (h16)(v[i].w * rstd * g.w * (1.f + sc.w) + sh.w);
;       *(h16x4*)(dst + (size_t)row * 1024 + c) = o;
;     }
;   }
.Lrn2_l2:
	s_lshr_b32 s6, s3, 12
	s_cmp_lt_u32 s3, 0x8000
	s_cselect_b32 s6, s6, 8
	s_mul_i32 s6, s6, 0x6000
	s_add_u32 s22, s4, s6
	s_addc_u32 s23, s5, 0
	s_add_u32 s32, s22, 0x1000
	s_addc_u32 s33, s23, 0
	s_lshl_b32 s6, s3, 11
	s_add_u32 s24, s18, s6
	s_addc_u32 s25, s19, 0
	global_load_dwordx4 v[96:99], v0, s[32:33]
	global_load_dwordx4 v[100:103], v0, s[32:33] offset:1024
	global_load_dwordx4 v[104:107], v0, s[32:33] offset:2048
	global_load_dwordx4 v[108:111], v0, s[32:33] offset:3072
	global_load_dwordx4 v[178:181], v0, s[22:23]
	global_load_dwordx4 v[182:185], v0, s[22:23] offset:1024
	global_load_dwordx4 v[186:189], v0, s[22:23] offset:2048
	global_load_dwordx4 v[190:193], v0, s[22:23] offset:3072
	s_add_i32 s34, s3, s2
	s_add_i32 s34, s34, s2
	s_add_i32 s34, s34, s2
	s_cmp_lt_i32 s34, 0x8800
	s_cbranch_scc0 .Lrn2_tail2
	s_sub_u32 s7, s34, 0x8000
	s_cmp_lt_u32 s34, 0x8000
	s_cselect_b32 s7, s34, s7
	s_cselect_b32 s8, s12, s16
	s_cselect_b32 s9, s13, s17
	s_lshl_b32 s7, s7, 12
	s_add_u32 s8, s8, s7
	s_addc_u32 s9, s9, 0
	global_load_dwordx4 v[32:35], v0, s[8:9]
	global_load_dwordx4 v[36:39], v0, s[8:9] offset:1024
	global_load_dwordx4 v[40:43], v0, s[8:9] offset:2048
	global_load_dwordx4 v[44:47], v0, s[8:9] offset:3072
	s_waitcnt vmcnt(48)
	v_mul_f32_e32 v112, v163, v163
	v_mul_f32_e32 v113, v167, v167
	v_mul_f32_e32 v114, v171, v171
	v_mul_f32_e32 v115, v175, v175
	v_fmac_f32_e32 v112, v162, v162
	v_fmac_f32_e32 v113, v166, v166
	v_fmac_f32_e32 v114, v170, v170
	v_fmac_f32_e32 v115, v174, v174
	v_fmac_f32_e32 v112, v164, v164
	v_fmac_f32_e32 v113, v168, v168
	v_fmac_f32_e32 v114, v172, v172
	v_fmac_f32_e32 v115, v176, v176
	v_fmac_f32_e32 v112, v165, v165
	v_fmac_f32_e32 v113, v169, v169
	v_fmac_f32_e32 v114, v173, v173
	v_fmac_f32_e32 v115, v177, v177
	v_add_f32_e32 v112, v112, v113
	v_add_f32_e32 v112, v112, v114
	v_add_f32_e32 v112, v112, v115
	s_nop 1
	v_add_f32_dpp v112, v112, v112 quad_perm:[1,0,3,2] row_mask:0xf bank_mask:0xf bound_ctrl:1
	s_nop 1
	v_add_f32_dpp v112, v112, v112 quad_perm:[2,3,0,1] row_mask:0xf bank_mask:0xf bound_ctrl:1
	s_nop 1
	v_add_f32_dpp v112, v112, v112 row_half_mirror row_mask:0xf bank_mask:0xf bound_ctrl:1
	s_nop 1
	v_add_f32_dpp v112, v112, v112 row_mirror row_mask:0xf bank_mask:0xf bound_ctrl:1
	s_nop 1
	ds_swizzle_b32 v113, v112 offset:swizzle(SWAP,16)
	s_waitcnt lgkmcnt(0)
	v_add_f32_e32 v112, v112, v113
	v_mov_b32_e32 v113, v112
	s_nop 1
	v_permlane32_swap_b32_e32 v112, v113
	v_add_f32_e32 v112, v112, v113
	v_fmamk_f32 v112, v112, 0x3a800000, v224
	v_rsq_f32_e32 v112, v112
	s_waitcnt vmcnt(4)
	v_mul_f32_e32 v162, v162, v112
	v_mul_f32_e32 v163, v163, v112
	v_mul_f32_e32 v164, v164, v112
	v_mul_f32_e32 v165, v165, v112
	v_mul_f32_e32 v166, v166, v112
	v_mul_f32_e32 v167, v167, v112
	v_mul_f32_e32 v168, v168, v112
	v_mul_f32_e32 v169, v169, v112
	v_mul_f32_e32 v170, v170, v112
	v_mul_f32_e32 v171, v171, v112
	v_mul_f32_e32 v172, v172, v112
	v_mul_f32_e32 v173, v173, v112
	v_mul_f32_e32 v174, v174, v112
	v_mul_f32_e32 v175, v175, v112
	v_mul_f32_e32 v176, v176, v112
	v_mul_f32_e32 v177, v177, v112
	v_mul_f32_e32 v162, v80, v162
	v_mul_f32_e32 v163, v81, v163
	v_mul_f32_e32 v164, v82, v164
	v_mul_f32_e32 v165, v83, v165
	v_mul_f32_e32 v166, v84, v166
	v_mul_f32_e32 v167, v85, v167
	v_mul_f32_e32 v168, v86, v168
	v_mul_f32_e32 v169, v87, v169
	v_mul_f32_e32 v170, v88, v170
	v_mul_f32_e32 v171, v89, v171
	v_mul_f32_e32 v172, v90, v172
	v_mul_f32_e32 v173, v91, v173
	v_mul_f32_e32 v174, v92, v174
	v_mul_f32_e32 v175, v93, v175
	v_mul_f32_e32 v176, v94, v176
	v_mul_f32_e32 v177, v95, v177
	v_add_f32_e32 v96, 1.0, v96
	v_add_f32_e32 v97, 1.0, v97
	v_add_f32_e32 v98, 1.0, v98
	v_add_f32_e32 v99, 1.0, v99
	v_add_f32_e32 v100, 1.0, v100
	v_add_f32_e32 v101, 1.0, v101
	v_add_f32_e32 v102, 1.0, v102
	v_add_f32_e32 v103, 1.0, v103
	v_add_f32_e32 v104, 1.0, v104
	v_add_f32_e32 v105, 1.0, v105
	v_add_f32_e32 v106, 1.0, v106
	v_add_f32_e32 v107, 1.0, v107
	v_add_f32_e32 v108, 1.0, v108
	v_add_f32_e32 v109, 1.0, v109
	v_add_f32_e32 v110, 1.0, v110
	v_add_f32_e32 v111, 1.0, v111
	v_fma_f32 v162, v96, v162, v178
	v_fma_f32 v163, v97, v163, v179
	v_fma_f32 v164, v98, v164, v180
	v_fma_f32 v165, v99, v165, v181
	v_fma_f32 v166, v100, v166, v182
	v_fma_f32 v167, v101, v167, v183
	v_fma_f32 v168, v102, v168, v184
	v_fma_f32 v169, v103, v169, v185
	v_fma_f32 v170, v104, v170, v186
	v_fma_f32 v171, v105, v171, v187
	v_fma_f32 v172, v106, v172, v188
	v_fma_f32 v173, v107, v173, v189
	v_fma_f32 v174, v108, v174, v190
	v_fma_f32 v175, v109, v175, v191
	v_fma_f32 v176, v110, v176, v192
	v_fma_f32 v177, v111, v177, v193
	v_cvt_pk_f16_f32 v114, v162, v163
	v_cvt_pk_f16_f32 v115, v164, v165
	v_cvt_pk_f16_f32 v116, v166, v167
	v_cvt_pk_f16_f32 v117, v168, v169
	v_cvt_pk_f16_f32 v118, v170, v171
	v_cvt_pk_f16_f32 v119, v172, v173
	v_cvt_pk_f16_f32 v120, v174, v175
	v_cvt_pk_f16_f32 v121, v176, v177
	global_store_dwordx2 v128, v[114:115], s[24:25]
	global_store_dwordx2 v128, v[116:117], s[24:25] offset:512
	global_store_dwordx2 v128, v[118:119], s[24:25] offset:1024
	global_store_dwordx2 v128, v[120:121], s[24:25] offset:1536
	s_add_i32 s3, s3, s2
	s_branch .Lrn2_l3
; DI void rows_norm_mod(const P& p, const float* xlat, const float* xctx, int l, const float* gain, int sh_idx, int sc_idx,
;                       h16* dst, int nrows) {
;     ...
;   for (int row = gw; row < nrows; row += nw) {
;     const float* xr = row < TL ? xlat + (size_t)row * 1024 : xctx + (size_t)(row - TL) * 1024;
;     const int mrow = row < TL ? (row >> 12) : 8;
;     const float* mr = mod + ((size_t)l * 9 + mrow) * 6144;
;     f32x4 v[4];
;     float ss = 0.f;
; #pragma unroll
;     for (int i = 0; i < 4; ++i) {
;       v[i] = *(const f32x4*)(xr + lane * 4 + 256 * i);
;       ss += v[i].x * v[i].x + v[i].y * v[i].y + v[i].z * v[i].z + v[i].w * v[i].w;
;     }
;     ss = wave_sum(ss);
;     const float rstd = rsqrtf(ss * (1.f / 1024.f) + EPS);
; #pragma unroll
;     for (int i = 0; i < 4; ++i) {
;       const int c = lane * 4 + 256 * i;
;       f32x4 g = *(const f32x4*)(gain + c), sc = *(const f32x4*)(mr + sc_idx * 1024 + c), sh = *(const f32x4*)(mr + sh_idx * 1024 + c);
;       h16x4 o;
;       o.x = (h16)(v[i].x * rstd * g.x * (1.f + sc.x) + sh.x);
;       o.y = (h16)(v[i].y * rstd * g.y * (1.f + sc.y) + sh.y);
;       o.z = (h16)(v[i].z * rstd * g.z * (1.f + sc.z) + sh.z);
;       o.w = (h16)(v[i].w * rstd * g.w * (1.f + sc.w) + sh.w);
;       *(h16x4*)(dst + (size_t)row * 1024 + c) = o;
;     }
;   }
.Lrn2_tail0:
	s_waitcnt vmcnt(8)
	v_mul_f32_e32 v112, v3, v3
	v_mul_f32_e32 v113, v7, v7
	v_mul_f32_e32 v114, v11, v11
	v_mul_f32_e32 v115, v15, v15
	v_fmac_f32_e32 v112, v2, v2
	v_fmac_f32_e32 v113, v6, v6
	v_fmac_f32_e32 v114, v10, v10
	v_fmac_f32_e32 v115, v14, v14
	v_fmac_f32_e32 v112, v4, v4
	v_fmac_f32_e32 v113, v8, v8
	v_fmac_f32_e32 v114, v12, v12
	v_fmac_f32_e32 v115, v16, v16
	v_fmac_f32_e32 v112, v5, v5
	v_fmac_f32_e32 v113, v9, v9
	v_fmac_f32_e32 v114, v13, v13
	v_fmac_f32_e32 v115, v17, v17
	v_add_f32_e32 v112, v112, v113
	v_add_f32_e32 v112, v112, v114
	v_add_f32_e32 v112, v112, v115
	s_nop 1
	v_add_f32_dpp v112, v112, v112 quad_perm:[1,0,3,2] row_mask:0xf bank_mask:0xf bound_ctrl:1
	s_nop 1
	v_add_f32_dpp v112, v112, v112 quad_perm:[2,3,0,1] row_mask:0xf bank_mask:0xf bound_ctrl:1
	s_nop 1
	v_add_f32_dpp v112, v112, v112 row_half_mirror row_mask:0xf bank_mask:0xf bound_ctrl:1
	s_nop 1
	v_add_f32_dpp v112, v112, v112 row_mirror row_mask:0xf bank_mask:0xf bound_ctrl:1
	s_nop 1
	ds_swizzle_b32 v113, v112 offset:swizzle(SWAP,16)
	s_waitcnt lgkmcnt(0)
	v_add_f32_e32 v112, v112, v113
	v_mov_b32_e32 v113, v112
	s_nop 1
	v_permlane32_swap_b32_e32 v112, v113
	v_add_f32_e32 v112, v112, v113
	v_fmamk_f32 v112, v112, 0x3a800000, v224
	v_rsq_f32_e32 v112, v112
	s_waitcnt vmcnt(0)
	v_mul_f32_e32 v2, v2, v112
	v_mul_f32_e32 v3, v3, v112
	v_mul_f32_e32 v4, v4, v112
	v_mul_f32_e32 v5, v5, v112
	v_mul_f32_e32 v6, v6, v112
	v_mul_f32_e32 v7, v7, v112
	v_mul_f32_e32 v8, v8, v112
	v_mul_f32_e32 v9, v9, v112
	v_mul_f32_e32 v10, v10, v112
	v_mul_f32_e32 v11, v11, v112
	v_mul_f32_e32 v12, v12, v112
	v_mul_f32_e32 v13, v13, v112
	v_mul_f32_e32 v14, v14, v112
	v_mul_f32_e32 v15, v15, v112
	v_mul_f32_e32 v16, v16, v112
	v_mul_f32_e32 v17, v17, v112
	v_mul_f32_e32 v2, v80, v2
	v_mul_f32_e32 v3, v81, v3
	v_mul_f32_e32 v4, v82, v4
	v_mul_f32_e32 v5, v83, v5
	v_mul_f32_e32 v6, v84, v6
	v_mul_f32_e32 v7, v85, v7
	v_mul_f32_e32 v8, v86, v8
	v_mul_f32_e32 v9, v87, v9
	v_mul_f32_e32 v10, v88, v10
	v_mul_f32_e32 v11, v89, v11
	v_mul_f32_e32 v12, v90, v12
	v_mul_f32_e32 v13, v91, v13
	v_mul_f32_e32 v14, v92, v14
	v_mul_f32_e32 v15, v93, v15
	v_mul_f32_e32 v16, v94, v16
	v_mul_f32_e32 v17, v95, v17
	v_add_f32_e32 v96, 1.0, v96
	v_add_f32_e32 v97, 1.0, v97
	v_add_f32_e32 v98, 1.0, v98
	v_add_f32_e32 v99, 1.0, v99
	v_add_f32_e32 v100, 1.0, v100
	v_add_f32_e32 v101, 1.0, v101
	v_add_f32_e32 v102, 1.0, v102
	v_add_f32_e32 v103, 1.0, v103
	v_add_f32_e32 v104, 1.0, v104
	v_add_f32_e32 v105, 1.0, v105
	v_add_f32_e32 v106, 1.0, v106
	v_add_f32_e32 v107, 1.0, v107
	v_add_f32_e32 v108, 1.0, v108
	v_add_f32_e32 v109, 1.0, v109
	v_add_f32_e32 v110, 1.0, v110
	v_add_f32_e32 v111, 1.0, v111
	v_fma_f32 v2, v96, v2, v178
	v_fma_f32 v3, v97, v3, v179
	v_fma_f32 v4, v98, v4, v180
	v_fma_f32 v5, v99, v5, v181
	v_fma_f32 v6, v100, v6, v182
	v_fma_f32 v7, v101, v7, v183
	v_fma_f32 v8, v102, v8, v184
	v_fma_f32 v9, v103, v9, v185
	v_fma_f32 v10, v104, v10, v186
	v_fma_f32 v11, v105, v11, v187
	v_fma_f32 v12, v106, v12, v188
	v_fma_f32 v13, v107, v13, v189
	v_fma_f32 v14, v108, v14, v190
	v_fma_f32 v15, v109, v15, v191
	v_fma_f32 v16, v110, v16, v192
	v_fma_f32 v17, v111, v17, v193
	v_cvt_pk_f16_f32 v114, v2, v3
	v_cvt_pk_f16_f32 v115, v4, v5
	v_cvt_pk_f16_f32 v116, v6, v7
	v_cvt_pk_f16_f32 v117, v8, v9
	v_cvt_pk_f16_f32 v118, v10, v11
	v_cvt_pk_f16_f32 v119, v12, v13
	v_cvt_pk_f16_f32 v120, v14, v15
	v_cvt_pk_f16_f32 v121, v16, v17
	global_store_dwordx2 v128, v[114:115], s[24:25]
	global_store_dwordx2 v128, v[116:117], s[24:25] offset:512
	global_store_dwordx2 v128, v[118:119], s[24:25] offset:1024
	global_store_dwordx2 v128, v[120:121], s[24:25] offset:1536
	s_add_i32 s3, s3, s2
	s_cmp_lt_i32 s3, 0x8800
	s_cbranch_scc0 .Lrn2_exit
	s_lshr_b32 s6, s3, 12
	s_cmp_lt_u32 s3, 0x8000
	s_cselect_b32 s6, s6, 8
	s_mul_i32 s6, s6, 0x6000
	s_add_u32 s22, s4, s6
	s_addc_u32 s23, s5, 0
	s_add_u32 s32, s22, 0x1000
	s_addc_u32 s33, s23, 0
	s_lshl_b32 s6, s3, 11
	s_add_u32 s24, s18, s6
	s_addc_u32 s25, s19, 0
	global_load_dwordx4 v[96:99], v0, s[32:33]
	global_load_dwordx4 v[100:103], v0, s[32:33] offset:1024
	global_load_dwordx4 v[104:107], v0, s[32:33] offset:2048
	global_load_dwordx4 v[108:111], v0, s[32:33] offset:3072
	global_load_dwordx4 v[178:181], v0, s[22:23]
	global_load_dwordx4 v[182:185], v0, s[22:23] offset:1024
	global_load_dwordx4 v[186:189], v0, s[22:23] offset:2048
	global_load_dwordx4 v[190:193], v0, s[22:23] offset:3072
	s_waitcnt vmcnt(8)
	v_mul_f32_e32 v112, v33, v33
	v_mul_f32_e32 v113, v37, v37
	v_mul_f32_e32 v114, v41, v41
	v_mul_f32_e32 v115, v45, v45
	v_fmac_f32_e32 v112, v32, v32
	v_fmac_f32_e32 v113, v36, v36
	v_fmac_f32_e32 v114, v40, v40
	v_fmac_f32_e32 v115, v44, v44
	v_fmac_f32_e32 v112, v34, v34
	v_fmac_f32_e32 v113, v38, v38
	v_fmac_f32_e32 v114, v42, v42
	v_fmac_f32_e32 v115, v46, v46
	v_fmac_f32_e32 v112, v35, v35
	v_fmac_f32_e32 v113, v39, v39
	v_fmac_f32_e32 v114, v43, v43
	v_fmac_f32_e32 v115, v47, v47
	v_add_f32_e32 v112, v112, v113
	v_add_f32_e32 v112, v112, v114
	v_add_f32_e32 v112, v112, v115
	s_nop 1
	v_add_f32_dpp v112, v112, v112 quad_perm:[1,0,3,2] row_mask:0xf bank_mask:0xf bound_ctrl:1
	s_nop 1
	v_add_f32_dpp v112, v112, v112 quad_perm:[2,3,0,1] row_mask:0xf bank_mask:0xf bound_ctrl:1
	s_nop 1
	v_add_f32_dpp v112, v112, v112 row_half_mirror row_mask:0xf bank_mask:0xf bound_ctrl:1
	s_nop 1
	v_add_f32_dpp v112, v112, v112 row_mirror row_mask:0xf bank_mask:0xf bound_ctrl:1
	s_nop 1
	ds_swizzle_b32 v113, v112 offset:swizzle(SWAP,16)
	s_waitcnt lgkmcnt(0)
; DI void rows_norm_mod(const P& p, const float* xlat, const float* xctx, int l, const float* gain, int sh_idx, int sc_idx,
;                       h16* dst, int nrows) {
;     ...
;   for (int row = gw; row < nrows; row += nw) {
;     const float* xr = row < TL ? xlat + (size_t)row * 1024 : xctx + (size_t)(row - TL) * 1024;
;     const int mrow = row < TL ? (row >> 12) : 8;
;     const float* mr = mod + ((size_t)l * 9 + mrow) * 6144;
;     f32x4 v[4];
;     float ss = 0.f;
; #pragma unroll
;     for (int i = 0; i < 4; ++i) {
;       v[i] = *(const f32x4*)(xr + lane * 4 + 256 * i);
;       ss += v[i].x * v[i].x + v[i].y * v[i].y + v[i].z * v[i].z + v[i].w * v[i].w;
;     }
;     ss = wave_sum(ss);
;     const float rstd = rsqrtf(ss * (1.f / 1024.f) + EPS);
; #pragma unroll
;     for (int i = 0; i < 4; ++i) {
;       const int c = lane * 4 + 256 * i;
;       f32x4 g = *(const f32x4*)(gain + c), sc = *(const f32x4*)(mr + sc_idx * 1024 + c), sh = *(const f32x4*)(mr + sh_idx * 1024 + c);
;       h16x4 o;
;       o.x = (h16)(v[i].x * rstd * g.x * (1.f + sc.x) + sh.x);
;       o.y = (h16)(v[i].y * rstd * g.y * (1.f + sc.y) + sh.y);
;       o.z = (h16)(v[i].z * rstd * g.z * (1.f + sc.z) + sh.z);
;       o.w = (h16)(v[i].w * rstd * g.w * (1.f + sc.w) + sh.w);
;       *(h16x4*)(dst + (size_t)row * 1024 + c) = o;
;     }
;   }
	v_add_f32_e32 v112, v112, v113
	v_mov_b32_e32 v113, v112
	s_nop 1
	v_permlane32_swap_b32_e32 v112, v113
	v_add_f32_e32 v112, v112, v113
	v_fmamk_f32 v112, v112, 0x3a800000, v224
	v_rsq_f32_e32 v112, v112
	s_waitcnt vmcnt(0)
	v_mul_f32_e32 v32, v32, v112
	v_mul_f32_e32 v33, v33, v112
	v_mul_f32_e32 v34, v34, v112
	v_mul_f32_e32 v35, v35, v112
	v_mul_f32_e32 v36, v36, v112
	v_mul_f32_e32 v37, v37, v112
	v_mul_f32_e32 v38, v38, v112
	v_mul_f32_e32 v39, v39, v112
	v_mul_f32_e32 v40, v40, v112
	v_mul_f32_e32 v41, v41, v112
	v_mul_f32_e32 v42, v42, v112
	v_mul_f32_e32 v43, v43, v112
	v_mul_f32_e32 v44, v44, v112
	v_mul_f32_e32 v45, v45, v112
	v_mul_f32_e32 v46, v46, v112
	v_mul_f32_e32 v47, v47, v112
	v_mul_f32_e32 v32, v80, v32
	v_mul_f32_e32 v33, v81, v33
	v_mul_f32_e32 v34, v82, v34
	v_mul_f32_e32 v35, v83, v35
	v_mul_f32_e32 v36, v84, v36
	v_mul_f32_e32 v37, v85, v37
	v_mul_f32_e32 v38, v86, v38
	v_mul_f32_e32 v39, v87, v39
	v_mul_f32_e32 v40, v88, v40
	v_mul_f32_e32 v41, v89, v41
	v_mul_f32_e32 v42, v90, v42
	v_mul_f32_e32 v43, v91, v43
	v_mul_f32_e32 v44, v92, v44
	v_mul_f32_e32 v45, v93, v45
	v_mul_f32_e32 v46, v94, v46
	v_mul_f32_e32 v47, v95, v47
	v_add_f32_e32 v96, 1.0, v96
	v_add_f32_e32 v97, 1.0, v97
	v_add_f32_e32 v98, 1.0, v98
	v_add_f32_e32 v99, 1.0, v99
	v_add_f32_e32 v100, 1.0, v100
	v_add_f32_e32 v101, 1.0, v101
	v_add_f32_e32 v102, 1.0, v102
	v_add_f32_e32 v103, 1.0, v103
	v_add_f32_e32 v104, 1.0, v104
	v_add_f32_e32 v105, 1.0, v105
	v_add_f32_e32 v106, 1.0, v106
	v_add_f32_e32 v107, 1.0, v107
	v_add_f32_e32 v108, 1.0, v108
	v_add_f32_e32 v109, 1.0, v109
	v_add_f32_e32 v110, 1.0, v110
	v_add_f32_e32 v111, 1.0, v111
	v_fma_f32 v32, v96, v32, v178
	v_fma_f32 v33, v97, v33, v179
	v_fma_f32 v34, v98, v34, v180
	v_fma_f32 v35, v99, v35, v181
	v_fma_f32 v36, v100, v36, v182
	v_fma_f32 v37, v101, v37, v183
	v_fma_f32 v38, v102, v38, v184
	v_fma_f32 v39, v103, v39, v185
	v_fma_f32 v40, v104, v40, v186
	v_fma_f32 v41, v105, v41, v187
	v_fma_f32 v42, v106, v42, v188
	v_fma_f32 v43, v107, v43, v189
	v_fma_f32 v44, v108, v44, v190
	v_fma_f32 v45, v109, v45, v191
	v_fma_f32 v46, v110, v46, v192
	v_fma_f32 v47, v111, v47, v193
	v_cvt_pk_f16_f32 v114, v32, v33
	v_cvt_pk_f16_f32 v115, v34, v35
	v_cvt_pk_f16_f32 v116, v36, v37
	v_cvt_pk_f16_f32 v117, v38, v39
	v_cvt_pk_f16_f32 v118, v40, v41
	v_cvt_pk_f16_f32 v119, v42, v43
	v_cvt_pk_f16_f32 v120, v44, v45
	v_cvt_pk_f16_f32 v121, v46, v47
	global_store_dwordx2 v128, v[114:115], s[24:25]
	global_store_dwordx2 v128, v[116:117], s[24:25] offset:512
	global_store_dwordx2 v128, v[118:119], s[24:25] offset:1024
	global_store_dwordx2 v128, v[120:121], s[24:25] offset:1536
	s_add_i32 s3, s3, s2
	s_cmp_lt_i32 s3, 0x8800
	s_cbranch_scc0 .Lrn2_exit
	s_lshr_b32 s6, s3, 12
	s_cmp_lt_u32 s3, 0x8000
	s_cselect_b32 s6, s6, 8
	s_mul_i32 s6, s6, 0x6000
	s_add_u32 s22, s4, s6
	s_addc_u32 s23, s5, 0
	s_add_u32 s32, s22, 0x1000
	s_addc_u32 s33, s23, 0
	s_lshl_b32 s6, s3, 11
	s_add_u32 s24, s18, s6
	s_addc_u32 s25, s19, 0
	global_load_dwordx4 v[96:99], v0, s[32:33]
	global_load_dwordx4 v[100:103], v0, s[32:33] offset:1024
	global_load_dwordx4 v[104:107], v0, s[32:33] offset:2048
	global_load_dwordx4 v[108:111], v0, s[32:33] offset:3072
	global_load_dwordx4 v[178:181], v0, s[22:23]
	global_load_dwordx4 v[182:185], v0, s[22:23] offset:1024
	global_load_dwordx4 v[186:189], v0, s[22:23] offset:2048
	global_load_dwordx4 v[190:193], v0, s[22:23] offset:3072
	s_waitcnt vmcnt(8)
	v_mul_f32_e32 v112, v163, v163
	v_mul_f32_e32 v113, v167, v167
	v_mul_f32_e32 v114, v171, v171
	v_mul_f32_e32 v115, v175, v175
	v_fmac_f32_e32 v112, v162, v162
	v_fmac_f32_e32 v113, v166, v166
	v_fmac_f32_e32 v114, v170, v170
	v_fmac_f32_e32 v115, v174, v174
	v_fmac_f32_e32 v112, v164, v164
	v_fmac_f32_e32 v113, v168, v168
	v_fmac_f32_e32 v114, v172, v172
	v_fmac_f32_e32 v115, v176, v176
	v_fmac_f32_e32 v112, v165, v165
	v_fmac_f32_e32 v113, v169, v169
	v_fmac_f32_e32 v114, v173, v173
	v_fmac_f32_e32 v115, v177, v177
	v_add_f32_e32 v112, v112, v113
	v_add_f32_e32 v112, v112, v114
	v_add_f32_e32 v112, v112, v115
	s_nop 1
	v_add_f32_dpp v112, v112, v112 quad_perm:[1,0,3,2] row_mask:0xf bank_mask:0xf bound_ctrl:1
	s_nop 1
	v_add_f32_dpp v112, v112, v112 quad_perm:[2,3,0,1] row_mask:0xf bank_mask:0xf bound_ctrl:1
	s_nop 1
	v_add_f32_dpp v112, v112, v112 row_half_mirror row_mask:0xf bank_mask:0xf bound_ctrl:1
	s_nop 1
	v_add_f32_dpp v112, v112, v112 row_mirror row_mask:0xf bank_mask:0xf bound_ctrl:1
	s_nop 1
	ds_swizzle_b32 v113, v112 offset:swizzle(SWAP,16)
	s_waitcnt lgkmcnt(0)
	v_add_f32_e32 v112, v112, v113
	v_mov_b32_e32 v113, v112
	s_nop 1
	v_permlane32_swap_b32_e32 v112, v113
	v_add_f32_e32 v112, v112, v113
	v_fmamk_f32 v112, v112, 0x3a800000, v224
	v_rsq_f32_e32 v112, v112
	s_waitcnt vmcnt(0)
; DI void rows_norm_mod(const P& p, const float* xlat, const float* xctx, int l, const float* gain, int sh_idx, int sc_idx,
;                       h16* dst, int nrows) {
;     ...
;   for (int row = gw; row < nrows; row += nw) {
;     const float* xr = row < TL ? xlat + (size_t)row * 1024 : xctx + (size_t)(row - TL) * 1024;
;     const int mrow = row < TL ? (row >> 12) : 8;
;     const float* mr = mod + ((size_t)l * 9 + mrow) * 6144;
;     f32x4 v[4];
;     float ss = 0.f;
; #pragma unroll
;     for (int i = 0; i < 4; ++i) {
;       v[i] = *(const f32x4*)(xr + lane * 4 + 256 * i);
;       ss += v[i].x * v[i].x + v[i].y * v[i].y + v[i].z * v[i].z + v[i].w * v[i].w;
;     }
;     ss = wave_sum(ss);
;     const float rstd = rsqrtf(ss * (1.f / 1024.f) + EPS);
; #pragma unroll
;     for (int i = 0; i < 4; ++i) {
;       const int c = lane * 4 + 256 * i;
;       f32x4 g = *(const f32x4*)(gain + c), sc = *(const f32x4*)(mr + sc_idx * 1024 + c), sh = *(const f32x4*)(mr + sh_idx * 1024 + c);
;       h16x4 o;
;       o.x = (h16)(v[i].x * rstd * g.x * (1.f + sc.x) + sh.x);
;       o.y = (h16)(v[i].y * rstd * g.y * (1.f + sc.y) + sh.y);
;       o.z = (h16)(v[i].z * rstd * g.z * (1.f + sc.z) + sh.z);
;       o.w = (h16)(v[i].w * rstd * g.w * (1.f + sc.w) + sh.w);
;       *(h16x4*)(dst + (size_t)row * 1024 + c) = o;
;     }
;   }
	v_mul_f32_e32 v162, v162, v112
	v_mul_f32_e32 v163, v163, v112
	v_mul_f32_e32 v164, v164, v112
	v_mul_f32_e32 v165, v165, v112
	v_mul_f32_e32 v166, v166, v112
	v_mul_f32_e32 v167, v167, v112
	v_mul_f32_e32 v168, v168, v112
	v_mul_f32_e32 v169, v169, v112
	v_mul_f32_e32 v170, v170, v112
	v_mul_f32_e32 v171, v171, v112
	v_mul_f32_e32 v172, v172, v112
	v_mul_f32_e32 v173, v173, v112
	v_mul_f32_e32 v174, v174, v112
	v_mul_f32_e32 v175, v175, v112
	v_mul_f32_e32 v176, v176, v112
	v_mul_f32_e32 v177, v177, v112
	v_mul_f32_e32 v162, v80, v162
	v_mul_f32_e32 v163, v81, v163
	v_mul_f32_e32 v164, v82, v164
	v_mul_f32_e32 v165, v83, v165
	v_mul_f32_e32 v166, v84, v166
	v_mul_f32_e32 v167, v85, v167
	v_mul_f32_e32 v168, v86, v168
	v_mul_f32_e32 v169, v87, v169
	v_mul_f32_e32 v170, v88, v170
	v_mul_f32_e32 v171, v89, v171
	v_mul_f32_e32 v172, v90, v172
	v_mul_f32_e32 v173, v91, v173
	v_mul_f32_e32 v174, v92, v174
	v_mul_f32_e32 v175, v93, v175
	v_mul_f32_e32 v176, v94, v176
	v_mul_f32_e32 v177, v95, v177
	v_add_f32_e32 v96, 1.0, v96
	v_add_f32_e32 v97, 1.0, v97
	v_add_f32_e32 v98, 1.0, v98
	v_add_f32_e32 v99, 1.0, v99
	v_add_f32_e32 v100, 1.0, v100
	v_add_f32_e32 v101, 1.0, v101
	v_add_f32_e32 v102, 1.0, v102
	v_add_f32_e32 v103, 1.0, v103
	v_add_f32_e32 v104, 1.0, v104
	v_add_f32_e32 v105, 1.0, v105
	v_add_f32_e32 v106, 1.0, v106
	v_add_f32_e32 v107, 1.0, v107
	v_add_f32_e32 v108, 1.0, v108
	v_add_f32_e32 v109, 1.0, v109
	v_add_f32_e32 v110, 1.0, v110
	v_add_f32_e32 v111, 1.0, v111
	v_fma_f32 v162, v96, v162, v178
	v_fma_f32 v163, v97, v163, v179
	v_fma_f32 v164, v98, v164, v180
	v_fma_f32 v165, v99, v165, v181
	v_fma_f32 v166, v100, v166, v182
	v_fma_f32 v167, v101, v167, v183
	v_fma_f32 v168, v102, v168, v184
	v_fma_f32 v169, v103, v169, v185
	v_fma_f32 v170, v104, v170, v186
	v_fma_f32 v171, v105, v171, v187
	v_fma_f32 v172, v106, v172, v188
	v_fma_f32 v173, v107, v173, v189
	v_fma_f32 v174, v108, v174, v190
	v_fma_f32 v175, v109, v175, v191
	v_fma_f32 v176, v110, v176, v192
	v_fma_f32 v177, v111, v177, v193
	v_cvt_pk_f16_f32 v114, v162, v163
	v_cvt_pk_f16_f32 v115, v164, v165
	v_cvt_pk_f16_f32 v116, v166, v167
	v_cvt_pk_f16_f32 v117, v168, v169
	v_cvt_pk_f16_f32 v118, v170, v171
	v_cvt_pk_f16_f32 v119, v172, v173
	v_cvt_pk_f16_f32 v120, v174, v175
	v_cvt_pk_f16_f32 v121, v176, v177
	global_store_dwordx2 v128, v[114:115], s[24:25]
	global_store_dwordx2 v128, v[116:117], s[24:25] offset:512
	global_store_dwordx2 v128, v[118:119], s[24:25] offset:1024
	global_store_dwordx2 v128, v[120:121], s[24:25] offset:1536
	s_add_i32 s3, s3, s2
	s_branch .Lrn2_exit
.Lrn2_tail1:
	s_waitcnt vmcnt(8)
	v_mul_f32_e32 v112, v33, v33
	v_mul_f32_e32 v113, v37, v37
	v_mul_f32_e32 v114, v41, v41
	v_mul_f32_e32 v115, v45, v45
	v_fmac_f32_e32 v112, v32, v32
	v_fmac_f32_e32 v113, v36, v36
	v_fmac_f32_e32 v114, v40, v40
	v_fmac_f32_e32 v115, v44, v44
	v_fmac_f32_e32 v112, v34, v34
	v_fmac_f32_e32 v113, v38, v38
	v_fmac_f32_e32 v114, v42, v42
	v_fmac_f32_e32 v115, v46, v46
	v_fmac_f32_e32 v112, v35, v35
	v_fmac_f32_e32 v113, v39, v39
	v_fmac_f32_e32 v114, v43, v43
	v_fmac_f32_e32 v115, v47, v47
	v_add_f32_e32 v112, v112, v113
	v_add_f32_e32 v112, v112, v114
	v_add_f32_e32 v112, v112, v115
	s_nop 1
	v_add_f32_dpp v112, v112, v112 quad_perm:[1,0,3,2] row_mask:0xf bank_mask:0xf bound_ctrl:1
	s_nop 1
	v_add_f32_dpp v112, v112, v112 quad_perm:[2,3,0,1] row_mask:0xf bank_mask:0xf bound_ctrl:1
	s_nop 1
	v_add_f32_dpp v112, v112, v112 row_half_mirror row_mask:0xf bank_mask:0xf bound_ctrl:1
	s_nop 1
	v_add_f32_dpp v112, v112, v112 row_mirror row_mask:0xf bank_mask:0xf bound_ctrl:1
	s_nop 1
	ds_swizzle_b32 v113, v112 offset:swizzle(SWAP,16)
	s_waitcnt lgkmcnt(0)
	v_add_f32_e32 v112, v112, v113
	v_mov_b32_e32 v113, v112
	s_nop 1
	v_permlane32_swap_b32_e32 v112, v113
	v_add_f32_e32 v112, v112, v113
	v_fmamk_f32 v112, v112, 0x3a800000, v224
	v_rsq_f32_e32 v112, v112
	s_waitcnt vmcnt(0)
	v_mul_f32_e32 v32, v32, v112
	v_mul_f32_e32 v33, v33, v112
	v_mul_f32_e32 v34, v34, v112
	v_mul_f32_e32 v35, v35, v112
	v_mul_f32_e32 v36, v36, v112
	v_mul_f32_e32 v37, v37, v112
	v_mul_f32_e32 v38, v38, v112
	v_mul_f32_e32 v39, v39, v112
	v_mul_f32_e32 v40, v40, v112
	v_mul_f32_e32 v41, v41, v112
	v_mul_f32_e32 v42, v42, v112
	v_mul_f32_e32 v43, v43, v112
	v_mul_f32_e32 v44, v44, v112
	v_mul_f32_e32 v45, v45, v112
	v_mul_f32_e32 v46, v46, v112
	v_mul_f32_e32 v47, v47, v112
	v_mul_f32_e32 v32, v80, v32
	v_mul_f32_e32 v33, v81, v33
	v_mul_f32_e32 v34, v82, v34
	v_mul_f32_e32 v35, v83, v35
	v_mul_f32_e32 v36, v84, v36
	v_mul_f32_e32 v37, v85, v37
	v_mul_f32_e32 v38, v86, v38
	v_mul_f32_e32 v39, v87, v39
	v_mul_f32_e32 v40, v88, v40
	v_mul_f32_e32 v41, v89, v41
	v_mul_f32_e32 v42, v90, v42
	v_mul_f32_e32 v43, v91, v43
	v_mul_f32_e32 v44, v92, v44
	v_mul_f32_e32 v45, v93, v45
	v_mul_f32_e32 v46, v94, v46
	v_mul_f32_e32 v47, v95, v47
	v_add_f32_e32 v96, 1.0, v96
	v_add_f32_e32 v97, 1.0, v97
	v_add_f32_e32 v98, 1.0, v98
	v_add_f32_e32 v99, 1.0, v99
	v_add_f32_e32 v100, 1.0, v100
	v_add_f32_e32 v101, 1.0, v101
	v_add_f32_e32 v102, 1.0, v102
	v_add_f32_e32 v103, 1.0, v103
	v_add_f32_e32 v104, 1.0, v104
	v_add_f32_e32 v105, 1.0, v105
	v_add_f32_e32 v106, 1.0, v106
	v_add_f32_e32 v107, 1.0, v107
	v_add_f32_e32 v108, 1.0, v108
	v_add_f32_e32 v109, 1.0, v109
	v_add_f32_e32 v110, 1.0, v110
	v_add_f32_e32 v111, 1.0, v111
	v_fma_f32 v32, v96, v32, v178
	v_fma_f32 v33, v97, v33, v179
	v_fma_f32 v34, v98, v34, v180
	v_fma_f32 v35, v99, v35, v181
	v_fma_f32 v36, v100, v36, v182
	v_fma_f32 v37, v101, v37, v183
	v_fma_f32 v38, v102, v38, v184
	v_fma_f32 v39, v103, v39, v185
	v_fma_f32 v40, v104, v40, v186
	v_fma_f32 v41, v105, v41, v187
	v_fma_f32 v42, v106, v42, v188
	v_fma_f32 v43, v107, v43, v189
	v_fma_f32 v44, v108, v44, v190
	v_fma_f32 v45, v109, v45, v191
	v_fma_f32 v46, v110, v46, v192
	v_fma_f32 v47, v111, v47, v193
	v_cvt_pk_f16_f32 v114, v32, v33
	v_cvt_pk_f16_f32 v115, v34, v35
	v_cvt_pk_f16_f32 v116, v36, v37
	v_cvt_pk_f16_f32 v117, v38, v39
	v_cvt_pk_f16_f32 v118, v40, v41
	v_cvt_pk_f16_f32 v119, v42, v43
	v_cvt_pk_f16_f32 v120, v44, v45
	v_cvt_pk_f16_f32 v121, v46, v47
	global_store_dwordx2 v128, v[114:115], s[24:25]
	global_store_dwordx2 v128, v[116:117], s[24:25] offset:512
	global_store_dwordx2 v128, v[118:119], s[24:25] offset:1024
	global_store_dwordx2 v128, v[120:121], s[24:25] offset:1536
	s_add_i32 s3, s3, s2
	s_cmp_lt_i32 s3, 0x8800
	s_cbranch_scc0 .Lrn2_exit
; DI void rows_norm_mod(const P& p, const float* xlat, const float* xctx, int l, const float* gain, int sh_idx, int sc_idx,
;                       h16* dst, int nrows) {
;     ...
;   for (int row = gw; row < nrows; row += nw) {
;     const float* xr = row < TL ? xlat + (size_t)row * 1024 : xctx + (size_t)(row - TL) * 1024;
;     const int mrow = row < TL ? (row >> 12) : 8;
;     const float* mr = mod + ((size_t)l * 9 + mrow) * 6144;
;     f32x4 v[4];
;     float ss = 0.f;
; #pragma unroll
;     for (int i = 0; i < 4; ++i) {
;       v[i] = *(const f32x4*)(xr + lane * 4 + 256 * i);
;       ss += v[i].x * v[i].x + v[i].y * v[i].y + v[i].z * v[i].z + v[i].w * v[i].w;
;     }
;     ss = wave_sum(ss);
;     const float rstd = rsqrtf(ss * (1.f / 1024.f) + EPS);
; #pragma unroll
;     for (int i = 0; i < 4; ++i) {
;       const int c = lane * 4 + 256 * i;
;       f32x4 g = *(const f32x4*)(gain + c), sc = *(const f32x4*)(mr + sc_idx * 1024 + c), sh = *(const f32x4*)(mr + sh_idx * 1024 + c);
;       h16x4 o;
;       o.x = (h16)(v[i].x * rstd * g.x * (1.f + sc.x) + sh.x);
;       o.y = (h16)(v[i].y * rstd * g.y * (1.f + sc.y) + sh.y);
;       o.z = (h16)(v[i].z * rstd * g.z * (1.f + sc.z) + sh.z);
;       o.w = (h16)(v[i].w * rstd * g.w * (1.f + sc.w) + sh.w);
;       *(h16x4*)(dst + (size_t)row * 1024 + c) = o;
;     }
;   }
	s_lshr_b32 s6, s3, 12
	s_cmp_lt_u32 s3, 0x8000
	s_cselect_b32 s6, s6, 8
	s_mul_i32 s6, s6, 0x6000
	s_add_u32 s22, s4, s6
	s_addc_u32 s23, s5, 0
	s_add_u32 s32, s22, 0x1000
	s_addc_u32 s33, s23, 0
	s_lshl_b32 s6, s3, 11
	s_add_u32 s24, s18, s6
	s_addc_u32 s25, s19, 0
	global_load_dwordx4 v[96:99], v0, s[32:33]
	global_load_dwordx4 v[100:103], v0, s[32:33] offset:1024
	global_load_dwordx4 v[104:107], v0, s[32:33] offset:2048
	global_load_dwordx4 v[108:111], v0, s[32:33] offset:3072
	global_load_dwordx4 v[178:181], v0, s[22:23]
	global_load_dwordx4 v[182:185], v0, s[22:23] offset:1024
	global_load_dwordx4 v[186:189], v0, s[22:23] offset:2048
	global_load_dwordx4 v[190:193], v0, s[22:23] offset:3072
	s_waitcnt vmcnt(8)
	v_mul_f32_e32 v112, v163, v163
	v_mul_f32_e32 v113, v167, v167
	v_mul_f32_e32 v114, v171, v171
	v_mul_f32_e32 v115, v175, v175
	v_fmac_f32_e32 v112, v162, v162
	v_fmac_f32_e32 v113, v166, v166
	v_fmac_f32_e32 v114, v170, v170
	v_fmac_f32_e32 v115, v174, v174
	v_fmac_f32_e32 v112, v164, v164
	v_fmac_f32_e32 v113, v168, v168
	v_fmac_f32_e32 v114, v172, v172
	v_fmac_f32_e32 v115, v176, v176
	v_fmac_f32_e32 v112, v165, v165
	v_fmac_f32_e32 v113, v169, v169
	v_fmac_f32_e32 v114, v173, v173
	v_fmac_f32_e32 v115, v177, v177
	v_add_f32_e32 v112, v112, v113
	v_add_f32_e32 v112, v112, v114
	v_add_f32_e32 v112, v112, v115
	s_nop 1
	v_add_f32_dpp v112, v112, v112 quad_perm:[1,0,3,2] row_mask:0xf bank_mask:0xf bound_ctrl:1
	s_nop 1
	v_add_f32_dpp v112, v112, v112 quad_perm:[2,3,0,1] row_mask:0xf bank_mask:0xf bound_ctrl:1
	s_nop 1
	v_add_f32_dpp v112, v112, v112 row_half_mirror row_mask:0xf bank_mask:0xf bound_ctrl:1
	s_nop 1
	v_add_f32_dpp v112, v112, v112 row_mirror row_mask:0xf bank_mask:0xf bound_ctrl:1
	s_nop 1
	ds_swizzle_b32 v113, v112 offset:swizzle(SWAP,16)
	s_waitcnt lgkmcnt(0)
	v_add_f32_e32 v112, v112, v113
	v_mov_b32_e32 v113, v112
	s_nop 1
	v_permlane32_swap_b32_e32 v112, v113
	v_add_f32_e32 v112, v112, v113
	v_fmamk_f32 v112, v112, 0x3a800000, v224
	v_rsq_f32_e32 v112, v112
	s_waitcnt vmcnt(0)
	v_mul_f32_e32 v162, v162, v112
	v_mul_f32_e32 v163, v163, v112
	v_mul_f32_e32 v164, v164, v112
	v_mul_f32_e32 v165, v165, v112
	v_mul_f32_e32 v166, v166, v112
	v_mul_f32_e32 v167, v167, v112
	v_mul_f32_e32 v168, v168, v112
	v_mul_f32_e32 v169, v169, v112
	v_mul_f32_e32 v170, v170, v112
	v_mul_f32_e32 v171, v171, v112
	v_mul_f32_e32 v172, v172, v112
	v_mul_f32_e32 v173, v173, v112
	v_mul_f32_e32 v174, v174, v112
	v_mul_f32_e32 v175, v175, v112
	v_mul_f32_e32 v176, v176, v112
	v_mul_f32_e32 v177, v177, v112
	v_mul_f32_e32 v162, v80, v162
	v_mul_f32_e32 v163, v81, v163
	v_mul_f32_e32 v164, v82, v164
	v_mul_f32_e32 v165, v83, v165
	v_mul_f32_e32 v166, v84, v166
	v_mul_f32_e32 v167, v85, v167
	v_mul_f32_e32 v168, v86, v168
	v_mul_f32_e32 v169, v87, v169
	v_mul_f32_e32 v170, v88, v170
	v_mul_f32_e32 v171, v89, v171
	v_mul_f32_e32 v172, v90, v172
	v_mul_f32_e32 v173, v91, v173
	v_mul_f32_e32 v174, v92, v174
	v_mul_f32_e32 v175, v93, v175
	v_mul_f32_e32 v176, v94, v176
	v_mul_f32_e32 v177, v95, v177
	v_add_f32_e32 v96, 1.0, v96
	v_add_f32_e32 v97, 1.0, v97
	v_add_f32_e32 v98, 1.0, v98
	v_add_f32_e32 v99, 1.0, v99
	v_add_f32_e32 v100, 1.0, v100
	v_add_f32_e32 v101, 1.0, v101
	v_add_f32_e32 v102, 1.0, v102
	v_add_f32_e32 v103, 1.0, v103
	v_add_f32_e32 v104, 1.0, v104
	v_add_f32_e32 v105, 1.0, v105
	v_add_f32_e32 v106, 1.0, v106
	v_add_f32_e32 v107, 1.0, v107
	v_add_f32_e32 v108, 1.0, v108
	v_add_f32_e32 v109, 1.0, v109
	v_add_f32_e32 v110, 1.0, v110
	v_add_f32_e32 v111, 1.0, v111
	v_fma_f32 v162, v96, v162, v178
	v_fma_f32 v163, v97, v163, v179
	v_fma_f32 v164, v98, v164, v180
	v_fma_f32 v165, v99, v165, v181
	v_fma_f32 v166, v100, v166, v182
	v_fma_f32 v167, v101, v167, v183
	v_fma_f32 v168, v102, v168, v184
	v_fma_f32 v169, v103, v169, v185
	v_fma_f32 v170, v104, v170, v186
	v_fma_f32 v171, v105, v171, v187
	v_fma_f32 v172, v106, v172, v188
	v_fma_f32 v173, v107, v173, v189
	v_fma_f32 v174, v108, v174, v190
	v_fma_f32 v175, v109, v175, v191
	v_fma_f32 v176, v110, v176, v192
	v_fma_f32 v177, v111, v177, v193
	v_cvt_pk_f16_f32 v114, v162, v163
	v_cvt_pk_f16_f32 v115, v164, v165
	v_cvt_pk_f16_f32 v116, v166, v167
	v_cvt_pk_f16_f32 v117, v168, v169
	v_cvt_pk_f16_f32 v118, v170, v171
	v_cvt_pk_f16_f32 v119, v172, v173
	v_cvt_pk_f16_f32 v120, v174, v175
	v_cvt_pk_f16_f32 v121, v176, v177
	global_store_dwordx2 v128, v[114:115], s[24:25]
	global_store_dwordx2 v128, v[116:117], s[24:25] offset:512
	global_store_dwordx2 v128, v[118:119], s[24:25] offset:1024
	global_store_dwordx2 v128, v[120:121], s[24:25] offset:1536
	s_add_i32 s3, s3, s2
	s_cmp_lt_i32 s3, 0x8800
	s_cbranch_scc0 .Lrn2_exit
; DI void rows_norm_mod(const P& p, const float* xlat, const float* xctx, int l, const float* gain, int sh_idx, int sc_idx,
;                       h16* dst, int nrows) {
;     ...
;   for (int row = gw; row < nrows; row += nw) {
;     const float* xr = row < TL ? xlat + (size_t)row * 1024 : xctx + (size_t)(row - TL) * 1024;
;     const int mrow = row < TL ? (row >> 12) : 8;
;     const float* mr = mod + ((size_t)l * 9 + mrow) * 6144;
;     f32x4 v[4];
;     float ss = 0.f;
; #pragma unroll
;     for (int i = 0; i < 4; ++i) {
;       v[i] = *(const f32x4*)(xr + lane * 4 + 256 * i);
;       ss += v[i].x * v[i].x + v[i].y * v[i].y + v[i].z * v[i].z + v[i].w * v[i].w;
;     }
;     ss = wave_sum(ss);
;     const float rstd = rsqrtf(ss * (1.f / 1024.f) + EPS);
; #pragma unroll
;     for (int i = 0; i < 4; ++i) {
;       const int c = lane * 4 + 256 * i;
;       f32x4 g = *(const f32x4*)(gain + c), sc = *(const f32x4*)(mr + sc_idx * 1024 + c), sh = *(const f32x4*)(mr + sh_idx * 1024 + c);
;       h16x4 o;
;       o.x = (h16)(v[i].x * rstd * g.x * (1.f + sc.x) + sh.x);
;       o.y = (h16)(v[i].y * rstd * g.y * (1.f + sc.y) + sh.y);
;       o.z = (h16)(v[i].z * rstd * g.z * (1.f + sc.z) + sh.z);
;       o.w = (h16)(v[i].w * rstd * g.w * (1.f + sc.w) + sh.w);
;       *(h16x4*)(dst + (size_t)row * 1024 + c) = o;
;     }
;   }
	s_lshr_b32 s6, s3, 12
	s_cmp_lt_u32 s3, 0x8000
	s_cselect_b32 s6, s6, 8
	s_mul_i32 s6, s6, 0x6000
	s_add_u32 s22, s4, s6
	s_addc_u32 s23, s5, 0
	s_add_u32 s32, s22, 0x1000
	s_addc_u32 s33, s23, 0
	s_lshl_b32 s6, s3, 11
	s_add_u32 s24, s18, s6
	s_addc_u32 s25, s19, 0
	global_load_dwordx4 v[96:99], v0, s[32:33]
	global_load_dwordx4 v[100:103], v0, s[32:33] offset:1024
	global_load_dwordx4 v[104:107], v0, s[32:33] offset:2048
	global_load_dwordx4 v[108:111], v0, s[32:33] offset:3072
	global_load_dwordx4 v[178:181], v0, s[22:23]
	global_load_dwordx4 v[182:185], v0, s[22:23] offset:1024
	global_load_dwordx4 v[186:189], v0, s[22:23] offset:2048
	global_load_dwordx4 v[190:193], v0, s[22:23] offset:3072
	s_waitcnt vmcnt(8)
	v_mul_f32_e32 v112, v205, v205
	v_mul_f32_e32 v113, v209, v209
	v_mul_f32_e32 v114, v213, v213
	v_mul_f32_e32 v115, v217, v217
	v_fmac_f32_e32 v112, v204, v204
	v_fmac_f32_e32 v113, v208, v208
	v_fmac_f32_e32 v114, v212, v212
	v_fmac_f32_e32 v115, v216, v216
	v_fmac_f32_e32 v112, v206, v206
	v_fmac_f32_e32 v113, v210, v210
	v_fmac_f32_e32 v114, v214, v214
	v_fmac_f32_e32 v115, v218, v218
	v_fmac_f32_e32 v112, v207, v207
	v_fmac_f32_e32 v113, v211, v211
	v_fmac_f32_e32 v114, v215, v215
	v_fmac_f32_e32 v115, v219, v219
	v_add_f32_e32 v112, v112, v113
	v_add_f32_e32 v112, v112, v114
	v_add_f32_e32 v112, v112, v115
	s_nop 1
	v_add_f32_dpp v112, v112, v112 quad_perm:[1,0,3,2] row_mask:0xf bank_mask:0xf bound_ctrl:1
	s_nop 1
	v_add_f32_dpp v112, v112, v112 quad_perm:[2,3,0,1] row_mask:0xf bank_mask:0xf bound_ctrl:1
	s_nop 1
	v_add_f32_dpp v112, v112, v112 row_half_mirror row_mask:0xf bank_mask:0xf bound_ctrl:1
	s_nop 1
	v_add_f32_dpp v112, v112, v112 row_mirror row_mask:0xf bank_mask:0xf bound_ctrl:1
	s_nop 1
	ds_swizzle_b32 v113, v112 offset:swizzle(SWAP,16)
	s_waitcnt lgkmcnt(0)
	v_add_f32_e32 v112, v112, v113
	v_mov_b32_e32 v113, v112
	s_nop 1
	v_permlane32_swap_b32_e32 v112, v113
	v_add_f32_e32 v112, v112, v113
	v_fmamk_f32 v112, v112, 0x3a800000, v224
	v_rsq_f32_e32 v112, v112
	s_waitcnt vmcnt(0)
	v_mul_f32_e32 v204, v204, v112
	v_mul_f32_e32 v205, v205, v112
	v_mul_f32_e32 v206, v206, v112
	v_mul_f32_e32 v207, v207, v112
	v_mul_f32_e32 v208, v208, v112
	v_mul_f32_e32 v209, v209, v112
	v_mul_f32_e32 v210, v210, v112
	v_mul_f32_e32 v211, v211, v112
	v_mul_f32_e32 v212, v212, v112
	v_mul_f32_e32 v213, v213, v112
	v_mul_f32_e32 v214, v214, v112
	v_mul_f32_e32 v215, v215, v112
	v_mul_f32_e32 v216, v216, v112
	v_mul_f32_e32 v217, v217, v112
	v_mul_f32_e32 v218, v218, v112
	v_mul_f32_e32 v219, v219, v112
	v_mul_f32_e32 v204, v80, v204
	v_mul_f32_e32 v205, v81, v205
	v_mul_f32_e32 v206, v82, v206
	v_mul_f32_e32 v207, v83, v207
	v_mul_f32_e32 v208, v84, v208
	v_mul_f32_e32 v209, v85, v209
	v_mul_f32_e32 v210, v86, v210
	v_mul_f32_e32 v211, v87, v211
	v_mul_f32_e32 v212, v88, v212
	v_mul_f32_e32 v213, v89, v213
	v_mul_f32_e32 v214, v90, v214
	v_mul_f32_e32 v215, v91, v215
	v_mul_f32_e32 v216, v92, v216
	v_mul_f32_e32 v217, v93, v217
	v_mul_f32_e32 v218, v94, v218
	v_mul_f32_e32 v219, v95, v219
	v_add_f32_e32 v96, 1.0, v96
	v_add_f32_e32 v97, 1.0, v97
	v_add_f32_e32 v98, 1.0, v98
	v_add_f32_e32 v99, 1.0, v99
	v_add_f32_e32 v100, 1.0, v100
	v_add_f32_e32 v101, 1.0, v101
	v_add_f32_e32 v102, 1.0, v102
	v_add_f32_e32 v103, 1.0, v103
	v_add_f32_e32 v104, 1.0, v104
	v_add_f32_e32 v105, 1.0, v105
	v_add_f32_e32 v106, 1.0, v106
	v_add_f32_e32 v107, 1.0, v107
	v_add_f32_e32 v108, 1.0, v108
	v_add_f32_e32 v109, 1.0, v109
	v_add_f32_e32 v110, 1.0, v110
	v_add_f32_e32 v111, 1.0, v111
	v_fma_f32 v204, v96, v204, v178
	v_fma_f32 v205, v97, v205, v179
	v_fma_f32 v206, v98, v206, v180
	v_fma_f32 v207, v99, v207, v181
	v_fma_f32 v208, v100, v208, v182
	v_fma_f32 v209, v101, v209, v183
	v_fma_f32 v210, v102, v210, v184
	v_fma_f32 v211, v103, v211, v185
	v_fma_f32 v212, v104, v212, v186
	v_fma_f32 v213, v105, v213, v187
	v_fma_f32 v214, v106, v214, v188
	v_fma_f32 v215, v107, v215, v189
	v_fma_f32 v216, v108, v216, v190
	v_fma_f32 v217, v109, v217, v191
	v_fma_f32 v218, v110, v218, v192
	v_fma_f32 v219, v111, v219, v193
	v_cvt_pk_f16_f32 v114, v204, v205
	v_cvt_pk_f16_f32 v115, v206, v207
	v_cvt_pk_f16_f32 v116, v208, v209
	v_cvt_pk_f16_f32 v117, v210, v211
	v_cvt_pk_f16_f32 v118, v212, v213
	v_cvt_pk_f16_f32 v119, v214, v215
	v_cvt_pk_f16_f32 v120, v216, v217
	v_cvt_pk_f16_f32 v121, v218, v219
	global_store_dwordx2 v128, v[114:115], s[24:25]
	global_store_dwordx2 v128, v[116:117], s[24:25] offset:512
	global_store_dwordx2 v128, v[118:119], s[24:25] offset:1024
	global_store_dwordx2 v128, v[120:121], s[24:25] offset:1536
	s_add_i32 s3, s3, s2
	s_branch .Lrn2_exit
; DI void rows_norm_mod(const P& p, const float* xlat, const float* xctx, int l, const float* gain, int sh_idx, int sc_idx,
;                       h16* dst, int nrows) {
;     ...
;   for (int row = gw; row < nrows; row += nw) {
;     const float* xr = row < TL ? xlat + (size_t)row * 1024 : xctx + (size_t)(row - TL) * 1024;
;     const int mrow = row < TL ? (row >> 12) : 8;
;     const float* mr = mod + ((size_t)l * 9 + mrow) * 6144;
;     f32x4 v[4];
;     float ss = 0.f;
; #pragma unroll
;     for (int i = 0; i < 4; ++i) {
;       v[i] = *(const f32x4*)(xr + lane * 4 + 256 * i);
;       ss += v[i].x * v[i].x + v[i].y * v[i].y + v[i].z * v[i].z + v[i].w * v[i].w;
;     }
;     ss = wave_sum(ss);
;     const float rstd = rsqrtf(ss * (1.f / 1024.f) + EPS);
; #pragma unroll
;     for (int i = 0; i < 4; ++i) {
;       const int c = lane * 4 + 256 * i;
;       f32x4 g = *(const f32x4*)(gain + c), sc = *(const f32x4*)(mr + sc_idx * 1024 + c), sh = *(const f32x4*)(mr + sh_idx * 1024 + c);
;       h16x4 o;
;       o.x = (h16)(v[i].x * rstd * g.x * (1.f + sc.x) + sh.x);
;       o.y = (h16)(v[i].y * rstd * g.y * (1.f + sc.y) + sh.y);
;       o.z = (h16)(v[i].z * rstd * g.z * (1.f + sc.z) + sh.z);
;       o.w = (h16)(v[i].w * rstd * g.w * (1.f + sc.w) + sh.w);
;       *(h16x4*)(dst + (size_t)row * 1024 + c) = o;
;     }
;   }
.Lrn2_tail2:
	s_waitcnt vmcnt(8)
	v_mul_f32_e32 v112, v163, v163
	v_mul_f32_e32 v113, v167, v167
	v_mul_f32_e32 v114, v171, v171
	v_mul_f32_e32 v115, v175, v175
	v_fmac_f32_e32 v112, v162, v162
	v_fmac_f32_e32 v113, v166, v166
	v_fmac_f32_e32 v114, v170, v170
	v_fmac_f32_e32 v115, v174, v174
	v_fmac_f32_e32 v112, v164, v164
	v_fmac_f32_e32 v113, v168, v168
	v_fmac_f32_e32 v114, v172, v172
	v_fmac_f32_e32 v115, v176, v176
	v_fmac_f32_e32 v112, v165, v165
	v_fmac_f32_e32 v113, v169, v169
	v_fmac_f32_e32 v114, v173, v173
	v_fmac_f32_e32 v115, v177, v177
	v_add_f32_e32 v112, v112, v113
	v_add_f32_e32 v112, v112, v114
	v_add_f32_e32 v112, v112, v115
	s_nop 1
	v_add_f32_dpp v112, v112, v112 quad_perm:[1,0,3,2] row_mask:0xf bank_mask:0xf bound_ctrl:1
	s_nop 1
	v_add_f32_dpp v112, v112, v112 quad_perm:[2,3,0,1] row_mask:0xf bank_mask:0xf bound_ctrl:1
	s_nop 1
	v_add_f32_dpp v112, v112, v112 row_half_mirror row_mask:0xf bank_mask:0xf bound_ctrl:1
	s_nop 1
	v_add_f32_dpp v112, v112, v112 row_mirror row_mask:0xf bank_mask:0xf bound_ctrl:1
	s_nop 1
	ds_swizzle_b32 v113, v112 offset:swizzle(SWAP,16)
	s_waitcnt lgkmcnt(0)
	v_add_f32_e32 v112, v112, v113
	v_mov_b32_e32 v113, v112
	s_nop 1
	v_permlane32_swap_b32_e32 v112, v113
	v_add_f32_e32 v112, v112, v113
	v_fmamk_f32 v112, v112, 0x3a800000, v224
	v_rsq_f32_e32 v112, v112
	s_waitcnt vmcnt(0)
	v_mul_f32_e32 v162, v162, v112
	v_mul_f32_e32 v163, v163, v112
	v_mul_f32_e32 v164, v164, v112
	v_mul_f32_e32 v165, v165, v112
	v_mul_f32_e32 v166, v166, v112
	v_mul_f32_e32 v167, v167, v112
	v_mul_f32_e32 v168, v168, v112
	v_mul_f32_e32 v169, v169, v112
	v_mul_f32_e32 v170, v170, v112
	v_mul_f32_e32 v171, v171, v112
	v_mul_f32_e32 v172, v172, v112
	v_mul_f32_e32 v173, v173, v112
	v_mul_f32_e32 v174, v174, v112
	v_mul_f32_e32 v175, v175, v112
	v_mul_f32_e32 v176, v176, v112
	v_mul_f32_e32 v177, v177, v112
	v_mul_f32_e32 v162, v80, v162
	v_mul_f32_e32 v163, v81, v163
	v_mul_f32_e32 v164, v82, v164
	v_mul_f32_e32 v165, v83, v165
	v_mul_f32_e32 v166, v84, v166
	v_mul_f32_e32 v167, v85, v167
	v_mul_f32_e32 v168, v86, v168
	v_mul_f32_e32 v169, v87, v169
	v_mul_f32_e32 v170, v88, v170
	v_mul_f32_e32 v171, v89, v171
	v_mul_f32_e32 v172, v90, v172
	v_mul_f32_e32 v173, v91, v173
	v_mul_f32_e32 v174, v92, v174
	v_mul_f32_e32 v175, v93, v175
	v_mul_f32_e32 v176, v94, v176
	v_mul_f32_e32 v177, v95, v177
	v_add_f32_e32 v96, 1.0, v96
	v_add_f32_e32 v97, 1.0, v97
	v_add_f32_e32 v98, 1.0, v98
	v_add_f32_e32 v99, 1.0, v99
	v_add_f32_e32 v100, 1.0, v100
	v_add_f32_e32 v101, 1.0, v101
	v_add_f32_e32 v102, 1.0, v102
	v_add_f32_e32 v103, 1.0, v103
	v_add_f32_e32 v104, 1.0, v104
	v_add_f32_e32 v105, 1.0, v105
	v_add_f32_e32 v106, 1.0, v106
	v_add_f32_e32 v107, 1.0, v107
	v_add_f32_e32 v108, 1.0, v108
	v_add_f32_e32 v109, 1.0, v109
	v_add_f32_e32 v110, 1.0, v110
	v_add_f32_e32 v111, 1.0, v111
	v_fma_f32 v162, v96, v162, v178
	v_fma_f32 v163, v97, v163, v179
	v_fma_f32 v164, v98, v164, v180
	v_fma_f32 v165, v99, v165, v181
	v_fma_f32 v166, v100, v166, v182
	v_fma_f32 v167, v101, v167, v183
	v_fma_f32 v168, v102, v168, v184
	v_fma_f32 v169, v103, v169, v185
	v_fma_f32 v170, v104, v170, v186
	v_fma_f32 v171, v105, v171, v187
	v_fma_f32 v172, v106, v172, v188
	v_fma_f32 v173, v107, v173, v189
	v_fma_f32 v174, v108, v174, v190
	v_fma_f32 v175, v109, v175, v191
	v_fma_f32 v176, v110, v176, v192
	v_fma_f32 v177, v111, v177, v193
	v_cvt_pk_f16_f32 v114, v162, v163
	v_cvt_pk_f16_f32 v115, v164, v165
	v_cvt_pk_f16_f32 v116, v166, v167
	v_cvt_pk_f16_f32 v117, v168, v169
	v_cvt_pk_f16_f32 v118, v170, v171
	v_cvt_pk_f16_f32 v119, v172, v173
	v_cvt_pk_f16_f32 v120, v174, v175
	v_cvt_pk_f16_f32 v121, v176, v177
	global_store_dwordx2 v128, v[114:115], s[24:25]
	global_store_dwordx2 v128, v[116:117], s[24:25] offset:512
	global_store_dwordx2 v128, v[118:119], s[24:25] offset:1024
	global_store_dwordx2 v128, v[120:121], s[24:25] offset:1536
	s_add_i32 s3, s3, s2
	s_cmp_lt_i32 s3, 0x8800
	s_cbranch_scc0 .Lrn2_exit
	s_lshr_b32 s6, s3, 12
	s_cmp_lt_u32 s3, 0x8000
	s_cselect_b32 s6, s6, 8
	s_mul_i32 s6, s6, 0x6000
	s_add_u32 s22, s4, s6
	s_addc_u32 s23, s5, 0
	s_add_u32 s32, s22, 0x1000
	s_addc_u32 s33, s23, 0
	s_lshl_b32 s6, s3, 11
	s_add_u32 s24, s18, s6
	s_addc_u32 s25, s19, 0
	global_load_dwordx4 v[96:99], v0, s[32:33]
	global_load_dwordx4 v[100:103], v0, s[32:33] offset:1024
	global_load_dwordx4 v[104:107], v0, s[32:33] offset:2048
	global_load_dwordx4 v[108:111], v0, s[32:33] offset:3072
	global_load_dwordx4 v[178:181], v0, s[22:23]
	global_load_dwordx4 v[182:185], v0, s[22:23] offset:1024
	global_load_dwordx4 v[186:189], v0, s[22:23] offset:2048
	global_load_dwordx4 v[190:193], v0, s[22:23] offset:3072
	s_waitcnt vmcnt(8)
	v_mul_f32_e32 v112, v205, v205
	v_mul_f32_e32 v113, v209, v209
	v_mul_f32_e32 v114, v213, v213
	v_mul_f32_e32 v115, v217, v217
	v_fmac_f32_e32 v112, v204, v204
	v_fmac_f32_e32 v113, v208, v208
	v_fmac_f32_e32 v114, v212, v212
	v_fmac_f32_e32 v115, v216, v216
	v_fmac_f32_e32 v112, v206, v206
	v_fmac_f32_e32 v113, v210, v210
	v_fmac_f32_e32 v114, v214, v214
	v_fmac_f32_e32 v115, v218, v218
	v_fmac_f32_e32 v112, v207, v207
	v_fmac_f32_e32 v113, v211, v211
	v_fmac_f32_e32 v114, v215, v215
	v_fmac_f32_e32 v115, v219, v219
	v_add_f32_e32 v112, v112, v113
	v_add_f32_e32 v112, v112, v114
	v_add_f32_e32 v112, v112, v115
	s_nop 1
	v_add_f32_dpp v112, v112, v112 quad_perm:[1,0,3,2] row_mask:0xf bank_mask:0xf bound_ctrl:1
	s_nop 1
	v_add_f32_dpp v112, v112, v112 quad_perm:[2,3,0,1] row_mask:0xf bank_mask:0xf bound_ctrl:1
	s_nop 1
	v_add_f32_dpp v112, v112, v112 row_half_mirror row_mask:0xf bank_mask:0xf bound_ctrl:1
	s_nop 1
	v_add_f32_dpp v112, v112, v112 row_mirror row_mask:0xf bank_mask:0xf bound_ctrl:1
	s_nop 1
	ds_swizzle_b32 v113, v112 offset:swizzle(SWAP,16)
	s_waitcnt lgkmcnt(0)
; DI void rows_norm_mod(const P& p, const float* xlat, const float* xctx, int l, const float* gain, int sh_idx, int sc_idx,
;                       h16* dst, int nrows) {
;     ...
;   for (int row = gw; row < nrows; row += nw) {
;     const float* xr = row < TL ? xlat + (size_t)row * 1024 : xctx + (size_t)(row - TL) * 1024;
;     const int mrow = row < TL ? (row >> 12) : 8;
;     const float* mr = mod + ((size_t)l * 9 + mrow) * 6144;
;     f32x4 v[4];
;     float ss = 0.f;
; #pragma unroll
;     for (int i = 0; i < 4; ++i) {
;       v[i] = *(const f32x4*)(xr + lane * 4 + 256 * i);
;       ss += v[i].x * v[i].x + v[i].y * v[i].y + v[i].z * v[i].z + v[i].w * v[i].w;
;     }
;     ss = wave_sum(ss);
;     const float rstd = rsqrtf(ss * (1.f / 1024.f) + EPS);
; #pragma unroll
;     for (int i = 0; i < 4; ++i) {
;       const int c = lane * 4 + 256 * i;
;       f32x4 g = *(const f32x4*)(gain + c), sc = *(const f32x4*)(mr + sc_idx * 1024 + c), sh = *(const f32x4*)(mr + sh_idx * 1024 + c);
;       h16x4 o;
;       o.x = (h16)(v[i].x * rstd * g.x * (1.f + sc.x) + sh.x);
;       o.y = (h16)(v[i].y * rstd * g.y * (1.f + sc.y) + sh.y);
;       o.z = (h16)(v[i].z * rstd * g.z * (1.f + sc.z) + sh.z);
;       o.w = (h16)(v[i].w * rstd * g.w * (1.f + sc.w) + sh.w);
;       *(h16x4*)(dst + (size_t)row * 1024 + c) = o;
;     }
;   }
	v_add_f32_e32 v112, v112, v113
	v_mov_b32_e32 v113, v112
	s_nop 1
	v_permlane32_swap_b32_e32 v112, v113
	v_add_f32_e32 v112, v112, v113
	v_fmamk_f32 v112, v112, 0x3a800000, v224
	v_rsq_f32_e32 v112, v112
	s_waitcnt vmcnt(0)
	v_mul_f32_e32 v204, v204, v112
	v_mul_f32_e32 v205, v205, v112
	v_mul_f32_e32 v206, v206, v112
	v_mul_f32_e32 v207, v207, v112
	v_mul_f32_e32 v208, v208, v112
	v_mul_f32_e32 v209, v209, v112
	v_mul_f32_e32 v210, v210, v112
	v_mul_f32_e32 v211, v211, v112
	v_mul_f32_e32 v212, v212, v112
	v_mul_f32_e32 v213, v213, v112
	v_mul_f32_e32 v214, v214, v112
	v_mul_f32_e32 v215, v215, v112
	v_mul_f32_e32 v216, v216, v112
	v_mul_f32_e32 v217, v217, v112
	v_mul_f32_e32 v218, v218, v112
	v_mul_f32_e32 v219, v219, v112
	v_mul_f32_e32 v204, v80, v204
	v_mul_f32_e32 v205, v81, v205
	v_mul_f32_e32 v206, v82, v206
	v_mul_f32_e32 v207, v83, v207
	v_mul_f32_e32 v208, v84, v208
	v_mul_f32_e32 v209, v85, v209
	v_mul_f32_e32 v210, v86, v210
	v_mul_f32_e32 v211, v87, v211
	v_mul_f32_e32 v212, v88, v212
	v_mul_f32_e32 v213, v89, v213
	v_mul_f32_e32 v214, v90, v214
	v_mul_f32_e32 v215, v91, v215
	v_mul_f32_e32 v216, v92, v216
	v_mul_f32_e32 v217, v93, v217
	v_mul_f32_e32 v218, v94, v218
	v_mul_f32_e32 v219, v95, v219
	v_add_f32_e32 v96, 1.0, v96
	v_add_f32_e32 v97, 1.0, v97
	v_add_f32_e32 v98, 1.0, v98
	v_add_f32_e32 v99, 1.0, v99
	v_add_f32_e32 v100, 1.0, v100
	v_add_f32_e32 v101, 1.0, v101
	v_add_f32_e32 v102, 1.0, v102
	v_add_f32_e32 v103, 1.0, v103
	v_add_f32_e32 v104, 1.0, v104
	v_add_f32_e32 v105, 1.0, v105
	v_add_f32_e32 v106, 1.0, v106
	v_add_f32_e32 v107, 1.0, v107
	v_add_f32_e32 v108, 1.0, v108
	v_add_f32_e32 v109, 1.0, v109
	v_add_f32_e32 v110, 1.0, v110
	v_add_f32_e32 v111, 1.0, v111
	v_fma_f32 v204, v96, v204, v178
	v_fma_f32 v205, v97, v205, v179
	v_fma_f32 v206, v98, v206, v180
	v_fma_f32 v207, v99, v207, v181
	v_fma_f32 v208, v100, v208, v182
	v_fma_f32 v209, v101, v209, v183
	v_fma_f32 v210, v102, v210, v184
	v_fma_f32 v211, v103, v211, v185
	v_fma_f32 v212, v104, v212, v186
	v_fma_f32 v213, v105, v213, v187
	v_fma_f32 v214, v106, v214, v188
	v_fma_f32 v215, v107, v215, v189
	v_fma_f32 v216, v108, v216, v190
	v_fma_f32 v217, v109, v217, v191
	v_fma_f32 v218, v110, v218, v192
	v_fma_f32 v219, v111, v219, v193
	v_cvt_pk_f16_f32 v114, v204, v205
	v_cvt_pk_f16_f32 v115, v206, v207
	v_cvt_pk_f16_f32 v116, v208, v209
	v_cvt_pk_f16_f32 v117, v210, v211
	v_cvt_pk_f16_f32 v118, v212, v213
	v_cvt_pk_f16_f32 v119, v214, v215
	v_cvt_pk_f16_f32 v120, v216, v217
	v_cvt_pk_f16_f32 v121, v218, v219
	global_store_dwordx2 v128, v[114:115], s[24:25]
	global_store_dwordx2 v128, v[116:117], s[24:25] offset:512
	global_store_dwordx2 v128, v[118:119], s[24:25] offset:1024
	global_store_dwordx2 v128, v[120:121], s[24:25] offset:1536
	s_add_i32 s3, s3, s2
	s_cmp_lt_i32 s3, 0x8800
	s_cbranch_scc0 .Lrn2_exit
	s_lshr_b32 s6, s3, 12
	s_cmp_lt_u32 s3, 0x8000
	s_cselect_b32 s6, s6, 8
	s_mul_i32 s6, s6, 0x6000
	s_add_u32 s22, s4, s6
	s_addc_u32 s23, s5, 0
	s_add_u32 s32, s22, 0x1000
	s_addc_u32 s33, s23, 0
	s_lshl_b32 s6, s3, 11
	s_add_u32 s24, s18, s6
	s_addc_u32 s25, s19, 0
	global_load_dwordx4 v[96:99], v0, s[32:33]
	global_load_dwordx4 v[100:103], v0, s[32:33] offset:1024
	global_load_dwordx4 v[104:107], v0, s[32:33] offset:2048
	global_load_dwordx4 v[108:111], v0, s[32:33] offset:3072
	global_load_dwordx4 v[178:181], v0, s[22:23]
	global_load_dwordx4 v[182:185], v0, s[22:23] offset:1024
	global_load_dwordx4 v[186:189], v0, s[22:23] offset:2048
	global_load_dwordx4 v[190:193], v0, s[22:23] offset:3072
	s_waitcnt vmcnt(8)
	v_mul_f32_e32 v112, v3, v3
	v_mul_f32_e32 v113, v7, v7
	v_mul_f32_e32 v114, v11, v11
	v_mul_f32_e32 v115, v15, v15
	v_fmac_f32_e32 v112, v2, v2
	v_fmac_f32_e32 v113, v6, v6
	v_fmac_f32_e32 v114, v10, v10
	v_fmac_f32_e32 v115, v14, v14
	v_fmac_f32_e32 v112, v4, v4
	v_fmac_f32_e32 v113, v8, v8
	v_fmac_f32_e32 v114, v12, v12
	v_fmac_f32_e32 v115, v16, v16
	v_fmac_f32_e32 v112, v5, v5
	v_fmac_f32_e32 v113, v9, v9
	v_fmac_f32_e32 v114, v13, v13
	v_fmac_f32_e32 v115, v17, v17
	v_add_f32_e32 v112, v112, v113
	v_add_f32_e32 v112, v112, v114
	v_add_f32_e32 v112, v112, v115
	s_nop 1
	v_add_f32_dpp v112, v112, v112 quad_perm:[1,0,3,2] row_mask:0xf bank_mask:0xf bound_ctrl:1
	s_nop 1
	v_add_f32_dpp v112, v112, v112 quad_perm:[2,3,0,1] row_mask:0xf bank_mask:0xf bound_ctrl:1
	s_nop 1
	v_add_f32_dpp v112, v112, v112 row_half_mirror row_mask:0xf bank_mask:0xf bound_ctrl:1
	s_nop 1
	v_add_f32_dpp v112, v112, v112 row_mirror row_mask:0xf bank_mask:0xf bound_ctrl:1
	s_nop 1
	ds_swizzle_b32 v113, v112 offset:swizzle(SWAP,16)
	s_waitcnt lgkmcnt(0)
	v_add_f32_e32 v112, v112, v113
	v_mov_b32_e32 v113, v112
	s_nop 1
	v_permlane32_swap_b32_e32 v112, v113
	v_add_f32_e32 v112, v112, v113
	v_fmamk_f32 v112, v112, 0x3a800000, v224
	v_rsq_f32_e32 v112, v112
	s_waitcnt vmcnt(0)
; DI void rows_norm_mod(const P& p, const float* xlat, const float* xctx, int l, const float* gain, int sh_idx, int sc_idx,
;                       h16* dst, int nrows) {
;     ...
;   for (int row = gw; row < nrows; row += nw) {
;     const float* xr = row < TL ? xlat + (size_t)row * 1024 : xctx + (size_t)(row - TL) * 1024;
;     const int mrow = row < TL ? (row >> 12) : 8;
;     const float* mr = mod + ((size_t)l * 9 + mrow) * 6144;
;     f32x4 v[4];
;     float ss = 0.f;
; #pragma unroll
;     for (int i = 0; i < 4; ++i) {
;       v[i] = *(const f32x4*)(xr + lane * 4 + 256 * i);
;       ss += v[i].x * v[i].x + v[i].y * v[i].y + v[i].z * v[i].z + v[i].w * v[i].w;
;     }
;     ss = wave_sum(ss);
;     const float rstd = rsqrtf(ss * (1.f / 1024.f) + EPS);
; #pragma unroll
;     for (int i = 0; i < 4; ++i) {
;       const int c = lane * 4 + 256 * i;
;       f32x4 g = *(const f32x4*)(gain + c), sc = *(const f32x4*)(mr + sc_idx * 1024 + c), sh = *(const f32x4*)(mr + sh_idx * 1024 + c);
;       h16x4 o;
;       o.x = (h16)(v[i].x * rstd * g.x * (1.f + sc.x) + sh.x);
;       o.y = (h16)(v[i].y * rstd * g.y * (1.f + sc.y) + sh.y);
;       o.z = (h16)(v[i].z * rstd * g.z * (1.f + sc.z) + sh.z);
;       o.w = (h16)(v[i].w * rstd * g.w * (1.f + sc.w) + sh.w);
;       *(h16x4*)(dst + (size_t)row * 1024 + c) = o;
;     }
;   }
	v_mul_f32_e32 v2, v2, v112
	v_mul_f32_e32 v3, v3, v112
	v_mul_f32_e32 v4, v4, v112
	v_mul_f32_e32 v5, v5, v112
	v_mul_f32_e32 v6, v6, v112
	v_mul_f32_e32 v7, v7, v112
	v_mul_f32_e32 v8, v8, v112
	v_mul_f32_e32 v9, v9, v112
	v_mul_f32_e32 v10, v10, v112
	v_mul_f32_e32 v11, v11, v112
	v_mul_f32_e32 v12, v12, v112
	v_mul_f32_e32 v13, v13, v112
	v_mul_f32_e32 v14, v14, v112
	v_mul_f32_e32 v15, v15, v112
	v_mul_f32_e32 v16, v16, v112
	v_mul_f32_e32 v17, v17, v112
	v_mul_f32_e32 v2, v80, v2
	v_mul_f32_e32 v3, v81, v3
	v_mul_f32_e32 v4, v82, v4
	v_mul_f32_e32 v5, v83, v5
	v_mul_f32_e32 v6, v84, v6
	v_mul_f32_e32 v7, v85, v7
	v_mul_f32_e32 v8, v86, v8
	v_mul_f32_e32 v9, v87, v9
	v_mul_f32_e32 v10, v88, v10
	v_mul_f32_e32 v11, v89, v11
	v_mul_f32_e32 v12, v90, v12
	v_mul_f32_e32 v13, v91, v13
	v_mul_f32_e32 v14, v92, v14
	v_mul_f32_e32 v15, v93, v15
	v_mul_f32_e32 v16, v94, v16
	v_mul_f32_e32 v17, v95, v17
	v_add_f32_e32 v96, 1.0, v96
	v_add_f32_e32 v97, 1.0, v97
	v_add_f32_e32 v98, 1.0, v98
	v_add_f32_e32 v99, 1.0, v99
	v_add_f32_e32 v100, 1.0, v100
	v_add_f32_e32 v101, 1.0, v101
	v_add_f32_e32 v102, 1.0, v102
	v_add_f32_e32 v103, 1.0, v103
	v_add_f32_e32 v104, 1.0, v104
	v_add_f32_e32 v105, 1.0, v105
	v_add_f32_e32 v106, 1.0, v106
	v_add_f32_e32 v107, 1.0, v107
	v_add_f32_e32 v108, 1.0, v108
	v_add_f32_e32 v109, 1.0, v109
	v_add_f32_e32 v110, 1.0, v110
	v_add_f32_e32 v111, 1.0, v111
	v_fma_f32 v2, v96, v2, v178
	v_fma_f32 v3, v97, v3, v179
	v_fma_f32 v4, v98, v4, v180
	v_fma_f32 v5, v99, v5, v181
	v_fma_f32 v6, v100, v6, v182
	v_fma_f32 v7, v101, v7, v183
	v_fma_f32 v8, v102, v8, v184
	v_fma_f32 v9, v103, v9, v185
	v_fma_f32 v10, v104, v10, v186
	v_fma_f32 v11, v105, v11, v187
	v_fma_f32 v12, v106, v12, v188
	v_fma_f32 v13, v107, v13, v189
	v_fma_f32 v14, v108, v14, v190
	v_fma_f32 v15, v109, v15, v191
	v_fma_f32 v16, v110, v16, v192
	v_fma_f32 v17, v111, v17, v193
	v_cvt_pk_f16_f32 v114, v2, v3
	v_cvt_pk_f16_f32 v115, v4, v5
	v_cvt_pk_f16_f32 v116, v6, v7
	v_cvt_pk_f16_f32 v117, v8, v9
	v_cvt_pk_f16_f32 v118, v10, v11
	v_cvt_pk_f16_f32 v119, v12, v13
	v_cvt_pk_f16_f32 v120, v14, v15
	v_cvt_pk_f16_f32 v121, v16, v17
	global_store_dwordx2 v128, v[114:115], s[24:25]
	global_store_dwordx2 v128, v[116:117], s[24:25] offset:512
	global_store_dwordx2 v128, v[118:119], s[24:25] offset:1024
	global_store_dwordx2 v128, v[120:121], s[24:25] offset:1536
	s_add_i32 s3, s3, s2
	s_branch .Lrn2_exit
.Lrn2_tail3:
	s_waitcnt vmcnt(8)
	v_mul_f32_e32 v112, v205, v205
	v_mul_f32_e32 v113, v209, v209
	v_mul_f32_e32 v114, v213, v213
	v_mul_f32_e32 v115, v217, v217
	v_fmac_f32_e32 v112, v204, v204
	v_fmac_f32_e32 v113, v208, v208
	v_fmac_f32_e32 v114, v212, v212
	v_fmac_f32_e32 v115, v216, v216
	v_fmac_f32_e32 v112, v206, v206
	v_fmac_f32_e32 v113, v210, v210
	v_fmac_f32_e32 v114, v214, v214
	v_fmac_f32_e32 v115, v218, v218
	v_fmac_f32_e32 v112, v207, v207
	v_fmac_f32_e32 v113, v211, v211
	v_fmac_f32_e32 v114, v215, v215
	v_fmac_f32_e32 v115, v219, v219
	v_add_f32_e32 v112, v112, v113
	v_add_f32_e32 v112, v112, v114
	v_add_f32_e32 v112, v112, v115
	s_nop 1
	v_add_f32_dpp v112, v112, v112 quad_perm:[1,0,3,2] row_mask:0xf bank_mask:0xf bound_ctrl:1
	s_nop 1
	v_add_f32_dpp v112, v112, v112 quad_perm:[2,3,0,1] row_mask:0xf bank_mask:0xf bound_ctrl:1
	s_nop 1
	v_add_f32_dpp v112, v112, v112 row_half_mirror row_mask:0xf bank_mask:0xf bound_ctrl:1
	s_nop 1
	v_add_f32_dpp v112, v112, v112 row_mirror row_mask:0xf bank_mask:0xf bound_ctrl:1
	s_nop 1
	ds_swizzle_b32 v113, v112 offset:swizzle(SWAP,16)
	s_waitcnt lgkmcnt(0)
	v_add_f32_e32 v112, v112, v113
	v_mov_b32_e32 v113, v112
	s_nop 1
	v_permlane32_swap_b32_e32 v112, v113
	v_add_f32_e32 v112, v112, v113
	v_fmamk_f32 v112, v112, 0x3a800000, v224
	v_rsq_f32_e32 v112, v112
	s_waitcnt vmcnt(0)
	v_mul_f32_e32 v204, v204, v112
	v_mul_f32_e32 v205, v205, v112
	v_mul_f32_e32 v206, v206, v112
	v_mul_f32_e32 v207, v207, v112
	v_mul_f32_e32 v208, v208, v112
	v_mul_f32_e32 v209, v209, v112
	v_mul_f32_e32 v210, v210, v112
	v_mul_f32_e32 v211, v211, v112
	v_mul_f32_e32 v212, v212, v112
	v_mul_f32_e32 v213, v213, v112
	v_mul_f32_e32 v214, v214, v112
	v_mul_f32_e32 v215, v215, v112
	v_mul_f32_e32 v216, v216, v112
	v_mul_f32_e32 v217, v217, v112
	v_mul_f32_e32 v218, v218, v112
	v_mul_f32_e32 v219, v219, v112
	v_mul_f32_e32 v204, v80, v204
	v_mul_f32_e32 v205, v81, v205
	v_mul_f32_e32 v206, v82, v206
	v_mul_f32_e32 v207, v83, v207
	v_mul_f32_e32 v208, v84, v208
	v_mul_f32_e32 v209, v85, v209
	v_mul_f32_e32 v210, v86, v210
	v_mul_f32_e32 v211, v87, v211
	v_mul_f32_e32 v212, v88, v212
	v_mul_f32_e32 v213, v89, v213
	v_mul_f32_e32 v214, v90, v214
	v_mul_f32_e32 v215, v91, v215
	v_mul_f32_e32 v216, v92, v216
	v_mul_f32_e32 v217, v93, v217
	v_mul_f32_e32 v218, v94, v218
	v_mul_f32_e32 v219, v95, v219
	v_add_f32_e32 v96, 1.0, v96
	v_add_f32_e32 v97, 1.0, v97
	v_add_f32_e32 v98, 1.0, v98
	v_add_f32_e32 v99, 1.0, v99
	v_add_f32_e32 v100, 1.0, v100
	v_add_f32_e32 v101, 1.0, v101
	v_add_f32_e32 v102, 1.0, v102
	v_add_f32_e32 v103, 1.0, v103
	v_add_f32_e32 v104, 1.0, v104
	v_add_f32_e32 v105, 1.0, v105
	v_add_f32_e32 v106, 1.0, v106
	v_add_f32_e32 v107, 1.0, v107
	v_add_f32_e32 v108, 1.0, v108
	v_add_f32_e32 v109, 1.0, v109
	v_add_f32_e32 v110, 1.0, v110
	v_add_f32_e32 v111, 1.0, v111
	v_fma_f32 v204, v96, v204, v178
	v_fma_f32 v205, v97, v205, v179
	v_fma_f32 v206, v98, v206, v180
	v_fma_f32 v207, v99, v207, v181
	v_fma_f32 v208, v100, v208, v182
	v_fma_f32 v209, v101, v209, v183
	v_fma_f32 v210, v102, v210, v184
	v_fma_f32 v211, v103, v211, v185
	v_fma_f32 v212, v104, v212, v186
	v_fma_f32 v213, v105, v213, v187
	v_fma_f32 v214, v106, v214, v188
	v_fma_f32 v215, v107, v215, v189
	v_fma_f32 v216, v108, v216, v190
	v_fma_f32 v217, v109, v217, v191
	v_fma_f32 v218, v110, v218, v192
	v_fma_f32 v219, v111, v219, v193
	v_cvt_pk_f16_f32 v114, v204, v205
	v_cvt_pk_f16_f32 v115, v206, v207
	v_cvt_pk_f16_f32 v116, v208, v209
	v_cvt_pk_f16_f32 v117, v210, v211
	v_cvt_pk_f16_f32 v118, v212, v213
	v_cvt_pk_f16_f32 v119, v214, v215
	v_cvt_pk_f16_f32 v120, v216, v217
	v_cvt_pk_f16_f32 v121, v218, v219
	global_store_dwordx2 v128, v[114:115], s[24:25]
	global_store_dwordx2 v128, v[116:117], s[24:25] offset:512
	global_store_dwordx2 v128, v[118:119], s[24:25] offset:1024
	global_store_dwordx2 v128, v[120:121], s[24:25] offset:1536
	s_add_i32 s3, s3, s2
	s_cmp_lt_i32 s3, 0x8800
	s_cbranch_scc0 .Lrn2_exit
; DI void rows_norm_mod(const P& p, const float* xlat, const float* xctx, int l, const float* gain, int sh_idx, int sc_idx,
;                       h16* dst, int nrows) {
;     ...
;   for (int row = gw; row < nrows; row += nw) {
;     const float* xr = row < TL ? xlat + (size_t)row * 1024 : xctx + (size_t)(row - TL) * 1024;
;     const int mrow = row < TL ? (row >> 12) : 8;
;     const float* mr = mod + ((size_t)l * 9 + mrow) * 6144;
;     f32x4 v[4];
;     float ss = 0.f;
; #pragma unroll
;     for (int i = 0; i < 4; ++i) {
;       v[i] = *(const f32x4*)(xr + lane * 4 + 256 * i);
;       ss += v[i].x * v[i].x + v[i].y * v[i].y + v[i].z * v[i].z + v[i].w * v[i].w;
;     }
;     ss = wave_sum(ss);
;     const float rstd = rsqrtf(ss * (1.f / 1024.f) + EPS);
; #pragma unroll
;     for (int i = 0; i < 4; ++i) {
;       const int c = lane * 4 + 256 * i;
;       f32x4 g = *(const f32x4*)(gain + c), sc = *(const f32x4*)(mr + sc_idx * 1024 + c), sh = *(const f32x4*)(mr + sh_idx * 1024 + c);
;       h16x4 o;
;       o.x = (h16)(v[i].x * rstd * g.x * (1.f + sc.x) + sh.x);
;       o.y = (h16)(v[i].y * rstd * g.y * (1.f + sc.y) + sh.y);
;       o.z = (h16)(v[i].z * rstd * g.z * (1.f + sc.z) + sh.z);
;       o.w = (h16)(v[i].w * rstd * g.w * (1.f + sc.w) + sh.w);
;       *(h16x4*)(dst + (size_t)row * 1024 + c) = o;
;     }
;   }
	s_lshr_b32 s6, s3, 12
	s_cmp_lt_u32 s3, 0x8000
	s_cselect_b32 s6, s6, 8
	s_mul_i32 s6, s6, 0x6000
	s_add_u32 s22, s4, s6
	s_addc_u32 s23, s5, 0
	s_add_u32 s32, s22, 0x1000
	s_addc_u32 s33, s23, 0
	s_lshl_b32 s6, s3, 11
	s_add_u32 s24, s18, s6
	s_addc_u32 s25, s19, 0
	global_load_dwordx4 v[96:99], v0, s[32:33]
	global_load_dwordx4 v[100:103], v0, s[32:33] offset:1024
	global_load_dwordx4 v[104:107], v0, s[32:33] offset:2048
	global_load_dwordx4 v[108:111], v0, s[32:33] offset:3072
	global_load_dwordx4 v[178:181], v0, s[22:23]
	global_load_dwordx4 v[182:185], v0, s[22:23] offset:1024
	global_load_dwordx4 v[186:189], v0, s[22:23] offset:2048
	global_load_dwordx4 v[190:193], v0, s[22:23] offset:3072
	s_waitcnt vmcnt(8)
	v_mul_f32_e32 v112, v3, v3
	v_mul_f32_e32 v113, v7, v7
	v_mul_f32_e32 v114, v11, v11
	v_mul_f32_e32 v115, v15, v15
	v_fmac_f32_e32 v112, v2, v2
	v_fmac_f32_e32 v113, v6, v6
	v_fmac_f32_e32 v114, v10, v10
	v_fmac_f32_e32 v115, v14, v14
	v_fmac_f32_e32 v112, v4, v4
	v_fmac_f32_e32 v113, v8, v8
	v_fmac_f32_e32 v114, v12, v12
	v_fmac_f32_e32 v115, v16, v16
	v_fmac_f32_e32 v112, v5, v5
	v_fmac_f32_e32 v113, v9, v9
	v_fmac_f32_e32 v114, v13, v13
	v_fmac_f32_e32 v115, v17, v17
	v_add_f32_e32 v112, v112, v113
	v_add_f32_e32 v112, v112, v114
	v_add_f32_e32 v112, v112, v115
	s_nop 1
	v_add_f32_dpp v112, v112, v112 quad_perm:[1,0,3,2] row_mask:0xf bank_mask:0xf bound_ctrl:1
	s_nop 1
	v_add_f32_dpp v112, v112, v112 quad_perm:[2,3,0,1] row_mask:0xf bank_mask:0xf bound_ctrl:1
	s_nop 1
	v_add_f32_dpp v112, v112, v112 row_half_mirror row_mask:0xf bank_mask:0xf bound_ctrl:1
	s_nop 1
	v_add_f32_dpp v112, v112, v112 row_mirror row_mask:0xf bank_mask:0xf bound_ctrl:1
	s_nop 1
	ds_swizzle_b32 v113, v112 offset:swizzle(SWAP,16)
	s_waitcnt lgkmcnt(0)
	v_add_f32_e32 v112, v112, v113
	v_mov_b32_e32 v113, v112
	s_nop 1
	v_permlane32_swap_b32_e32 v112, v113
	v_add_f32_e32 v112, v112, v113
	v_fmamk_f32 v112, v112, 0x3a800000, v224
	v_rsq_f32_e32 v112, v112
	s_waitcnt vmcnt(0)
	v_mul_f32_e32 v2, v2, v112
	v_mul_f32_e32 v3, v3, v112
	v_mul_f32_e32 v4, v4, v112
	v_mul_f32_e32 v5, v5, v112
	v_mul_f32_e32 v6, v6, v112
	v_mul_f32_e32 v7, v7, v112
	v_mul_f32_e32 v8, v8, v112
	v_mul_f32_e32 v9, v9, v112
	v_mul_f32_e32 v10, v10, v112
	v_mul_f32_e32 v11, v11, v112
	v_mul_f32_e32 v12, v12, v112
	v_mul_f32_e32 v13, v13, v112
	v_mul_f32_e32 v14, v14, v112
	v_mul_f32_e32 v15, v15, v112
	v_mul_f32_e32 v16, v16, v112
	v_mul_f32_e32 v17, v17, v112
	v_mul_f32_e32 v2, v80, v2
	v_mul_f32_e32 v3, v81, v3
	v_mul_f32_e32 v4, v82, v4
	v_mul_f32_e32 v5, v83, v5
	v_mul_f32_e32 v6, v84, v6
	v_mul_f32_e32 v7, v85, v7
	v_mul_f32_e32 v8, v86, v8
	v_mul_f32_e32 v9, v87, v9
	v_mul_f32_e32 v10, v88, v10
	v_mul_f32_e32 v11, v89, v11
	v_mul_f32_e32 v12, v90, v12
	v_mul_f32_e32 v13, v91, v13
	v_mul_f32_e32 v14, v92, v14
	v_mul_f32_e32 v15, v93, v15
	v_mul_f32_e32 v16, v94, v16
	v_mul_f32_e32 v17, v95, v17
	v_add_f32_e32 v96, 1.0, v96
	v_add_f32_e32 v97, 1.0, v97
	v_add_f32_e32 v98, 1.0, v98
	v_add_f32_e32 v99, 1.0, v99
	v_add_f32_e32 v100, 1.0, v100
	v_add_f32_e32 v101, 1.0, v101
	v_add_f32_e32 v102, 1.0, v102
	v_add_f32_e32 v103, 1.0, v103
	v_add_f32_e32 v104, 1.0, v104
	v_add_f32_e32 v105, 1.0, v105
	v_add_f32_e32 v106, 1.0, v106
	v_add_f32_e32 v107, 1.0, v107
	v_add_f32_e32 v108, 1.0, v108
	v_add_f32_e32 v109, 1.0, v109
	v_add_f32_e32 v110, 1.0, v110
	v_add_f32_e32 v111, 1.0, v111
	v_fma_f32 v2, v96, v2, v178
	v_fma_f32 v3, v97, v3, v179
	v_fma_f32 v4, v98, v4, v180
	v_fma_f32 v5, v99, v5, v181
	v_fma_f32 v6, v100, v6, v182
	v_fma_f32 v7, v101, v7, v183
	v_fma_f32 v8, v102, v8, v184
	v_fma_f32 v9, v103, v9, v185
	v_fma_f32 v10, v104, v10, v186
	v_fma_f32 v11, v105, v11, v187
	v_fma_f32 v12, v106, v12, v188
	v_fma_f32 v13, v107, v13, v189
	v_fma_f32 v14, v108, v14, v190
	v_fma_f32 v15, v109, v15, v191
	v_fma_f32 v16, v110, v16, v192
	v_fma_f32 v17, v111, v17, v193
	v_cvt_pk_f16_f32 v114, v2, v3
	v_cvt_pk_f16_f32 v115, v4, v5
	v_cvt_pk_f16_f32 v116, v6, v7
	v_cvt_pk_f16_f32 v117, v8, v9
	v_cvt_pk_f16_f32 v118, v10, v11
	v_cvt_pk_f16_f32 v119, v12, v13
	v_cvt_pk_f16_f32 v120, v14, v15
	v_cvt_pk_f16_f32 v121, v16, v17
	global_store_dwordx2 v128, v[114:115], s[24:25]
	global_store_dwordx2 v128, v[116:117], s[24:25] offset:512
	global_store_dwordx2 v128, v[118:119], s[24:25] offset:1024
	global_store_dwordx2 v128, v[120:121], s[24:25] offset:1536
	s_add_i32 s3, s3, s2
	s_cmp_lt_i32 s3, 0x8800
	s_cbranch_scc0 .Lrn2_exit
; DI void rows_norm_mod(const P& p, const float* xlat, const float* xctx, int l, const float* gain, int sh_idx, int sc_idx,
;                       h16* dst, int nrows) {
;     ...
;   for (int row = gw; row < nrows; row += nw) {
;     const float* xr = row < TL ? xlat + (size_t)row * 1024 : xctx + (size_t)(row - TL) * 1024;
;     const int mrow = row < TL ? (row >> 12) : 8;
;     const float* mr = mod + ((size_t)l * 9 + mrow) * 6144;
;     f32x4 v[4];
;     float ss = 0.f;
; #pragma unroll
;     for (int i = 0; i < 4; ++i) {
;       v[i] = *(const f32x4*)(xr + lane * 4 + 256 * i);
;       ss += v[i].x * v[i].x + v[i].y * v[i].y + v[i].z * v[i].z + v[i].w * v[i].w;
;     }
;     ss = wave_sum(ss);
;     const float rstd = rsqrtf(ss * (1.f / 1024.f) + EPS);
; #pragma unroll
;     for (int i = 0; i < 4; ++i) {
;       const int c = lane * 4 + 256 * i;
;       f32x4 g = *(const f32x4*)(gain + c), sc = *(const f32x4*)(mr + sc_idx * 1024 + c), sh = *(const f32x4*)(mr + sh_idx * 1024 + c);
;       h16x4 o;
;       o.x = (h16)(v[i].x * rstd * g.x * (1.f + sc.x) + sh.x);
;       o.y = (h16)(v[i].y * rstd * g.y * (1.f + sc.y) + sh.y);
;       o.z = (h16)(v[i].z * rstd * g.z * (1.f + sc.z) + sh.z);
;       o.w = (h16)(v[i].w * rstd * g.w * (1.f + sc.w) + sh.w);
;       *(h16x4*)(dst + (size_t)row * 1024 + c) = o;
;     }
;   }
	s_lshr_b32 s6, s3, 12
	s_cmp_lt_u32 s3, 0x8000
	s_cselect_b32 s6, s6, 8
	s_mul_i32 s6, s6, 0x6000
	s_add_u32 s22, s4, s6
	s_addc_u32 s23, s5, 0
	s_add_u32 s32, s22, 0x1000
	s_addc_u32 s33, s23, 0
	s_lshl_b32 s6, s3, 11
	s_add_u32 s24, s18, s6
	s_addc_u32 s25, s19, 0
	global_load_dwordx4 v[96:99], v0, s[32:33]
	global_load_dwordx4 v[100:103], v0, s[32:33] offset:1024
	global_load_dwordx4 v[104:107], v0, s[32:33] offset:2048
	global_load_dwordx4 v[108:111], v0, s[32:33] offset:3072
	global_load_dwordx4 v[178:181], v0, s[22:23]
	global_load_dwordx4 v[182:185], v0, s[22:23] offset:1024
	global_load_dwordx4 v[186:189], v0, s[22:23] offset:2048
	global_load_dwordx4 v[190:193], v0, s[22:23] offset:3072
	s_waitcnt vmcnt(8)
	v_mul_f32_e32 v112, v33, v33
	v_mul_f32_e32 v113, v37, v37
	v_mul_f32_e32 v114, v41, v41
	v_mul_f32_e32 v115, v45, v45
	v_fmac_f32_e32 v112, v32, v32
	v_fmac_f32_e32 v113, v36, v36
	v_fmac_f32_e32 v114, v40, v40
	v_fmac_f32_e32 v115, v44, v44
	v_fmac_f32_e32 v112, v34, v34
	v_fmac_f32_e32 v113, v38, v38
	v_fmac_f32_e32 v114, v42, v42
	v_fmac_f32_e32 v115, v46, v46
	v_fmac_f32_e32 v112, v35, v35
	v_fmac_f32_e32 v113, v39, v39
	v_fmac_f32_e32 v114, v43, v43
	v_fmac_f32_e32 v115, v47, v47
	v_add_f32_e32 v112, v112, v113
	v_add_f32_e32 v112, v112, v114
	v_add_f32_e32 v112, v112, v115
	s_nop 1
	v_add_f32_dpp v112, v112, v112 quad_perm:[1,0,3,2] row_mask:0xf bank_mask:0xf bound_ctrl:1
	s_nop 1
	v_add_f32_dpp v112, v112, v112 quad_perm:[2,3,0,1] row_mask:0xf bank_mask:0xf bound_ctrl:1
	s_nop 1
	v_add_f32_dpp v112, v112, v112 row_half_mirror row_mask:0xf bank_mask:0xf bound_ctrl:1
	s_nop 1
	v_add_f32_dpp v112, v112, v112 row_mirror row_mask:0xf bank_mask:0xf bound_ctrl:1
	s_nop 1
	ds_swizzle_b32 v113, v112 offset:swizzle(SWAP,16)
	s_waitcnt lgkmcnt(0)
	v_add_f32_e32 v112, v112, v113
	v_mov_b32_e32 v113, v112
	s_nop 1
	v_permlane32_swap_b32_e32 v112, v113
	v_add_f32_e32 v112, v112, v113
	v_fmamk_f32 v112, v112, 0x3a800000, v224
	v_rsq_f32_e32 v112, v112
	s_waitcnt vmcnt(0)
	v_mul_f32_e32 v32, v32, v112
	v_mul_f32_e32 v33, v33, v112
	v_mul_f32_e32 v34, v34, v112
	v_mul_f32_e32 v35, v35, v112
	v_mul_f32_e32 v36, v36, v112
	v_mul_f32_e32 v37, v37, v112
	v_mul_f32_e32 v38, v38, v112
	v_mul_f32_e32 v39, v39, v112
	v_mul_f32_e32 v40, v40, v112
	v_mul_f32_e32 v41, v41, v112
	v_mul_f32_e32 v42, v42, v112
	v_mul_f32_e32 v43, v43, v112
	v_mul_f32_e32 v44, v44, v112
	v_mul_f32_e32 v45, v45, v112
	v_mul_f32_e32 v46, v46, v112
	v_mul_f32_e32 v47, v47, v112
	v_mul_f32_e32 v32, v80, v32
	v_mul_f32_e32 v33, v81, v33
	v_mul_f32_e32 v34, v82, v34
	v_mul_f32_e32 v35, v83, v35
	v_mul_f32_e32 v36, v84, v36
	v_mul_f32_e32 v37, v85, v37
	v_mul_f32_e32 v38, v86, v38
	v_mul_f32_e32 v39, v87, v39
	v_mul_f32_e32 v40, v88, v40
	v_mul_f32_e32 v41, v89, v41
	v_mul_f32_e32 v42, v90, v42
	v_mul_f32_e32 v43, v91, v43
	v_mul_f32_e32 v44, v92, v44
	v_mul_f32_e32 v45, v93, v45
	v_mul_f32_e32 v46, v94, v46
	v_mul_f32_e32 v47, v95, v47
	v_add_f32_e32 v96, 1.0, v96
	v_add_f32_e32 v97, 1.0, v97
	v_add_f32_e32 v98, 1.0, v98
	v_add_f32_e32 v99, 1.0, v99
	v_add_f32_e32 v100, 1.0, v100
	v_add_f32_e32 v101, 1.0, v101
	v_add_f32_e32 v102, 1.0, v102
	v_add_f32_e32 v103, 1.0, v103
	v_add_f32_e32 v104, 1.0, v104
	v_add_f32_e32 v105, 1.0, v105
	v_add_f32_e32 v106, 1.0, v106
	v_add_f32_e32 v107, 1.0, v107
	v_add_f32_e32 v108, 1.0, v108
	v_add_f32_e32 v109, 1.0, v109
	v_add_f32_e32 v110, 1.0, v110
	v_add_f32_e32 v111, 1.0, v111
	v_fma_f32 v32, v96, v32, v178
	v_fma_f32 v33, v97, v33, v179
	v_fma_f32 v34, v98, v34, v180
	v_fma_f32 v35, v99, v35, v181
	v_fma_f32 v36, v100, v36, v182
	v_fma_f32 v37, v101, v37, v183
	v_fma_f32 v38, v102, v38, v184
	v_fma_f32 v39, v103, v39, v185
	v_fma_f32 v40, v104, v40, v186
	v_fma_f32 v41, v105, v41, v187
	v_fma_f32 v42, v106, v42, v188
	v_fma_f32 v43, v107, v43, v189
	v_fma_f32 v44, v108, v44, v190
	v_fma_f32 v45, v109, v45, v191
	v_fma_f32 v46, v110, v46, v192
	v_fma_f32 v47, v111, v47, v193
	v_cvt_pk_f16_f32 v114, v32, v33
	v_cvt_pk_f16_f32 v115, v34, v35
	v_cvt_pk_f16_f32 v116, v36, v37
	v_cvt_pk_f16_f32 v117, v38, v39
	v_cvt_pk_f16_f32 v118, v40, v41
	v_cvt_pk_f16_f32 v119, v42, v43
	v_cvt_pk_f16_f32 v120, v44, v45
	v_cvt_pk_f16_f32 v121, v46, v47
	global_store_dwordx2 v128, v[114:115], s[24:25]
	global_store_dwordx2 v128, v[116:117], s[24:25] offset:512
	global_store_dwordx2 v128, v[118:119], s[24:25] offset:1024
	global_store_dwordx2 v128, v[120:121], s[24:25] offset:1536
	s_add_i32 s3, s3, s2
	s_branch .Lrn2_exit
